# v15: v14 + ds_swizzle SWAP,16 butterflies in GEMM epilogues replaced by v_permlane16_swap (no LDS round trip)
# baseline (speedup 1.0000x reference)
; __device__ __forceinline__ unsigned cvtpk(float lo, float hi) { f32x2 v = {lo, hi}; bf16x2_t b = __builtin_convertvector(v, bf16x2_t); return __builtin_bit_cast(unsigned, b); }
; __device__ __forceinline__ float wave_sum(float v) { v = bfly_add<1>(v); v = bfly_add<2>(v); v = bfly_add<4>(v); v = bfly_add<8>(v); v = bfly_add<16>(v); v = bfly_add<32>(v); return v; }
; __device__ __forceinline__ void rms_row_to_bf16(const float* xrow, const float* g, bf16_t* orow, int lane) {
;     const f32x4* xr = (const f32x4*)xrow + lane; const f32x4* gr = (const f32x4*)g + lane;
;     f32x4 v[4]; float s = 0.f;
; #pragma unroll
;     for (int j = 0; j < 4; ++j) { v[j] = xr[64 * j]; s += (v[j][0] * v[j][0] + v[j][1] * v[j][1]) + (v[j][2] * v[j][2] + v[j][3] * v[j][3]); }
;     const float rstd = rsqrtf(wave_sum(s) * (1.f / DM) + EPS);
;     u32x2* o8 = (u32x2*)orow + lane;
; #pragma unroll
;     for (int j = 0; j < 4; ++j) { const f32x4 gg = g ? gr[64 * j] : (f32x4){1.f, 1.f, 1.f, 1.f}; u32x2 w; w.x = cvtpk(v[j][0] * rstd * gg[0], v[j][1] * rstd * gg[1]); w.y = cvtpk(v[j][2] * rstd * gg[2], v[j][3] * rstd * gg[3]); o8[64 * j] = w; }
.LBB0_84:
	s_ashr_i32 s9, s12, 31
	s_lshr_b32 s9, s9, 20
	s_add_i32 s9, s12, s9
	s_ashr_i32 s20, s9, 12
	s_and_b32 s9, s9, 0xfffff000
	s_sub_i32 s16, s12, s9
	s_add_i32 s18, s16, 0xfffff800
	s_ashr_i32 s17, s9, 31
	s_sub_u32 s9, s12, s9
	s_subb_u32 s17, s13, s17
	s_cmpk_lt_i32 s16, 0x800
	s_cselect_b32 s16, s9, s18
	s_cselect_b32 s9, 16, 24
	s_cselect_b32 s17, s17, 0
	s_add_u32 s18, s2, s9
	s_addc_u32 s19, s3, 0
	s_load_dwordx2 s[18:19], s[18:19], 0x0
	s_lshl_b64 s[16:17], s[16:17], 12
	s_waitcnt lgkmcnt(0)
	s_add_u32 s16, s18, s16
	s_addc_u32 s17, s19, s17
	global_load_dwordx4 v[14:17], v1, s[16:17]
	global_load_dwordx4 v[10:13], v1, s[16:17] offset:1024
	global_load_dwordx4 v[6:9], v1, s[16:17] offset:2048
	global_load_dwordx4 v[2:5], v1, s[16:17] offset:3072
	s_lshl_b32 s16, s20, 10
	s_ashr_i32 s17, s16, 31
	s_and_b64 vcc, exec, s[4:5]
	s_waitcnt vmcnt(3)
	v_mul_f32_e32 v18, v15, v15
	v_mul_f32_e32 v19, v17, v17
	s_waitcnt vmcnt(2)
	v_mul_f32_e32 v20, v11, v11
	v_mul_f32_e32 v21, v13, v13
	s_waitcnt vmcnt(1)
	v_mul_f32_e32 v22, v7, v7
	v_mul_f32_e32 v23, v9, v9
	v_fmac_f32_e32 v18, v14, v14
	v_fmac_f32_e32 v19, v16, v16
	v_fmac_f32_e32 v20, v10, v10
	v_fmac_f32_e32 v21, v12, v12
	s_waitcnt vmcnt(0)
	v_mul_f32_e32 v28, v3, v3
	v_mul_f32_e32 v29, v5, v5
	v_fmac_f32_e32 v22, v6, v6
	v_fmac_f32_e32 v23, v8, v8
	v_add_f32_e32 v18, v18, v19
	v_add_f32_e32 v19, v20, v21
	v_fmac_f32_e32 v28, v2, v2
	v_fmac_f32_e32 v29, v4, v4
	v_add_f32_e32 v20, v22, v23
	v_add_f32_e32 v18, v18, v19
	v_add_f32_e32 v21, v28, v29
	v_add_f32_e32 v18, v18, v20
	v_add_f32_e32 v18, v18, v21
	ds_swizzle_b32 v19, v18 offset:swizzle(SWAP,1)
	v_mov_b32_e32 v20, 1.0
	v_mov_b32_e32 v21, 1.0
	v_mov_b32_e32 v22, 1.0
	v_lshl_add_u64 v[28:29], s[16:17], 2, v[24:25]
	s_waitcnt lgkmcnt(0)
	v_add_f32_e32 v18, v18, v19
	ds_swizzle_b32 v19, v18 offset:swizzle(SWAP,2)
	s_waitcnt lgkmcnt(0)
	v_add_f32_e32 v18, v18, v19
	ds_swizzle_b32 v19, v18 offset:swizzle(SWAP,4)
	s_waitcnt lgkmcnt(0)
	v_add_f32_e32 v19, v18, v19
	ds_swizzle_b32 v23, v19 offset:swizzle(SWAP,8)
	v_mov_b32_e32 v18, 1.0
	s_waitcnt lgkmcnt(0)
	v_add_f32_e32 v19, v19, v23
	v_mov_b32_e32 v23, v19
	s_nop 1
	v_permlane16_swap_b32_e32 v19, v23
	s_waitcnt lgkmcnt(0)
	v_add_f32_e32 v19, v19, v23
	v_mov_b32_e32 v32, v19
	s_nop 1
	v_permlane32_swap_b32_e32 v19, v32
	v_mov_b32_e32 v23, 1.0
	s_cbranch_vccnz .LBB0_86
	global_load_dwordx4 v[20:23], v[28:29], off

; __device__ __forceinline__ unsigned cvtpk(float lo, float hi) { f32x2 v = {lo, hi}; bf16x2_t b = __builtin_convertvector(v, bf16x2_t); return __builtin_bit_cast(unsigned, b); }
;     __device__ __forceinline__ void operator()(const f32x4 (&acc)[2][2][4][2], const Unit& u, int wr, int wc, int fr, int fq) const {
;     ...
;                 const int row = u.pm * BM + ai * HALF + wr * 64 + m * 16 + fr;
;                 float rs = 1.f;
;                 if (PS) { const f32x4 p = *(const f32x4*)(PS + (size_t)row * 16 + 4 * fq); float s = (p[0] + p[1]) + (p[2] + p[3]); s = bfly_add<16>(s); s = bfly_add<32>(s); rs = rsqrtf(s * (1.f / DM) + EPS); }
;                 f32x4 v[2][2]; float ss = 0.f;
; #pragma unroll
;                 for (int bj = 0; bj < 2; ++bj)
; #pragma unroll
;                     for (int n = 0; n < 2; ++n) { v[bj][n] = acc[ai][bj][m][n] * rs; const f32x4 x = v[bj][n]; ss += (x[0] * x[0] + x[1] * x[1]) + (x[2] * x[2] + x[3] * x[3]); }
;                 if (nrm) { ss = bfly_add<16>(ss); ss = bfly_add<32>(ss); const float r2 = rsqrtf(ss * (1.f / 64.f) + EPS);
; #pragma unroll
;                     for (int bj = 0; bj < 2; ++bj)
; #pragma unroll
;                         for (int n = 0; n < 2; ++n) v[bj][n] = v[bj][n] * r2 * gv[bj][n]; }
;                 bf16_t* rowp = Z + (size_t)row * ldz + u.pn * BM + 64 * wc + 8 * fq;
; #pragma unroll
;                 for (int bj = 0; bj < 2; ++bj) { u32x4 w; w.x = cvtpk(v[bj][0][0], v[bj][0][1]); w.y = cvtpk(v[bj][0][2], v[bj][0][3]); w.z = cvtpk(v[bj][1][0], v[bj][1][1]); w.w = cvtpk(v[bj][1][2], v[bj][1][3]);
;                     *(u32x4*)(rowp + 32 * bj) = w; }
.LBB0_160:
	v_lshl_add_u32 v168, s40, 8, v170
	v_ashrrev_i32_e32 v169, 31, v168
	v_lshlrev_b64 v[178:179], 6, v[168:169]
	v_lshl_add_u64 v[178:179], v[162:163], 0, v[178:179]
	global_load_dwordx4 v[178:181], v[178:179], off
	s_and_b64 vcc, exec, s[4:5]
	s_waitcnt vmcnt(0)
	v_mov_b32_e32 v186, v179
	v_mov_b32_e32 v187, v180
	v_mov_b32_e32 v179, v181
	v_pk_add_f32 v[178:179], v[186:187], v[178:179]
	s_nop 0
	v_add_f32_e32 v169, v178, v179
	v_mov_b32_e32 v174, v169
	s_nop 1
	v_permlane16_swap_b32_e32 v169, v174
	s_waitcnt lgkmcnt(0)
	v_add_f32_e32 v169, v169, v174
	v_mov_b32_e32 v174, v169
	s_nop 1
	v_permlane32_swap_b32_e32 v169, v174
	v_add_f32_e32 v169, v169, v174
	v_fmamk_f32 v169, v169, 0x3a800000, v173
	v_mul_f32_e32 v174, 0x4b800000, v169
	v_cmp_gt_f32_e64 s[8:9], s62, v169
	s_nop 1
	v_cndmask_b32_e64 v169, v169, v174, s[8:9]
	v_rsq_f32_e32 v169, v169
	s_nop 0
	v_mul_f32_e32 v174, 0x45800000, v169
	v_cndmask_b32_e64 v174, v169, v174, s[8:9]
	v_pk_mul_f32 v[142:143], v[142:143], v[174:175] op_sel_hi:[1,0]
	v_pk_mul_f32 v[140:141], v[140:141], v[174:175] op_sel_hi:[1,0]
	v_pk_mul_f32 v[138:139], v[138:139], v[174:175] op_sel_hi:[1,0]
	v_pk_mul_f32 v[136:137], v[136:137], v[174:175] op_sel_hi:[1,0]
	v_pk_mul_f32 v[134:135], v[134:135], v[174:175] op_sel_hi:[1,0]
	v_pk_mul_f32 v[132:133], v[132:133], v[174:175] op_sel_hi:[1,0]
	v_pk_mul_f32 v[130:131], v[130:131], v[174:175] op_sel_hi:[1,0]
	v_pk_mul_f32 v[128:129], v[128:129], v[174:175] op_sel_hi:[1,0]
	s_cbranch_vccnz .LBB0_162
	v_pk_mul_f32 v[178:179], v[142:143], v[142:143]
	v_pk_mul_f32 v[180:181], v[140:141], v[140:141]
	v_mul_f32_e32 v174, v132, v132
	v_pk_mov_b32 v[186:187], v[180:181], v[178:179] op_sel:[1,0]
	v_mov_b32_e32 v181, v179
	v_pk_add_f32 v[178:179], v[186:187], v[180:181]
	v_pk_mul_f32 v[180:181], v[138:139], v[138:139]
	v_pk_mul_f32 v[186:187], v[136:137], v[136:137]
	v_pk_add_f32 v[178:179], v[178:179], v[178:179] op_sel_hi:[0,1]
	v_pk_mov_b32 v[188:189], v[186:187], v[180:181] op_sel:[1,0]
	v_mov_b32_e32 v187, v181
	v_pk_add_f32 v[180:181], v[188:189], v[186:187]
	v_pk_fma_f32 v[186:187], v[132:133], v[132:133], v[174:175] op_sel_hi:[1,1,0]
	v_mul_f32_e32 v174, v134, v134
	v_pk_add_f32 v[180:181], v[180:181], v[180:181] op_sel_hi:[0,1]
	v_pk_fma_f32 v[188:189], v[134:135], v[134:135], v[174:175] op_sel_hi:[1,1,0]
	v_mul_f32_e32 v186, v128, v128
	v_mul_f32_e32 v188, v129, v129
	v_mul_f32_e32 v178, v130, v130
	v_mul_f32_e32 v180, v131, v131
	v_pk_add_f32 v[186:187], v[186:187], v[188:189]
	v_pk_add_f32 v[178:179], v[178:179], v[180:181]
	s_nop 0
	v_pk_add_f32 v[178:179], v[186:187], v[178:179]
	s_nop 0
	v_add_f32_e32 v169, v178, v179
	v_mov_b32_e32 v174, v169
	s_nop 1
	v_permlane16_swap_b32_e32 v169, v174
	s_waitcnt lgkmcnt(0)
	v_add_f32_e32 v169, v169, v174
	v_mov_b32_e32 v174, v169
	s_nop 1
	v_permlane32_swap_b32_e32 v169, v174
	v_add_f32_e32 v169, v169, v174
	v_fmamk_f32 v169, v169, 0x3c800000, v173
	v_mul_f32_e32 v174, 0x4b800000, v169
	v_cmp_gt_f32_e32 vcc, s62, v169
	s_nop 1
	v_cndmask_b32_e32 v169, v169, v174, vcc
	v_rsq_f32_e32 v169, v169
	s_nop 0
	v_mul_f32_e32 v174, 0x45800000, v169
	v_cndmask_b32_e32 v174, v169, v174, vcc
	v_pk_mul_f32 v[140:141], v[140:141], v[174:175] op_sel_hi:[1,0]
	v_pk_mul_f32 v[142:143], v[142:143], v[174:175] op_sel_hi:[1,0]
	v_pk_mul_f32 v[136:137], v[136:137], v[174:175] op_sel_hi:[1,0]
	v_pk_mul_f32 v[138:139], v[138:139], v[174:175] op_sel_hi:[1,0]
	v_pk_mul_f32 v[132:133], v[132:133], v[174:175] op_sel_hi:[1,0]
	v_pk_mul_f32 v[134:135], v[134:135], v[174:175] op_sel_hi:[1,0]
	v_pk_mul_f32 v[128:129], v[128:129], v[174:175] op_sel_hi:[1,0]
	v_pk_mul_f32 v[130:131], v[130:131], v[174:175] op_sel_hi:[1,0]
	v_pk_mul_f32 v[142:143], v[70:71], v[142:143]
	v_pk_mul_f32 v[140:141], v[68:69], v[140:141]
	v_pk_mul_f32 v[138:139], v[66:67], v[138:139]
	v_pk_mul_f32 v[136:137], v[64:65], v[136:137]
	v_pk_mul_f32 v[134:135], v[78:79], v[134:135]
	v_pk_mul_f32 v[132:133], v[76:77], v[132:133]
	v_pk_mul_f32 v[130:131], v[74:75], v[130:131]
	v_pk_mul_f32 v[128:129], v[72:73], v[128:129]
.LBB0_162:
	s_lshl_b32 s26, s39, 8
	v_mov_b64_e32 v[178:179], s[14:15]
	s_ashr_i32 s27, s26, 31
	v_mad_i64_i32 v[178:179], s[8:9], v168, s63, v[178:179]
	v_lshl_add_u64 v[178:179], s[26:27], 1, v[178:179]
	v_lshl_add_u64 v[178:179], v[178:179], 0, s[84:85]
	v_lshl_add_u64 v[178:179], v[178:179], 0, v[144:145]
	v_cvt_pk_bf16_f32 v140, v140, v141
	v_cvt_pk_bf16_f32 v141, v142, v143
	v_cvt_pk_bf16_f32 v142, v136, v137
	v_cvt_pk_bf16_f32 v143, v138, v139
	v_cvt_pk_bf16_f32 v132, v132, v133
	v_cvt_pk_bf16_f32 v133, v134, v135
	v_cvt_pk_bf16_f32 v134, v128, v129
	v_cvt_pk_bf16_f32 v135, v130, v131
	global_store_dwordx4 v[178:179], v[140:143], off
	global_store_dwordx4 v[178:179], v[132:135], off offset:64
	v_or_b32_e32 v128, 16, v168
	v_ashrrev_i32_e32 v129, 31, v128
	v_lshlrev_b64 v[130:131], 6, v[128:129]
	v_lshl_add_u64 v[130:131], v[162:163], 0, v[130:131]
	global_load_dwordx4 v[130:133], v[130:131], off
	s_and_b64 vcc, exec, s[4:5]
	s_waitcnt vmcnt(0)
	v_mov_b32_e32 v134, v131
	v_mov_b32_e32 v135, v132
	v_mov_b32_e32 v131, v133
	v_pk_add_f32 v[130:131], v[134:135], v[130:131]
	s_nop 0
	v_add_f32_e32 v129, v130, v131
	v_mov_b32_e32 v130, v129
	s_nop 1
	v_permlane16_swap_b32_e32 v129, v130
	s_waitcnt lgkmcnt(0)
	v_add_f32_e32 v129, v129, v130
	v_mov_b32_e32 v130, v129
	s_nop 1
	v_permlane32_swap_b32_e32 v129, v130
	v_add_f32_e32 v129, v129, v130
	v_fmamk_f32 v129, v129, 0x3a800000, v173
	v_mul_f32_e32 v130, 0x4b800000, v129
	v_cmp_gt_f32_e64 s[8:9], s62, v129
	s_nop 1
	v_cndmask_b32_e64 v129, v129, v130, s[8:9]
	v_rsq_f32_e32 v129, v129
	s_nop 0
	v_mul_f32_e32 v130, 0x45800000, v129
	v_cndmask_b32_e64 v130, v129, v130, s[8:9]
	v_pk_mul_f32 v[126:127], v[126:127], v[130:131] op_sel_hi:[1,0]
	v_pk_mul_f32 v[124:125], v[124:125], v[130:131] op_sel_hi:[1,0]
	v_pk_mul_f32 v[122:123], v[122:123], v[130:131] op_sel_hi:[1,0]
	v_pk_mul_f32 v[120:121], v[120:121], v[130:131] op_sel_hi:[1,0]
	v_pk_mul_f32 v[118:119], v[118:119], v[130:131] op_sel_hi:[1,0]
	v_pk_mul_f32 v[116:117], v[116:117], v[130:131] op_sel_hi:[1,0]
	v_pk_mul_f32 v[114:115], v[114:115], v[130:131] op_sel_hi:[1,0]
	v_pk_mul_f32 v[112:113], v[112:113], v[130:131] op_sel_hi:[1,0]
	s_cbranch_vccnz .LBB0_164
; __device__ __forceinline__ unsigned cvtpk(float lo, float hi) { f32x2 v = {lo, hi}; bf16x2_t b = __builtin_convertvector(v, bf16x2_t); return __builtin_bit_cast(unsigned, b); }
;     __device__ __forceinline__ void operator()(const f32x4 (&acc)[2][2][4][2], const Unit& u, int wr, int wc, int fr, int fq) const {
;     ...
;                 const int row = u.pm * BM + ai * HALF + wr * 64 + m * 16 + fr;
;                 float rs = 1.f;
;                 if (PS) { const f32x4 p = *(const f32x4*)(PS + (size_t)row * 16 + 4 * fq); float s = (p[0] + p[1]) + (p[2] + p[3]); s = bfly_add<16>(s); s = bfly_add<32>(s); rs = rsqrtf(s * (1.f / DM) + EPS); }
;                 f32x4 v[2][2]; float ss = 0.f;
; #pragma unroll
;                 for (int bj = 0; bj < 2; ++bj)
; #pragma unroll
;                     for (int n = 0; n < 2; ++n) { v[bj][n] = acc[ai][bj][m][n] * rs; const f32x4 x = v[bj][n]; ss += (x[0] * x[0] + x[1] * x[1]) + (x[2] * x[2] + x[3] * x[3]); }
;                 if (nrm) { ss = bfly_add<16>(ss); ss = bfly_add<32>(ss); const float r2 = rsqrtf(ss * (1.f / 64.f) + EPS);
; #pragma unroll
;                     for (int bj = 0; bj < 2; ++bj)
; #pragma unroll
;                         for (int n = 0; n < 2; ++n) v[bj][n] = v[bj][n] * r2 * gv[bj][n]; }
;                 bf16_t* rowp = Z + (size_t)row * ldz + u.pn * BM + 64 * wc + 8 * fq;
; #pragma unroll
;                 for (int bj = 0; bj < 2; ++bj) { u32x4 w; w.x = cvtpk(v[bj][0][0], v[bj][0][1]); w.y = cvtpk(v[bj][0][2], v[bj][0][3]); w.z = cvtpk(v[bj][1][0], v[bj][1][1]); w.w = cvtpk(v[bj][1][2], v[bj][1][3]);
;                     *(u32x4*)(rowp + 32 * bj) = w; }
	v_pk_mul_f32 v[130:131], v[126:127], v[126:127]
	v_pk_mul_f32 v[132:133], v[124:125], v[124:125]
	s_nop 0
	v_pk_mov_b32 v[134:135], v[132:133], v[130:131] op_sel:[1,0]
	v_mov_b32_e32 v133, v131
	v_pk_add_f32 v[130:131], v[134:135], v[132:133]
	v_pk_mul_f32 v[132:133], v[122:123], v[122:123]
	v_pk_add_f32 v[130:131], v[130:131], v[130:131] op_sel_hi:[0,1]
	v_pk_mul_f32 v[134:135], v[120:121], v[120:121]
	v_mul_f32_e32 v130, v116, v116
	v_pk_mov_b32 v[136:137], v[134:135], v[132:133] op_sel:[1,0]
	v_mov_b32_e32 v135, v133
	v_pk_add_f32 v[132:133], v[136:137], v[134:135]
	v_pk_fma_f32 v[134:135], v[116:117], v[116:117], v[130:131] op_sel_hi:[1,1,0]
	v_mul_f32_e32 v130, v118, v118
	v_pk_add_f32 v[132:133], v[132:133], v[132:133] op_sel_hi:[0,1]
	v_pk_fma_f32 v[136:137], v[118:119], v[118:119], v[130:131] op_sel_hi:[1,1,0]
	v_mul_f32_e32 v134, v112, v112
	v_mul_f32_e32 v136, v113, v113
	v_mul_f32_e32 v130, v114, v114
	v_mul_f32_e32 v132, v115, v115
	v_pk_add_f32 v[134:135], v[134:135], v[136:137]
	v_pk_add_f32 v[130:131], v[130:131], v[132:133]
	s_nop 0
	v_pk_add_f32 v[130:131], v[134:135], v[130:131]
	s_nop 0
	v_add_f32_e32 v129, v130, v131
	v_mov_b32_e32 v130, v129
	s_nop 1
	v_permlane16_swap_b32_e32 v129, v130
	s_waitcnt lgkmcnt(0)
	v_add_f32_e32 v129, v129, v130
	v_mov_b32_e32 v130, v129
	s_nop 1
	v_permlane32_swap_b32_e32 v129, v130
	v_add_f32_e32 v129, v129, v130
	v_fmamk_f32 v129, v129, 0x3c800000, v173
	v_mul_f32_e32 v130, 0x4b800000, v129
	v_cmp_gt_f32_e32 vcc, s62, v129
	s_nop 1
	v_cndmask_b32_e32 v129, v129, v130, vcc
	v_rsq_f32_e32 v129, v129
	s_nop 0
	v_mul_f32_e32 v130, 0x45800000, v129
	v_cndmask_b32_e32 v130, v129, v130, vcc
	v_pk_mul_f32 v[124:125], v[124:125], v[130:131] op_sel_hi:[1,0]
	v_pk_mul_f32 v[126:127], v[126:127], v[130:131] op_sel_hi:[1,0]
	v_pk_mul_f32 v[120:121], v[120:121], v[130:131] op_sel_hi:[1,0]
	v_pk_mul_f32 v[122:123], v[122:123], v[130:131] op_sel_hi:[1,0]
	v_pk_mul_f32 v[116:117], v[116:117], v[130:131] op_sel_hi:[1,0]
	v_pk_mul_f32 v[118:119], v[118:119], v[130:131] op_sel_hi:[1,0]
	v_pk_mul_f32 v[112:113], v[112:113], v[130:131] op_sel_hi:[1,0]
	v_pk_mul_f32 v[114:115], v[114:115], v[130:131] op_sel_hi:[1,0]
	v_pk_mul_f32 v[126:127], v[70:71], v[126:127]
	v_pk_mul_f32 v[124:125], v[68:69], v[124:125]
	v_pk_mul_f32 v[122:123], v[66:67], v[122:123]
	v_pk_mul_f32 v[120:121], v[64:65], v[120:121]
	v_pk_mul_f32 v[118:119], v[78:79], v[118:119]
	v_pk_mul_f32 v[116:117], v[76:77], v[116:117]
	v_pk_mul_f32 v[114:115], v[74:75], v[114:115]
	v_pk_mul_f32 v[112:113], v[72:73], v[112:113]
.LBB0_164:
	v_mov_b64_e32 v[130:131], s[14:15]
	v_mad_i64_i32 v[128:129], s[8:9], v128, s63, v[130:131]
	v_lshl_add_u64 v[128:129], s[26:27], 1, v[128:129]
	v_lshl_add_u64 v[128:129], v[128:129], 0, s[84:85]
	v_lshl_add_u64 v[128:129], v[128:129], 0, v[144:145]
	v_cvt_pk_bf16_f32 v124, v124, v125
	v_cvt_pk_bf16_f32 v125, v126, v127
	v_cvt_pk_bf16_f32 v126, v120, v121
	v_cvt_pk_bf16_f32 v127, v122, v123
	v_cvt_pk_bf16_f32 v116, v116, v117
	v_cvt_pk_bf16_f32 v117, v118, v119
	v_cvt_pk_bf16_f32 v118, v112, v113
	v_cvt_pk_bf16_f32 v119, v114, v115
	global_store_dwordx4 v[128:129], v[124:127], off
	global_store_dwordx4 v[128:129], v[116:119], off offset:64
	v_or_b32_e32 v112, 32, v168
	v_ashrrev_i32_e32 v113, 31, v112
	v_lshlrev_b64 v[114:115], 6, v[112:113]
	v_lshl_add_u64 v[114:115], v[162:163], 0, v[114:115]
	global_load_dwordx4 v[114:117], v[114:115], off
	s_and_b64 vcc, exec, s[4:5]
	s_waitcnt vmcnt(0)
	v_mov_b32_e32 v118, v115
	v_mov_b32_e32 v119, v116
	v_mov_b32_e32 v115, v117
	v_pk_add_f32 v[114:115], v[118:119], v[114:115]
	s_nop 0
	v_add_f32_e32 v113, v114, v115
	v_mov_b32_e32 v114, v113
	s_nop 1
	v_permlane16_swap_b32_e32 v113, v114
	s_waitcnt lgkmcnt(0)
	v_add_f32_e32 v113, v113, v114
	v_mov_b32_e32 v114, v113
	s_nop 1
	v_permlane32_swap_b32_e32 v113, v114
	v_add_f32_e32 v113, v113, v114
	v_fmamk_f32 v113, v113, 0x3a800000, v173
	v_mul_f32_e32 v114, 0x4b800000, v113
	v_cmp_gt_f32_e64 s[8:9], s62, v113
	s_nop 1
	v_cndmask_b32_e64 v113, v113, v114, s[8:9]
	v_rsq_f32_e32 v113, v113
	s_nop 0
	v_mul_f32_e32 v114, 0x45800000, v113
	v_cndmask_b32_e64 v114, v113, v114, s[8:9]
	v_pk_mul_f32 v[110:111], v[110:111], v[114:115] op_sel_hi:[1,0]
	v_pk_mul_f32 v[108:109], v[108:109], v[114:115] op_sel_hi:[1,0]
	v_pk_mul_f32 v[106:107], v[106:107], v[114:115] op_sel_hi:[1,0]
	v_pk_mul_f32 v[104:105], v[104:105], v[114:115] op_sel_hi:[1,0]
	v_pk_mul_f32 v[102:103], v[102:103], v[114:115] op_sel_hi:[1,0]
	v_pk_mul_f32 v[100:101], v[100:101], v[114:115] op_sel_hi:[1,0]
	v_pk_mul_f32 v[98:99], v[98:99], v[114:115] op_sel_hi:[1,0]
	v_pk_mul_f32 v[96:97], v[96:97], v[114:115] op_sel_hi:[1,0]
	s_cbranch_vccnz .LBB0_166
; __device__ __forceinline__ unsigned cvtpk(float lo, float hi) { f32x2 v = {lo, hi}; bf16x2_t b = __builtin_convertvector(v, bf16x2_t); return __builtin_bit_cast(unsigned, b); }
;     __device__ __forceinline__ void operator()(const f32x4 (&acc)[2][2][4][2], const Unit& u, int wr, int wc, int fr, int fq) const {
;     ...
;                 const int row = u.pm * BM + ai * HALF + wr * 64 + m * 16 + fr;
;                 float rs = 1.f;
;                 if (PS) { const f32x4 p = *(const f32x4*)(PS + (size_t)row * 16 + 4 * fq); float s = (p[0] + p[1]) + (p[2] + p[3]); s = bfly_add<16>(s); s = bfly_add<32>(s); rs = rsqrtf(s * (1.f / DM) + EPS); }
;                 f32x4 v[2][2]; float ss = 0.f;
; #pragma unroll
;                 for (int bj = 0; bj < 2; ++bj)
; #pragma unroll
;                     for (int n = 0; n < 2; ++n) { v[bj][n] = acc[ai][bj][m][n] * rs; const f32x4 x = v[bj][n]; ss += (x[0] * x[0] + x[1] * x[1]) + (x[2] * x[2] + x[3] * x[3]); }
;                 if (nrm) { ss = bfly_add<16>(ss); ss = bfly_add<32>(ss); const float r2 = rsqrtf(ss * (1.f / 64.f) + EPS);
; #pragma unroll
;                     for (int bj = 0; bj < 2; ++bj)
; #pragma unroll
;                         for (int n = 0; n < 2; ++n) v[bj][n] = v[bj][n] * r2 * gv[bj][n]; }
;                 bf16_t* rowp = Z + (size_t)row * ldz + u.pn * BM + 64 * wc + 8 * fq;
; #pragma unroll
;                 for (int bj = 0; bj < 2; ++bj) { u32x4 w; w.x = cvtpk(v[bj][0][0], v[bj][0][1]); w.y = cvtpk(v[bj][0][2], v[bj][0][3]); w.z = cvtpk(v[bj][1][0], v[bj][1][1]); w.w = cvtpk(v[bj][1][2], v[bj][1][3]);
;                     *(u32x4*)(rowp + 32 * bj) = w; }
	v_pk_mul_f32 v[114:115], v[110:111], v[110:111]
	v_pk_mul_f32 v[116:117], v[108:109], v[108:109]
	s_nop 0
	v_pk_mov_b32 v[118:119], v[116:117], v[114:115] op_sel:[1,0]
	v_mov_b32_e32 v117, v115
	v_pk_add_f32 v[114:115], v[118:119], v[116:117]
	v_pk_mul_f32 v[116:117], v[106:107], v[106:107]
	v_pk_add_f32 v[114:115], v[114:115], v[114:115] op_sel_hi:[0,1]
	v_pk_mul_f32 v[118:119], v[104:105], v[104:105]
	v_mul_f32_e32 v114, v100, v100
	v_pk_mov_b32 v[120:121], v[118:119], v[116:117] op_sel:[1,0]
	v_mov_b32_e32 v119, v117
	v_pk_add_f32 v[116:117], v[120:121], v[118:119]
	v_pk_fma_f32 v[118:119], v[100:101], v[100:101], v[114:115] op_sel_hi:[1,1,0]
	v_mul_f32_e32 v114, v102, v102
	v_pk_add_f32 v[116:117], v[116:117], v[116:117] op_sel_hi:[0,1]
	v_pk_fma_f32 v[120:121], v[102:103], v[102:103], v[114:115] op_sel_hi:[1,1,0]
	v_mul_f32_e32 v118, v96, v96
	v_mul_f32_e32 v120, v97, v97
	v_mul_f32_e32 v114, v98, v98
	v_mul_f32_e32 v116, v99, v99
	v_pk_add_f32 v[118:119], v[118:119], v[120:121]
	v_pk_add_f32 v[114:115], v[114:115], v[116:117]
	s_nop 0
	v_pk_add_f32 v[114:115], v[118:119], v[114:115]
	s_nop 0
	v_add_f32_e32 v113, v114, v115
	v_mov_b32_e32 v114, v113
	s_nop 1
	v_permlane16_swap_b32_e32 v113, v114
	s_waitcnt lgkmcnt(0)
	v_add_f32_e32 v113, v113, v114
	v_mov_b32_e32 v114, v113
	s_nop 1
	v_permlane32_swap_b32_e32 v113, v114
	v_add_f32_e32 v113, v113, v114
	v_fmamk_f32 v113, v113, 0x3c800000, v173
	v_mul_f32_e32 v114, 0x4b800000, v113
	v_cmp_gt_f32_e32 vcc, s62, v113
	s_nop 1
	v_cndmask_b32_e32 v113, v113, v114, vcc
	v_rsq_f32_e32 v113, v113
	s_nop 0
	v_mul_f32_e32 v114, 0x45800000, v113
	v_cndmask_b32_e32 v114, v113, v114, vcc
	v_pk_mul_f32 v[108:109], v[108:109], v[114:115] op_sel_hi:[1,0]
	v_pk_mul_f32 v[110:111], v[110:111], v[114:115] op_sel_hi:[1,0]
	v_pk_mul_f32 v[104:105], v[104:105], v[114:115] op_sel_hi:[1,0]
	v_pk_mul_f32 v[106:107], v[106:107], v[114:115] op_sel_hi:[1,0]
	v_pk_mul_f32 v[100:101], v[100:101], v[114:115] op_sel_hi:[1,0]
	v_pk_mul_f32 v[102:103], v[102:103], v[114:115] op_sel_hi:[1,0]
	v_pk_mul_f32 v[96:97], v[96:97], v[114:115] op_sel_hi:[1,0]
	v_pk_mul_f32 v[98:99], v[98:99], v[114:115] op_sel_hi:[1,0]
	v_pk_mul_f32 v[110:111], v[70:71], v[110:111]
	v_pk_mul_f32 v[108:109], v[68:69], v[108:109]
	v_pk_mul_f32 v[106:107], v[66:67], v[106:107]
	v_pk_mul_f32 v[104:105], v[64:65], v[104:105]
	v_pk_mul_f32 v[102:103], v[78:79], v[102:103]
	v_pk_mul_f32 v[100:101], v[76:77], v[100:101]
	v_pk_mul_f32 v[98:99], v[74:75], v[98:99]
	v_pk_mul_f32 v[96:97], v[72:73], v[96:97]
.LBB0_166:
	v_mov_b64_e32 v[114:115], s[14:15]
	v_mad_i64_i32 v[112:113], s[8:9], v112, s63, v[114:115]
	v_lshl_add_u64 v[112:113], s[26:27], 1, v[112:113]
	v_lshl_add_u64 v[112:113], v[112:113], 0, s[84:85]
	v_lshl_add_u64 v[112:113], v[112:113], 0, v[144:145]
	v_cvt_pk_bf16_f32 v108, v108, v109
	v_cvt_pk_bf16_f32 v109, v110, v111
	v_cvt_pk_bf16_f32 v110, v104, v105
	v_cvt_pk_bf16_f32 v111, v106, v107
	v_cvt_pk_bf16_f32 v100, v100, v101
	v_cvt_pk_bf16_f32 v101, v102, v103
	v_cvt_pk_bf16_f32 v102, v96, v97
	v_cvt_pk_bf16_f32 v103, v98, v99
	global_store_dwordx4 v[112:113], v[108:111], off
	global_store_dwordx4 v[112:113], v[100:103], off offset:64
	v_or_b32_e32 v96, 48, v168
	v_ashrrev_i32_e32 v97, 31, v96
	v_lshlrev_b64 v[98:99], 6, v[96:97]
	v_lshl_add_u64 v[98:99], v[162:163], 0, v[98:99]
	global_load_dwordx4 v[98:101], v[98:99], off
	s_and_b64 vcc, exec, s[4:5]
	s_waitcnt vmcnt(0)
	v_mov_b32_e32 v102, v99
	v_mov_b32_e32 v103, v100
	v_mov_b32_e32 v99, v101
	v_pk_add_f32 v[98:99], v[102:103], v[98:99]
	s_nop 0
	v_add_f32_e32 v97, v98, v99
	v_mov_b32_e32 v98, v97
	s_nop 1
	v_permlane16_swap_b32_e32 v97, v98
	s_waitcnt lgkmcnt(0)
	v_add_f32_e32 v97, v97, v98
	v_mov_b32_e32 v98, v97
	s_nop 1
	v_permlane32_swap_b32_e32 v97, v98
	v_add_f32_e32 v97, v97, v98
	v_fmamk_f32 v97, v97, 0x3a800000, v173
	v_mul_f32_e32 v98, 0x4b800000, v97
	v_cmp_gt_f32_e64 s[8:9], s62, v97
	s_nop 1
	v_cndmask_b32_e64 v97, v97, v98, s[8:9]
	v_rsq_f32_e32 v97, v97
	s_nop 0
	v_mul_f32_e32 v98, 0x45800000, v97
	v_cndmask_b32_e64 v98, v97, v98, s[8:9]
	v_pk_mul_f32 v[94:95], v[94:95], v[98:99] op_sel_hi:[1,0]
	v_pk_mul_f32 v[92:93], v[92:93], v[98:99] op_sel_hi:[1,0]
	v_pk_mul_f32 v[90:91], v[90:91], v[98:99] op_sel_hi:[1,0]
	v_pk_mul_f32 v[88:89], v[88:89], v[98:99] op_sel_hi:[1,0]
	v_pk_mul_f32 v[86:87], v[86:87], v[98:99] op_sel_hi:[1,0]
	v_pk_mul_f32 v[84:85], v[84:85], v[98:99] op_sel_hi:[1,0]
	v_pk_mul_f32 v[82:83], v[82:83], v[98:99] op_sel_hi:[1,0]
	v_pk_mul_f32 v[80:81], v[80:81], v[98:99] op_sel_hi:[1,0]
	s_cbranch_vccnz .LBB0_168
	v_pk_mul_f32 v[98:99], v[94:95], v[94:95]
	v_pk_mul_f32 v[100:101], v[92:93], v[92:93]
	s_nop 0
	v_pk_mov_b32 v[102:103], v[100:101], v[98:99] op_sel:[1,0]
	v_mov_b32_e32 v101, v99
	v_pk_add_f32 v[98:99], v[102:103], v[100:101]
	v_pk_mul_f32 v[100:101], v[90:91], v[90:91]
	v_pk_add_f32 v[98:99], v[98:99], v[98:99] op_sel_hi:[0,1]
	v_pk_mul_f32 v[102:103], v[88:89], v[88:89]
	v_mul_f32_e32 v98, v84, v84
	v_pk_mov_b32 v[104:105], v[102:103], v[100:101] op_sel:[1,0]
	v_mov_b32_e32 v103, v101
	v_pk_add_f32 v[100:101], v[104:105], v[102:103]
	v_pk_fma_f32 v[102:103], v[84:85], v[84:85], v[98:99] op_sel_hi:[1,1,0]
	v_mul_f32_e32 v98, v86, v86
	v_pk_add_f32 v[100:101], v[100:101], v[100:101] op_sel_hi:[0,1]
	v_pk_fma_f32 v[104:105], v[86:87], v[86:87], v[98:99] op_sel_hi:[1,1,0]
	v_mul_f32_e32 v102, v80, v80
	v_mul_f32_e32 v104, v81, v81
	v_mul_f32_e32 v98, v82, v82
	v_mul_f32_e32 v100, v83, v83
	v_pk_add_f32 v[102:103], v[102:103], v[104:105]
	v_pk_add_f32 v[98:99], v[98:99], v[100:101]
	s_nop 0
	v_pk_add_f32 v[98:99], v[102:103], v[98:99]
	s_nop 0
	v_add_f32_e32 v97, v98, v99
	v_mov_b32_e32 v98, v97
	s_nop 1
	v_permlane16_swap_b32_e32 v97, v98
	s_waitcnt lgkmcnt(0)
	v_add_f32_e32 v97, v97, v98
	v_mov_b32_e32 v98, v97
	s_nop 1
	v_permlane32_swap_b32_e32 v97, v98
	v_add_f32_e32 v97, v97, v98
	v_fmamk_f32 v97, v97, 0x3c800000, v173
	v_mul_f32_e32 v98, 0x4b800000, v97
	v_cmp_gt_f32_e32 vcc, s62, v97
	s_nop 1
	v_cndmask_b32_e32 v97, v97, v98, vcc
	v_rsq_f32_e32 v97, v97
	s_nop 0
	v_mul_f32_e32 v98, 0x45800000, v97
	v_cndmask_b32_e32 v98, v97, v98, vcc
	v_pk_mul_f32 v[92:93], v[92:93], v[98:99] op_sel_hi:[1,0]
	v_pk_mul_f32 v[94:95], v[94:95], v[98:99] op_sel_hi:[1,0]
	v_pk_mul_f32 v[88:89], v[88:89], v[98:99] op_sel_hi:[1,0]
	v_pk_mul_f32 v[90:91], v[90:91], v[98:99] op_sel_hi:[1,0]
	v_pk_mul_f32 v[84:85], v[84:85], v[98:99] op_sel_hi:[1,0]
	v_pk_mul_f32 v[86:87], v[86:87], v[98:99] op_sel_hi:[1,0]
	v_pk_mul_f32 v[80:81], v[80:81], v[98:99] op_sel_hi:[1,0]
	v_pk_mul_f32 v[82:83], v[82:83], v[98:99] op_sel_hi:[1,0]
	v_pk_mul_f32 v[94:95], v[70:71], v[94:95]
	v_pk_mul_f32 v[92:93], v[68:69], v[92:93]
	v_pk_mul_f32 v[90:91], v[66:67], v[90:91]
	v_pk_mul_f32 v[88:89], v[64:65], v[88:89]
	v_pk_mul_f32 v[86:87], v[78:79], v[86:87]
	v_pk_mul_f32 v[84:85], v[76:77], v[84:85]
	v_pk_mul_f32 v[82:83], v[74:75], v[82:83]
	v_pk_mul_f32 v[80:81], v[72:73], v[80:81]
; __device__ __forceinline__ unsigned cvtpk(float lo, float hi) { f32x2 v = {lo, hi}; bf16x2_t b = __builtin_convertvector(v, bf16x2_t); return __builtin_bit_cast(unsigned, b); }
;     __device__ __forceinline__ void operator()(const f32x4 (&acc)[2][2][4][2], const Unit& u, int wr, int wc, int fr, int fq) const {
;     ...
;                 const int row = u.pm * BM + ai * HALF + wr * 64 + m * 16 + fr;
;                 float rs = 1.f;
;                 if (PS) { const f32x4 p = *(const f32x4*)(PS + (size_t)row * 16 + 4 * fq); float s = (p[0] + p[1]) + (p[2] + p[3]); s = bfly_add<16>(s); s = bfly_add<32>(s); rs = rsqrtf(s * (1.f / DM) + EPS); }
;                 f32x4 v[2][2]; float ss = 0.f;
; #pragma unroll
;                 for (int bj = 0; bj < 2; ++bj)
; #pragma unroll
;                     for (int n = 0; n < 2; ++n) { v[bj][n] = acc[ai][bj][m][n] * rs; const f32x4 x = v[bj][n]; ss += (x[0] * x[0] + x[1] * x[1]) + (x[2] * x[2] + x[3] * x[3]); }
;                 if (nrm) { ss = bfly_add<16>(ss); ss = bfly_add<32>(ss); const float r2 = rsqrtf(ss * (1.f / 64.f) + EPS);
; #pragma unroll
;                     for (int bj = 0; bj < 2; ++bj)
; #pragma unroll
;                         for (int n = 0; n < 2; ++n) v[bj][n] = v[bj][n] * r2 * gv[bj][n]; }
;                 bf16_t* rowp = Z + (size_t)row * ldz + u.pn * BM + 64 * wc + 8 * fq;
; #pragma unroll
;                 for (int bj = 0; bj < 2; ++bj) { u32x4 w; w.x = cvtpk(v[bj][0][0], v[bj][0][1]); w.y = cvtpk(v[bj][0][2], v[bj][0][3]); w.z = cvtpk(v[bj][1][0], v[bj][1][1]); w.w = cvtpk(v[bj][1][2], v[bj][1][3]);
;                     *(u32x4*)(rowp + 32 * bj) = w; }
.LBB0_168:
	v_mov_b64_e32 v[98:99], s[14:15]
	v_mad_i64_i32 v[96:97], s[8:9], v96, s63, v[98:99]
	v_lshl_add_u64 v[96:97], s[26:27], 1, v[96:97]
	v_lshl_add_u64 v[96:97], v[96:97], 0, s[84:85]
	v_lshl_add_u64 v[96:97], v[96:97], 0, v[144:145]
	v_cvt_pk_bf16_f32 v92, v92, v93
	v_cvt_pk_bf16_f32 v93, v94, v95
	v_cvt_pk_bf16_f32 v94, v88, v89
	v_cvt_pk_bf16_f32 v95, v90, v91
	v_cvt_pk_bf16_f32 v84, v84, v85
	v_cvt_pk_bf16_f32 v85, v86, v87
	v_cvt_pk_bf16_f32 v86, v80, v81
	v_cvt_pk_bf16_f32 v87, v82, v83
	global_store_dwordx4 v[96:97], v[92:95], off
	global_store_dwordx4 v[96:97], v[84:87], off offset:64
	v_add_u32_e32 v80, 0x80, v168
	v_ashrrev_i32_e32 v81, 31, v80
	v_lshlrev_b64 v[82:83], 6, v[80:81]
	v_lshl_add_u64 v[82:83], v[162:163], 0, v[82:83]
	global_load_dwordx4 v[82:85], v[82:83], off
	s_and_b64 vcc, exec, s[4:5]
	s_waitcnt vmcnt(0)
	v_mov_b32_e32 v86, v83
	v_mov_b32_e32 v87, v84
	v_mov_b32_e32 v83, v85
	v_pk_add_f32 v[82:83], v[86:87], v[82:83]
	s_nop 0
	v_add_f32_e32 v81, v82, v83
	v_mov_b32_e32 v82, v81
	s_nop 1
	v_permlane16_swap_b32_e32 v81, v82
	s_waitcnt lgkmcnt(0)
	v_add_f32_e32 v81, v81, v82
	v_mov_b32_e32 v82, v81
	s_nop 1
	v_permlane32_swap_b32_e32 v81, v82
	v_add_f32_e32 v81, v81, v82
	v_fmamk_f32 v81, v81, 0x3a800000, v173
	v_mul_f32_e32 v82, 0x4b800000, v81
	v_cmp_gt_f32_e64 s[8:9], s62, v81
	s_nop 1
	v_cndmask_b32_e64 v81, v81, v82, s[8:9]
	v_rsq_f32_e32 v81, v81
	s_nop 0
	v_mul_f32_e32 v82, 0x45800000, v81
	v_cndmask_b32_e64 v82, v81, v82, s[8:9]
	v_pk_mul_f32 v[62:63], v[62:63], v[82:83] op_sel_hi:[1,0]
	v_pk_mul_f32 v[60:61], v[60:61], v[82:83] op_sel_hi:[1,0]
	v_pk_mul_f32 v[58:59], v[58:59], v[82:83] op_sel_hi:[1,0]
	v_pk_mul_f32 v[56:57], v[56:57], v[82:83] op_sel_hi:[1,0]
	v_pk_mul_f32 v[54:55], v[54:55], v[82:83] op_sel_hi:[1,0]
	v_pk_mul_f32 v[52:53], v[52:53], v[82:83] op_sel_hi:[1,0]
	v_pk_mul_f32 v[50:51], v[50:51], v[82:83] op_sel_hi:[1,0]
	v_pk_mul_f32 v[48:49], v[48:49], v[82:83] op_sel_hi:[1,0]
	s_cbranch_vccnz .LBB0_170
	v_pk_mul_f32 v[82:83], v[62:63], v[62:63]
	v_pk_mul_f32 v[84:85], v[60:61], v[60:61]
	s_nop 0
	v_pk_mov_b32 v[86:87], v[84:85], v[82:83] op_sel:[1,0]
	v_mov_b32_e32 v85, v83
	v_pk_add_f32 v[82:83], v[86:87], v[84:85]
	v_pk_mul_f32 v[84:85], v[58:59], v[58:59]
	v_pk_add_f32 v[82:83], v[82:83], v[82:83] op_sel_hi:[0,1]
	v_pk_mul_f32 v[86:87], v[56:57], v[56:57]
	v_mul_f32_e32 v82, v52, v52
	v_pk_mov_b32 v[88:89], v[86:87], v[84:85] op_sel:[1,0]
	v_mov_b32_e32 v87, v85
	v_pk_add_f32 v[84:85], v[88:89], v[86:87]
	v_pk_fma_f32 v[86:87], v[52:53], v[52:53], v[82:83] op_sel_hi:[1,1,0]
	v_mul_f32_e32 v82, v54, v54
	v_pk_add_f32 v[84:85], v[84:85], v[84:85] op_sel_hi:[0,1]
	v_pk_fma_f32 v[88:89], v[54:55], v[54:55], v[82:83] op_sel_hi:[1,1,0]
	v_mul_f32_e32 v86, v48, v48
	v_mul_f32_e32 v88, v49, v49
	v_mul_f32_e32 v82, v50, v50
	v_mul_f32_e32 v84, v51, v51
	v_pk_add_f32 v[86:87], v[86:87], v[88:89]
	v_pk_add_f32 v[82:83], v[82:83], v[84:85]
	s_nop 0
	v_pk_add_f32 v[82:83], v[86:87], v[82:83]
	s_nop 0
	v_add_f32_e32 v81, v82, v83
	v_mov_b32_e32 v82, v81
	s_nop 1
	v_permlane16_swap_b32_e32 v81, v82
	s_waitcnt lgkmcnt(0)
	v_add_f32_e32 v81, v81, v82
	v_mov_b32_e32 v82, v81
	s_nop 1
	v_permlane32_swap_b32_e32 v81, v82
	v_add_f32_e32 v81, v81, v82
	v_fmamk_f32 v81, v81, 0x3c800000, v173
	v_mul_f32_e32 v82, 0x4b800000, v81
	v_cmp_gt_f32_e32 vcc, s62, v81
	s_nop 1
	v_cndmask_b32_e32 v81, v81, v82, vcc
	v_rsq_f32_e32 v81, v81
	s_nop 0
	v_mul_f32_e32 v82, 0x45800000, v81
	v_cndmask_b32_e32 v82, v81, v82, vcc
	v_pk_mul_f32 v[60:61], v[60:61], v[82:83] op_sel_hi:[1,0]
	v_pk_mul_f32 v[62:63], v[62:63], v[82:83] op_sel_hi:[1,0]
	v_pk_mul_f32 v[56:57], v[56:57], v[82:83] op_sel_hi:[1,0]
	v_pk_mul_f32 v[58:59], v[58:59], v[82:83] op_sel_hi:[1,0]
	v_pk_mul_f32 v[52:53], v[52:53], v[82:83] op_sel_hi:[1,0]
	v_pk_mul_f32 v[54:55], v[54:55], v[82:83] op_sel_hi:[1,0]
	v_pk_mul_f32 v[48:49], v[48:49], v[82:83] op_sel_hi:[1,0]
	v_pk_mul_f32 v[50:51], v[50:51], v[82:83] op_sel_hi:[1,0]
	v_pk_mul_f32 v[62:63], v[70:71], v[62:63]
	v_pk_mul_f32 v[60:61], v[68:69], v[60:61]
	v_pk_mul_f32 v[58:59], v[66:67], v[58:59]
	v_pk_mul_f32 v[56:57], v[64:65], v[56:57]
	v_pk_mul_f32 v[54:55], v[78:79], v[54:55]
	v_pk_mul_f32 v[52:53], v[76:77], v[52:53]
	v_pk_mul_f32 v[50:51], v[74:75], v[50:51]
	v_pk_mul_f32 v[48:49], v[72:73], v[48:49]
; __device__ __forceinline__ unsigned cvtpk(float lo, float hi) { f32x2 v = {lo, hi}; bf16x2_t b = __builtin_convertvector(v, bf16x2_t); return __builtin_bit_cast(unsigned, b); }
;     __device__ __forceinline__ void operator()(const f32x4 (&acc)[2][2][4][2], const Unit& u, int wr, int wc, int fr, int fq) const {
;     ...
;                 const int row = u.pm * BM + ai * HALF + wr * 64 + m * 16 + fr;
;                 float rs = 1.f;
;                 if (PS) { const f32x4 p = *(const f32x4*)(PS + (size_t)row * 16 + 4 * fq); float s = (p[0] + p[1]) + (p[2] + p[3]); s = bfly_add<16>(s); s = bfly_add<32>(s); rs = rsqrtf(s * (1.f / DM) + EPS); }
;                 f32x4 v[2][2]; float ss = 0.f;
; #pragma unroll
;                 for (int bj = 0; bj < 2; ++bj)
; #pragma unroll
;                     for (int n = 0; n < 2; ++n) { v[bj][n] = acc[ai][bj][m][n] * rs; const f32x4 x = v[bj][n]; ss += (x[0] * x[0] + x[1] * x[1]) + (x[2] * x[2] + x[3] * x[3]); }
;                 if (nrm) { ss = bfly_add<16>(ss); ss = bfly_add<32>(ss); const float r2 = rsqrtf(ss * (1.f / 64.f) + EPS);
; #pragma unroll
;                     for (int bj = 0; bj < 2; ++bj)
; #pragma unroll
;                         for (int n = 0; n < 2; ++n) v[bj][n] = v[bj][n] * r2 * gv[bj][n]; }
;                 bf16_t* rowp = Z + (size_t)row * ldz + u.pn * BM + 64 * wc + 8 * fq;
; #pragma unroll
;                 for (int bj = 0; bj < 2; ++bj) { u32x4 w; w.x = cvtpk(v[bj][0][0], v[bj][0][1]); w.y = cvtpk(v[bj][0][2], v[bj][0][3]); w.z = cvtpk(v[bj][1][0], v[bj][1][1]); w.w = cvtpk(v[bj][1][2], v[bj][1][3]);
;                     *(u32x4*)(rowp + 32 * bj) = w; }
.LBB0_170:
	v_mov_b64_e32 v[82:83], s[14:15]
	v_mad_i64_i32 v[80:81], s[8:9], v80, s63, v[82:83]
	v_lshl_add_u64 v[80:81], s[26:27], 1, v[80:81]
	v_lshl_add_u64 v[80:81], v[80:81], 0, s[84:85]
	v_lshl_add_u64 v[80:81], v[80:81], 0, v[144:145]
	v_cvt_pk_bf16_f32 v60, v60, v61
	v_cvt_pk_bf16_f32 v61, v62, v63
	v_cvt_pk_bf16_f32 v62, v56, v57
	v_cvt_pk_bf16_f32 v63, v58, v59
	v_cvt_pk_bf16_f32 v52, v52, v53
	v_cvt_pk_bf16_f32 v53, v54, v55
	v_cvt_pk_bf16_f32 v54, v48, v49
	v_cvt_pk_bf16_f32 v55, v50, v51
	global_store_dwordx4 v[80:81], v[60:63], off
	global_store_dwordx4 v[80:81], v[52:55], off offset:64
	v_add_u32_e32 v48, 0x90, v168
	v_ashrrev_i32_e32 v49, 31, v48
	v_lshlrev_b64 v[50:51], 6, v[48:49]
	v_lshl_add_u64 v[50:51], v[162:163], 0, v[50:51]
	global_load_dwordx4 v[50:53], v[50:51], off
	s_and_b64 vcc, exec, s[4:5]
	s_waitcnt vmcnt(0)
	v_mov_b32_e32 v54, v51
	v_mov_b32_e32 v55, v52
	v_mov_b32_e32 v51, v53
	v_pk_add_f32 v[50:51], v[54:55], v[50:51]
	s_nop 0
	v_add_f32_e32 v49, v50, v51
	v_mov_b32_e32 v50, v49
	s_nop 1
	v_permlane16_swap_b32_e32 v49, v50
	s_waitcnt lgkmcnt(0)
	v_add_f32_e32 v49, v49, v50
	v_mov_b32_e32 v50, v49
	s_nop 1
	v_permlane32_swap_b32_e32 v49, v50
	v_add_f32_e32 v49, v49, v50
	v_fmamk_f32 v49, v49, 0x3a800000, v173
	v_mul_f32_e32 v50, 0x4b800000, v49
	v_cmp_gt_f32_e64 s[8:9], s62, v49
	s_nop 1
	v_cndmask_b32_e64 v49, v49, v50, s[8:9]
	v_rsq_f32_e32 v49, v49
	s_nop 0
	v_mul_f32_e32 v50, 0x45800000, v49
	v_cndmask_b32_e64 v50, v49, v50, s[8:9]
	v_pk_mul_f32 v[46:47], v[46:47], v[50:51] op_sel_hi:[1,0]
	v_pk_mul_f32 v[44:45], v[44:45], v[50:51] op_sel_hi:[1,0]
	v_pk_mul_f32 v[42:43], v[42:43], v[50:51] op_sel_hi:[1,0]
	v_pk_mul_f32 v[40:41], v[40:41], v[50:51] op_sel_hi:[1,0]
	v_pk_mul_f32 v[38:39], v[38:39], v[50:51] op_sel_hi:[1,0]
	v_pk_mul_f32 v[36:37], v[36:37], v[50:51] op_sel_hi:[1,0]
	v_pk_mul_f32 v[34:35], v[34:35], v[50:51] op_sel_hi:[1,0]
	v_pk_mul_f32 v[32:33], v[32:33], v[50:51] op_sel_hi:[1,0]
	s_cbranch_vccnz .LBB0_172
	v_pk_mul_f32 v[50:51], v[46:47], v[46:47]
	v_pk_mul_f32 v[52:53], v[44:45], v[44:45]
	s_nop 0
	v_pk_mov_b32 v[54:55], v[52:53], v[50:51] op_sel:[1,0]
	v_mov_b32_e32 v53, v51
	v_pk_add_f32 v[50:51], v[54:55], v[52:53]
	v_pk_mul_f32 v[52:53], v[42:43], v[42:43]
	v_pk_add_f32 v[50:51], v[50:51], v[50:51] op_sel_hi:[0,1]
	v_pk_mul_f32 v[54:55], v[40:41], v[40:41]
	v_mul_f32_e32 v50, v36, v36
	v_pk_mov_b32 v[56:57], v[54:55], v[52:53] op_sel:[1,0]
	v_mov_b32_e32 v55, v53
	v_pk_add_f32 v[52:53], v[56:57], v[54:55]
	v_pk_fma_f32 v[54:55], v[36:37], v[36:37], v[50:51] op_sel_hi:[1,1,0]
	v_mul_f32_e32 v50, v38, v38
	v_pk_add_f32 v[52:53], v[52:53], v[52:53] op_sel_hi:[0,1]
	v_pk_fma_f32 v[56:57], v[38:39], v[38:39], v[50:51] op_sel_hi:[1,1,0]
	v_mul_f32_e32 v54, v32, v32
	v_mul_f32_e32 v56, v33, v33
	v_mul_f32_e32 v50, v34, v34
	v_mul_f32_e32 v52, v35, v35
	v_pk_add_f32 v[54:55], v[54:55], v[56:57]
	v_pk_add_f32 v[50:51], v[50:51], v[52:53]
	s_nop 0
	v_pk_add_f32 v[50:51], v[54:55], v[50:51]
	s_nop 0
	v_add_f32_e32 v49, v50, v51
	v_mov_b32_e32 v50, v49
	s_nop 1
	v_permlane16_swap_b32_e32 v49, v50
	s_waitcnt lgkmcnt(0)
	v_add_f32_e32 v49, v49, v50
	v_mov_b32_e32 v50, v49
	s_nop 1
	v_permlane32_swap_b32_e32 v49, v50
	v_add_f32_e32 v49, v49, v50
	v_fmamk_f32 v49, v49, 0x3c800000, v173
	v_mul_f32_e32 v50, 0x4b800000, v49
	v_cmp_gt_f32_e32 vcc, s62, v49
	s_nop 1
	v_cndmask_b32_e32 v49, v49, v50, vcc
	v_rsq_f32_e32 v49, v49
	s_nop 0
	v_mul_f32_e32 v50, 0x45800000, v49
	v_cndmask_b32_e32 v50, v49, v50, vcc
	v_pk_mul_f32 v[44:45], v[44:45], v[50:51] op_sel_hi:[1,0]
	v_pk_mul_f32 v[46:47], v[46:47], v[50:51] op_sel_hi:[1,0]
	v_pk_mul_f32 v[40:41], v[40:41], v[50:51] op_sel_hi:[1,0]
	v_pk_mul_f32 v[42:43], v[42:43], v[50:51] op_sel_hi:[1,0]
	v_pk_mul_f32 v[36:37], v[36:37], v[50:51] op_sel_hi:[1,0]
	v_pk_mul_f32 v[38:39], v[38:39], v[50:51] op_sel_hi:[1,0]
	v_pk_mul_f32 v[32:33], v[32:33], v[50:51] op_sel_hi:[1,0]
	v_pk_mul_f32 v[34:35], v[34:35], v[50:51] op_sel_hi:[1,0]
	v_pk_mul_f32 v[46:47], v[70:71], v[46:47]
	v_pk_mul_f32 v[44:45], v[68:69], v[44:45]
	v_pk_mul_f32 v[42:43], v[66:67], v[42:43]
	v_pk_mul_f32 v[40:41], v[64:65], v[40:41]
	v_pk_mul_f32 v[38:39], v[78:79], v[38:39]
	v_pk_mul_f32 v[36:37], v[76:77], v[36:37]
	v_pk_mul_f32 v[34:35], v[74:75], v[34:35]
	v_pk_mul_f32 v[32:33], v[72:73], v[32:33]
; __device__ __forceinline__ unsigned cvtpk(float lo, float hi) { f32x2 v = {lo, hi}; bf16x2_t b = __builtin_convertvector(v, bf16x2_t); return __builtin_bit_cast(unsigned, b); }
;     __device__ __forceinline__ void operator()(const f32x4 (&acc)[2][2][4][2], const Unit& u, int wr, int wc, int fr, int fq) const {
;     ...
;                 const int row = u.pm * BM + ai * HALF + wr * 64 + m * 16 + fr;
;                 float rs = 1.f;
;                 if (PS) { const f32x4 p = *(const f32x4*)(PS + (size_t)row * 16 + 4 * fq); float s = (p[0] + p[1]) + (p[2] + p[3]); s = bfly_add<16>(s); s = bfly_add<32>(s); rs = rsqrtf(s * (1.f / DM) + EPS); }
;                 f32x4 v[2][2]; float ss = 0.f;
; #pragma unroll
;                 for (int bj = 0; bj < 2; ++bj)
; #pragma unroll
;                     for (int n = 0; n < 2; ++n) { v[bj][n] = acc[ai][bj][m][n] * rs; const f32x4 x = v[bj][n]; ss += (x[0] * x[0] + x[1] * x[1]) + (x[2] * x[2] + x[3] * x[3]); }
;                 if (nrm) { ss = bfly_add<16>(ss); ss = bfly_add<32>(ss); const float r2 = rsqrtf(ss * (1.f / 64.f) + EPS);
; #pragma unroll
;                     for (int bj = 0; bj < 2; ++bj)
; #pragma unroll
;                         for (int n = 0; n < 2; ++n) v[bj][n] = v[bj][n] * r2 * gv[bj][n]; }
;                 bf16_t* rowp = Z + (size_t)row * ldz + u.pn * BM + 64 * wc + 8 * fq;
; #pragma unroll
;                 for (int bj = 0; bj < 2; ++bj) { u32x4 w; w.x = cvtpk(v[bj][0][0], v[bj][0][1]); w.y = cvtpk(v[bj][0][2], v[bj][0][3]); w.z = cvtpk(v[bj][1][0], v[bj][1][1]); w.w = cvtpk(v[bj][1][2], v[bj][1][3]);
;                     *(u32x4*)(rowp + 32 * bj) = w; }
.LBB0_172:
	v_mov_b64_e32 v[50:51], s[14:15]
	v_mad_i64_i32 v[48:49], s[8:9], v48, s63, v[50:51]
	v_lshl_add_u64 v[48:49], s[26:27], 1, v[48:49]
	v_lshl_add_u64 v[48:49], v[48:49], 0, s[84:85]
	v_lshl_add_u64 v[48:49], v[48:49], 0, v[144:145]
	v_cvt_pk_bf16_f32 v44, v44, v45
	v_cvt_pk_bf16_f32 v45, v46, v47
	v_cvt_pk_bf16_f32 v46, v40, v41
	v_cvt_pk_bf16_f32 v47, v42, v43
	v_cvt_pk_bf16_f32 v36, v36, v37
	v_cvt_pk_bf16_f32 v37, v38, v39
	v_cvt_pk_bf16_f32 v38, v32, v33
	v_cvt_pk_bf16_f32 v39, v34, v35
	global_store_dwordx4 v[48:49], v[44:47], off
	global_store_dwordx4 v[48:49], v[36:39], off offset:64
	v_add_u32_e32 v32, 0xa0, v168
	v_ashrrev_i32_e32 v33, 31, v32
	v_lshlrev_b64 v[34:35], 6, v[32:33]
	v_lshl_add_u64 v[34:35], v[162:163], 0, v[34:35]
	global_load_dwordx4 v[34:37], v[34:35], off
	s_and_b64 vcc, exec, s[4:5]
	s_waitcnt vmcnt(0)
	v_mov_b32_e32 v38, v35
	v_mov_b32_e32 v39, v36
	v_mov_b32_e32 v35, v37
	v_pk_add_f32 v[34:35], v[38:39], v[34:35]
	s_nop 0
	v_add_f32_e32 v33, v34, v35
	v_mov_b32_e32 v34, v33
	s_nop 1
	v_permlane16_swap_b32_e32 v33, v34
	s_waitcnt lgkmcnt(0)
	v_add_f32_e32 v33, v33, v34
	v_mov_b32_e32 v34, v33
	s_nop 1
	v_permlane32_swap_b32_e32 v33, v34
	v_add_f32_e32 v33, v33, v34
	v_fmamk_f32 v33, v33, 0x3a800000, v173
	v_mul_f32_e32 v34, 0x4b800000, v33
	v_cmp_gt_f32_e64 s[8:9], s62, v33
	s_nop 1
	v_cndmask_b32_e64 v33, v33, v34, s[8:9]
	v_rsq_f32_e32 v33, v33
	s_nop 0
	v_mul_f32_e32 v34, 0x45800000, v33
	v_cndmask_b32_e64 v34, v33, v34, s[8:9]
	v_pk_mul_f32 v[30:31], v[30:31], v[34:35] op_sel_hi:[1,0]
	v_pk_mul_f32 v[28:29], v[28:29], v[34:35] op_sel_hi:[1,0]
	v_pk_mul_f32 v[26:27], v[26:27], v[34:35] op_sel_hi:[1,0]
	v_pk_mul_f32 v[24:25], v[24:25], v[34:35] op_sel_hi:[1,0]
	v_pk_mul_f32 v[22:23], v[22:23], v[34:35] op_sel_hi:[1,0]
	v_pk_mul_f32 v[20:21], v[20:21], v[34:35] op_sel_hi:[1,0]
	v_pk_mul_f32 v[18:19], v[18:19], v[34:35] op_sel_hi:[1,0]
	v_pk_mul_f32 v[16:17], v[16:17], v[34:35] op_sel_hi:[1,0]
	s_cbranch_vccnz .LBB0_174
	v_pk_mul_f32 v[34:35], v[30:31], v[30:31]
	v_pk_mul_f32 v[36:37], v[28:29], v[28:29]
	s_nop 0
	v_pk_mov_b32 v[38:39], v[36:37], v[34:35] op_sel:[1,0]
	v_mov_b32_e32 v37, v35
	v_pk_add_f32 v[34:35], v[38:39], v[36:37]
	v_pk_mul_f32 v[36:37], v[26:27], v[26:27]
	v_pk_add_f32 v[34:35], v[34:35], v[34:35] op_sel_hi:[0,1]
	v_pk_mul_f32 v[38:39], v[24:25], v[24:25]
	v_mul_f32_e32 v34, v20, v20
	v_pk_mov_b32 v[40:41], v[38:39], v[36:37] op_sel:[1,0]
	v_mov_b32_e32 v39, v37
	v_pk_add_f32 v[36:37], v[40:41], v[38:39]
	v_pk_fma_f32 v[38:39], v[20:21], v[20:21], v[34:35] op_sel_hi:[1,1,0]
	v_mul_f32_e32 v34, v22, v22
	v_pk_add_f32 v[36:37], v[36:37], v[36:37] op_sel_hi:[0,1]
	v_pk_fma_f32 v[40:41], v[22:23], v[22:23], v[34:35] op_sel_hi:[1,1,0]
	v_mul_f32_e32 v38, v16, v16
	v_mul_f32_e32 v40, v17, v17
	v_mul_f32_e32 v34, v18, v18
	v_mul_f32_e32 v36, v19, v19
	v_pk_add_f32 v[38:39], v[38:39], v[40:41]
	v_pk_add_f32 v[34:35], v[34:35], v[36:37]
	s_nop 0
	v_pk_add_f32 v[34:35], v[38:39], v[34:35]
	s_nop 0
	v_add_f32_e32 v33, v34, v35
	v_mov_b32_e32 v34, v33
	s_nop 1
	v_permlane16_swap_b32_e32 v33, v34
	s_waitcnt lgkmcnt(0)
	v_add_f32_e32 v33, v33, v34
	v_mov_b32_e32 v34, v33
	s_nop 1
	v_permlane32_swap_b32_e32 v33, v34
	v_add_f32_e32 v33, v33, v34
	v_fmamk_f32 v33, v33, 0x3c800000, v173
	v_mul_f32_e32 v34, 0x4b800000, v33
	v_cmp_gt_f32_e32 vcc, s62, v33
	s_nop 1
	v_cndmask_b32_e32 v33, v33, v34, vcc
	v_rsq_f32_e32 v33, v33
	s_nop 0
	v_mul_f32_e32 v34, 0x45800000, v33
	v_cndmask_b32_e32 v34, v33, v34, vcc
	v_pk_mul_f32 v[28:29], v[28:29], v[34:35] op_sel_hi:[1,0]
	v_pk_mul_f32 v[30:31], v[30:31], v[34:35] op_sel_hi:[1,0]
	v_pk_mul_f32 v[24:25], v[24:25], v[34:35] op_sel_hi:[1,0]
	v_pk_mul_f32 v[26:27], v[26:27], v[34:35] op_sel_hi:[1,0]
	v_pk_mul_f32 v[20:21], v[20:21], v[34:35] op_sel_hi:[1,0]
	v_pk_mul_f32 v[22:23], v[22:23], v[34:35] op_sel_hi:[1,0]
	v_pk_mul_f32 v[16:17], v[16:17], v[34:35] op_sel_hi:[1,0]
	v_pk_mul_f32 v[18:19], v[18:19], v[34:35] op_sel_hi:[1,0]
	v_pk_mul_f32 v[30:31], v[70:71], v[30:31]
	v_pk_mul_f32 v[28:29], v[68:69], v[28:29]
	v_pk_mul_f32 v[26:27], v[66:67], v[26:27]
	v_pk_mul_f32 v[24:25], v[64:65], v[24:25]
	v_pk_mul_f32 v[22:23], v[78:79], v[22:23]
	v_pk_mul_f32 v[20:21], v[76:77], v[20:21]
	v_pk_mul_f32 v[18:19], v[74:75], v[18:19]
	v_pk_mul_f32 v[16:17], v[72:73], v[16:17]
; __device__ __forceinline__ unsigned cvtpk(float lo, float hi) { f32x2 v = {lo, hi}; bf16x2_t b = __builtin_convertvector(v, bf16x2_t); return __builtin_bit_cast(unsigned, b); }
;     __device__ __forceinline__ void operator()(const f32x4 (&acc)[2][2][4][2], const Unit& u, int wr, int wc, int fr, int fq) const {
;     ...
;                 const int row = u.pm * BM + ai * HALF + wr * 64 + m * 16 + fr;
;                 float rs = 1.f;
;                 if (PS) { const f32x4 p = *(const f32x4*)(PS + (size_t)row * 16 + 4 * fq); float s = (p[0] + p[1]) + (p[2] + p[3]); s = bfly_add<16>(s); s = bfly_add<32>(s); rs = rsqrtf(s * (1.f / DM) + EPS); }
;                 f32x4 v[2][2]; float ss = 0.f;
; #pragma unroll
;                 for (int bj = 0; bj < 2; ++bj)
; #pragma unroll
;                     for (int n = 0; n < 2; ++n) { v[bj][n] = acc[ai][bj][m][n] * rs; const f32x4 x = v[bj][n]; ss += (x[0] * x[0] + x[1] * x[1]) + (x[2] * x[2] + x[3] * x[3]); }
;                 if (nrm) { ss = bfly_add<16>(ss); ss = bfly_add<32>(ss); const float r2 = rsqrtf(ss * (1.f / 64.f) + EPS);
; #pragma unroll
;                     for (int bj = 0; bj < 2; ++bj)
; #pragma unroll
;                         for (int n = 0; n < 2; ++n) v[bj][n] = v[bj][n] * r2 * gv[bj][n]; }
;                 bf16_t* rowp = Z + (size_t)row * ldz + u.pn * BM + 64 * wc + 8 * fq;
; #pragma unroll
;                 for (int bj = 0; bj < 2; ++bj) { u32x4 w; w.x = cvtpk(v[bj][0][0], v[bj][0][1]); w.y = cvtpk(v[bj][0][2], v[bj][0][3]); w.z = cvtpk(v[bj][1][0], v[bj][1][1]); w.w = cvtpk(v[bj][1][2], v[bj][1][3]);
;                     *(u32x4*)(rowp + 32 * bj) = w; }
.LBB0_174:
	v_mov_b64_e32 v[34:35], s[14:15]
	v_mad_i64_i32 v[32:33], s[8:9], v32, s63, v[34:35]
	v_lshl_add_u64 v[32:33], s[26:27], 1, v[32:33]
	v_lshl_add_u64 v[32:33], v[32:33], 0, s[84:85]
	v_lshl_add_u64 v[32:33], v[32:33], 0, v[144:145]
	v_cvt_pk_bf16_f32 v28, v28, v29
	v_cvt_pk_bf16_f32 v29, v30, v31
	v_cvt_pk_bf16_f32 v30, v24, v25
	v_cvt_pk_bf16_f32 v31, v26, v27
	v_cvt_pk_bf16_f32 v20, v20, v21
	v_cvt_pk_bf16_f32 v21, v22, v23
	v_cvt_pk_bf16_f32 v22, v16, v17
	v_cvt_pk_bf16_f32 v23, v18, v19
	global_store_dwordx4 v[32:33], v[28:31], off
	global_store_dwordx4 v[32:33], v[20:23], off offset:64
	v_add_u32_e32 v16, 0xb0, v168
	v_ashrrev_i32_e32 v17, 31, v16
	v_lshlrev_b64 v[18:19], 6, v[16:17]
	v_lshl_add_u64 v[18:19], v[162:163], 0, v[18:19]
	global_load_dwordx4 v[18:21], v[18:19], off
	s_and_b64 vcc, exec, s[4:5]
	s_waitcnt vmcnt(0)
	v_mov_b32_e32 v22, v19
	v_mov_b32_e32 v23, v20
	v_mov_b32_e32 v19, v21
	v_pk_add_f32 v[18:19], v[22:23], v[18:19]
	s_nop 0
	v_add_f32_e32 v17, v18, v19
	v_mov_b32_e32 v18, v17
	s_nop 1
	v_permlane16_swap_b32_e32 v17, v18
	s_waitcnt lgkmcnt(0)
	v_add_f32_e32 v17, v17, v18
	v_mov_b32_e32 v18, v17
	s_nop 1
	v_permlane32_swap_b32_e32 v17, v18
	v_add_f32_e32 v17, v17, v18
	v_fmamk_f32 v17, v17, 0x3a800000, v173
	v_mul_f32_e32 v18, 0x4b800000, v17
	v_cmp_gt_f32_e64 s[8:9], s62, v17
	s_nop 1
	v_cndmask_b32_e64 v17, v17, v18, s[8:9]
	v_rsq_f32_e32 v17, v17
	s_nop 0
	v_mul_f32_e32 v18, 0x45800000, v17
	v_cndmask_b32_e64 v18, v17, v18, s[8:9]
	v_pk_mul_f32 v[14:15], v[14:15], v[18:19] op_sel_hi:[1,0]
	v_pk_mul_f32 v[12:13], v[12:13], v[18:19] op_sel_hi:[1,0]
	v_pk_mul_f32 v[10:11], v[10:11], v[18:19] op_sel_hi:[1,0]
	v_pk_mul_f32 v[8:9], v[8:9], v[18:19] op_sel_hi:[1,0]
	v_pk_mul_f32 v[6:7], v[6:7], v[18:19] op_sel_hi:[1,0]
	v_pk_mul_f32 v[4:5], v[4:5], v[18:19] op_sel_hi:[1,0]
	v_pk_mul_f32 v[2:3], v[2:3], v[18:19] op_sel_hi:[1,0]
	v_pk_mul_f32 v[0:1], v[0:1], v[18:19] op_sel_hi:[1,0]
	s_cbranch_vccnz .LBB0_176
	v_pk_mul_f32 v[18:19], v[14:15], v[14:15]
	v_pk_mul_f32 v[20:21], v[12:13], v[12:13]
	s_nop 0
	v_pk_mov_b32 v[22:23], v[20:21], v[18:19] op_sel:[1,0]
	v_mov_b32_e32 v21, v19
	v_pk_add_f32 v[18:19], v[22:23], v[20:21]
	v_pk_mul_f32 v[20:21], v[10:11], v[10:11]
	v_pk_add_f32 v[18:19], v[18:19], v[18:19] op_sel_hi:[0,1]
	v_pk_mul_f32 v[22:23], v[8:9], v[8:9]
	v_mul_f32_e32 v18, v4, v4
	v_pk_mov_b32 v[24:25], v[22:23], v[20:21] op_sel:[1,0]
	v_mov_b32_e32 v23, v21
	v_pk_add_f32 v[20:21], v[24:25], v[22:23]
	v_pk_fma_f32 v[22:23], v[4:5], v[4:5], v[18:19] op_sel_hi:[1,1,0]
	v_mul_f32_e32 v18, v6, v6
	v_pk_add_f32 v[20:21], v[20:21], v[20:21] op_sel_hi:[0,1]
	v_pk_fma_f32 v[24:25], v[6:7], v[6:7], v[18:19] op_sel_hi:[1,1,0]
	v_mul_f32_e32 v22, v0, v0
	v_mul_f32_e32 v24, v1, v1
	v_mul_f32_e32 v18, v2, v2
	v_mul_f32_e32 v20, v3, v3
	v_pk_add_f32 v[22:23], v[22:23], v[24:25]
	v_pk_add_f32 v[18:19], v[18:19], v[20:21]
	s_nop 0
	v_pk_add_f32 v[18:19], v[22:23], v[18:19]
	s_nop 0
	v_add_f32_e32 v17, v18, v19
	v_mov_b32_e32 v18, v17
	s_nop 1
	v_permlane16_swap_b32_e32 v17, v18
	s_waitcnt lgkmcnt(0)
	v_add_f32_e32 v17, v17, v18
	v_mov_b32_e32 v18, v17
	s_nop 1
	v_permlane32_swap_b32_e32 v17, v18
	v_add_f32_e32 v17, v17, v18
	v_fmamk_f32 v17, v17, 0x3c800000, v173
	v_mul_f32_e32 v18, 0x4b800000, v17
	v_cmp_gt_f32_e32 vcc, s62, v17
	s_nop 1
	v_cndmask_b32_e32 v17, v17, v18, vcc
	v_rsq_f32_e32 v17, v17
	s_nop 0
	v_mul_f32_e32 v18, 0x45800000, v17
	v_cndmask_b32_e32 v18, v17, v18, vcc
	v_pk_mul_f32 v[12:13], v[12:13], v[18:19] op_sel_hi:[1,0]
	v_pk_mul_f32 v[14:15], v[14:15], v[18:19] op_sel_hi:[1,0]
	v_pk_mul_f32 v[8:9], v[8:9], v[18:19] op_sel_hi:[1,0]
	v_pk_mul_f32 v[10:11], v[10:11], v[18:19] op_sel_hi:[1,0]
	v_pk_mul_f32 v[4:5], v[4:5], v[18:19] op_sel_hi:[1,0]
	v_pk_mul_f32 v[6:7], v[6:7], v[18:19] op_sel_hi:[1,0]
	v_pk_mul_f32 v[0:1], v[0:1], v[18:19] op_sel_hi:[1,0]
	v_pk_mul_f32 v[2:3], v[2:3], v[18:19] op_sel_hi:[1,0]
	v_pk_mul_f32 v[14:15], v[70:71], v[14:15]
	v_pk_mul_f32 v[12:13], v[68:69], v[12:13]
	v_pk_mul_f32 v[10:11], v[66:67], v[10:11]
	v_pk_mul_f32 v[8:9], v[64:65], v[8:9]
	v_pk_mul_f32 v[6:7], v[78:79], v[6:7]
	v_pk_mul_f32 v[4:5], v[76:77], v[4:5]
	v_pk_mul_f32 v[2:3], v[74:75], v[2:3]
	v_pk_mul_f32 v[0:1], v[72:73], v[0:1]

; __device__ __forceinline__ unsigned cvtpk(float lo, float hi) { f32x2 v = {lo, hi}; bf16x2_t b = __builtin_convertvector(v, bf16x2_t); return __builtin_bit_cast(unsigned, b); }
;     __device__ __forceinline__ void operator()(const f32x4 (&acc)[2][2][4][2], const Unit& u, int wr, int wc, int fr, int fq) const {
;     ...
;                 if (nrm) { ss = bfly_add<16>(ss); ss = bfly_add<32>(ss); const float r2 = rsqrtf(ss * (1.f / 64.f) + EPS);
; #pragma unroll
;                     for (int bj = 0; bj < 2; ++bj)
; #pragma unroll
;                         for (int n = 0; n < 2; ++n) v[bj][n] = v[bj][n] * r2 * gv[bj][n]; }
;                 bf16_t* rowp = Z + (size_t)row * ldz + u.pn * BM + 64 * wc + 8 * fq;
; #pragma unroll
;                 for (int bj = 0; bj < 2; ++bj) { u32x4 w; w.x = cvtpk(v[bj][0][0], v[bj][0][1]); w.y = cvtpk(v[bj][0][2], v[bj][0][3]); w.z = cvtpk(v[bj][1][0], v[bj][1][1]); w.w = cvtpk(v[bj][1][2], v[bj][1][3]);
;                     *(u32x4*)(rowp + 32 * bj) = w; }
.LBB0_204:
	v_lshl_add_u32 v168, s37, 8, v161
	v_ashrrev_i32_e32 v169, 31, v168
	s_lshl_b32 s20, s36, 8
	v_lshlrev_b64 v[178:179], 10, v[168:169]
	s_ashr_i32 s21, s20, 31
	v_lshl_add_u64 v[178:179], s[8:9], 0, v[178:179]
	v_lshl_add_u64 v[178:179], s[20:21], 1, v[178:179]
	s_lshl_b32 s84, s34, 1
	v_lshl_add_u64 v[178:179], v[178:179], 0, s[84:85]
	v_lshlrev_b32_e32 v144, 1, v160
	v_lshl_add_u64 v[178:179], v[178:179], 0, v[144:145]
	v_cvt_pk_bf16_f32 v140, v140, v141
	v_cvt_pk_bf16_f32 v141, v142, v143
	v_cvt_pk_bf16_f32 v142, v136, v137
	v_cvt_pk_bf16_f32 v143, v138, v139
	v_cvt_pk_bf16_f32 v132, v132, v133
	v_cvt_pk_bf16_f32 v133, v134, v135
	v_cvt_pk_bf16_f32 v134, v128, v129
	v_cvt_pk_bf16_f32 v135, v130, v131
	global_store_dwordx4 v[178:179], v[140:143], off
	global_store_dwordx4 v[178:179], v[132:135], off offset:64
	s_and_b64 vcc, exec, s[4:5]
	s_cbranch_vccnz .LBB0_206
	v_pk_mul_f32 v[128:129], v[126:127], v[126:127]
	v_pk_mul_f32 v[130:131], v[124:125], v[124:125]
	s_nop 0
	v_pk_mov_b32 v[132:133], v[130:131], v[128:129] op_sel:[1,0]
	v_mov_b32_e32 v131, v129
	v_pk_add_f32 v[128:129], v[132:133], v[130:131]
	v_pk_mul_f32 v[130:131], v[122:123], v[122:123]
	v_pk_mul_f32 v[132:133], v[120:121], v[120:121]
	v_pk_add_f32 v[128:129], v[128:129], v[128:129] op_sel:[0,1] op_sel_hi:[1,0]
	v_pk_mov_b32 v[134:135], v[132:133], v[130:131] op_sel:[1,0]
	v_mov_b32_e32 v133, v131
	v_pk_add_f32 v[130:131], v[134:135], v[132:133]
	v_mul_f32_e32 v132, v112, v112
	v_mul_f32_e32 v133, v113, v113
	v_pk_add_f32 v[130:131], v[130:131], v[130:131] op_sel:[0,1] op_sel_hi:[1,0]
	v_mov_b32_e32 v129, v132
	v_mov_b32_e32 v131, v133
	v_pk_add_f32 v[128:129], v[128:129], v[130:131]
	v_mul_f32_e32 v130, v117, v117
	v_mul_f32_e32 v132, v119, v119
	v_mul_f32_e32 v134, v114, v114
	v_mul_f32_e32 v135, v115, v115
	v_pk_fma_f32 v[130:131], v[116:117], v[116:117], v[130:131] op_sel_hi:[1,1,0]
	v_pk_fma_f32 v[132:133], v[118:119], v[118:119], v[132:133] op_sel_hi:[1,1,0]
	v_mov_b32_e32 v131, v134
	v_mov_b32_e32 v133, v135
	v_pk_add_f32 v[130:131], v[130:131], v[132:133]
	s_nop 0
	v_pk_add_f32 v[128:129], v[128:129], v[130:131]
	s_nop 0
	v_add_f32_e32 v128, v128, v129
	v_mov_b32_e32 v129, v128
	s_nop 1
	v_permlane16_swap_b32_e32 v128, v129
	s_waitcnt lgkmcnt(0)
	v_add_f32_e32 v128, v128, v129
	v_mov_b32_e32 v129, v128
	s_nop 1
	v_permlane32_swap_b32_e32 v128, v129
	v_add_f32_e32 v128, v128, v129
	v_fmamk_f32 v128, v128, 0x3c800000, v173
	v_mul_f32_e32 v129, 0x4b800000, v128
	v_cmp_gt_f32_e32 vcc, s62, v128
	s_nop 1
	v_cndmask_b32_e32 v128, v128, v129, vcc
	v_rsq_f32_e32 v128, v128
	s_nop 0
	v_mul_f32_e32 v129, 0x45800000, v128
	v_cndmask_b32_e32 v128, v128, v129, vcc
	v_pk_mul_f32 v[124:125], v[124:125], v[128:129] op_sel_hi:[1,0]
	v_pk_mul_f32 v[126:127], v[126:127], v[128:129] op_sel_hi:[1,0]
	v_pk_mul_f32 v[120:121], v[120:121], v[128:129] op_sel_hi:[1,0]
	v_pk_mul_f32 v[122:123], v[122:123], v[128:129] op_sel_hi:[1,0]
	v_pk_mul_f32 v[116:117], v[116:117], v[128:129] op_sel_hi:[1,0]
	v_pk_mul_f32 v[118:119], v[118:119], v[128:129] op_sel_hi:[1,0]
	v_pk_mul_f32 v[112:113], v[112:113], v[128:129] op_sel_hi:[1,0]
	v_pk_mul_f32 v[114:115], v[114:115], v[128:129] op_sel_hi:[1,0]
	s_waitcnt vmcnt(0)
	v_pk_mul_f32 v[126:127], v[102:103], v[126:127]
	v_pk_mul_f32 v[124:125], v[100:101], v[124:125]
	v_pk_mul_f32 v[122:123], v[98:99], v[122:123]
	v_pk_mul_f32 v[120:121], v[96:97], v[120:121]
	v_pk_mul_f32 v[118:119], v[110:111], v[118:119]
	v_pk_mul_f32 v[116:117], v[108:109], v[116:117]
	v_pk_mul_f32 v[114:115], v[106:107], v[114:115]
	v_pk_mul_f32 v[112:113], v[104:105], v[112:113]
.LBB0_206:
	v_or_b32_e32 v128, 16, v168
	v_ashrrev_i32_e32 v129, 31, v128
	v_lshlrev_b64 v[128:129], 10, v[128:129]
	v_lshl_add_u64 v[128:129], s[8:9], 0, v[128:129]
	v_lshl_add_u64 v[128:129], s[20:21], 1, v[128:129]
	v_lshl_add_u64 v[128:129], v[128:129], 0, s[84:85]
	v_lshl_add_u64 v[128:129], v[128:129], 0, v[144:145]
	v_cvt_pk_bf16_f32 v124, v124, v125
	v_cvt_pk_bf16_f32 v125, v126, v127
	v_cvt_pk_bf16_f32 v126, v120, v121
	v_cvt_pk_bf16_f32 v127, v122, v123
	v_cvt_pk_bf16_f32 v116, v116, v117
	v_cvt_pk_bf16_f32 v117, v118, v119
	v_cvt_pk_bf16_f32 v118, v112, v113
	v_cvt_pk_bf16_f32 v119, v114, v115
	global_store_dwordx4 v[128:129], v[124:127], off
	global_store_dwordx4 v[128:129], v[116:119], off offset:64
	s_and_b64 vcc, exec, s[4:5]
	s_cbranch_vccnz .LBB0_208
	v_pk_mul_f32 v[112:113], v[94:95], v[94:95]
	v_pk_mul_f32 v[114:115], v[92:93], v[92:93]
	s_nop 0
	v_pk_mov_b32 v[116:117], v[114:115], v[112:113] op_sel:[1,0]
	v_mov_b32_e32 v115, v113
	v_pk_add_f32 v[112:113], v[116:117], v[114:115]
	v_pk_mul_f32 v[114:115], v[90:91], v[90:91]
	v_pk_mul_f32 v[116:117], v[88:89], v[88:89]
	v_pk_add_f32 v[112:113], v[112:113], v[112:113] op_sel:[0,1] op_sel_hi:[1,0]
	v_pk_mov_b32 v[118:119], v[116:117], v[114:115] op_sel:[1,0]
	v_mov_b32_e32 v117, v115
	v_pk_add_f32 v[114:115], v[118:119], v[116:117]
	v_mul_f32_e32 v116, v80, v80
	v_mul_f32_e32 v117, v81, v81
	v_pk_add_f32 v[114:115], v[114:115], v[114:115] op_sel:[0,1] op_sel_hi:[1,0]
	v_mov_b32_e32 v113, v116
	v_mov_b32_e32 v115, v117
	v_pk_add_f32 v[112:113], v[112:113], v[114:115]
	v_mul_f32_e32 v114, v85, v85
	v_mul_f32_e32 v116, v87, v87
	v_mul_f32_e32 v118, v82, v82
	v_mul_f32_e32 v119, v83, v83
	v_pk_fma_f32 v[114:115], v[84:85], v[84:85], v[114:115] op_sel_hi:[1,1,0]
	v_pk_fma_f32 v[116:117], v[86:87], v[86:87], v[116:117] op_sel_hi:[1,1,0]
	v_mov_b32_e32 v115, v118
	v_mov_b32_e32 v117, v119
	v_pk_add_f32 v[114:115], v[114:115], v[116:117]
	s_nop 0
	v_pk_add_f32 v[112:113], v[112:113], v[114:115]
	s_nop 0
	v_add_f32_e32 v112, v112, v113
	v_mov_b32_e32 v113, v112
	s_nop 1
	v_permlane16_swap_b32_e32 v112, v113
	s_waitcnt lgkmcnt(0)
	v_add_f32_e32 v112, v112, v113
	v_mov_b32_e32 v113, v112
	s_nop 1
	v_permlane32_swap_b32_e32 v112, v113
	v_add_f32_e32 v112, v112, v113
	v_fmamk_f32 v112, v112, 0x3c800000, v173
	v_mul_f32_e32 v113, 0x4b800000, v112
	v_cmp_gt_f32_e32 vcc, s62, v112
	s_nop 1
	v_cndmask_b32_e32 v112, v112, v113, vcc
	v_rsq_f32_e32 v112, v112
	s_nop 0
	v_mul_f32_e32 v113, 0x45800000, v112
	v_cndmask_b32_e32 v112, v112, v113, vcc
	v_pk_mul_f32 v[92:93], v[92:93], v[112:113] op_sel_hi:[1,0]
	v_pk_mul_f32 v[94:95], v[94:95], v[112:113] op_sel_hi:[1,0]
	v_pk_mul_f32 v[88:89], v[88:89], v[112:113] op_sel_hi:[1,0]
	v_pk_mul_f32 v[90:91], v[90:91], v[112:113] op_sel_hi:[1,0]
	v_pk_mul_f32 v[84:85], v[84:85], v[112:113] op_sel_hi:[1,0]
	v_pk_mul_f32 v[86:87], v[86:87], v[112:113] op_sel_hi:[1,0]
	v_pk_mul_f32 v[80:81], v[80:81], v[112:113] op_sel_hi:[1,0]
	v_pk_mul_f32 v[82:83], v[82:83], v[112:113] op_sel_hi:[1,0]
	s_waitcnt vmcnt(0)
	v_pk_mul_f32 v[94:95], v[102:103], v[94:95]
	v_pk_mul_f32 v[92:93], v[100:101], v[92:93]
	v_pk_mul_f32 v[90:91], v[98:99], v[90:91]
	v_pk_mul_f32 v[88:89], v[96:97], v[88:89]
	v_pk_mul_f32 v[86:87], v[110:111], v[86:87]
	v_pk_mul_f32 v[84:85], v[108:109], v[84:85]
	v_pk_mul_f32 v[82:83], v[106:107], v[82:83]
	v_pk_mul_f32 v[80:81], v[104:105], v[80:81]
; __device__ __forceinline__ unsigned cvtpk(float lo, float hi) { f32x2 v = {lo, hi}; bf16x2_t b = __builtin_convertvector(v, bf16x2_t); return __builtin_bit_cast(unsigned, b); }
;     __device__ __forceinline__ void operator()(const f32x4 (&acc)[2][2][4][2], const Unit& u, int wr, int wc, int fr, int fq) const {
;     ...
;                 if (nrm) { ss = bfly_add<16>(ss); ss = bfly_add<32>(ss); const float r2 = rsqrtf(ss * (1.f / 64.f) + EPS);
; #pragma unroll
;                     for (int bj = 0; bj < 2; ++bj)
; #pragma unroll
;                         for (int n = 0; n < 2; ++n) v[bj][n] = v[bj][n] * r2 * gv[bj][n]; }
;                 bf16_t* rowp = Z + (size_t)row * ldz + u.pn * BM + 64 * wc + 8 * fq;
; #pragma unroll
;                 for (int bj = 0; bj < 2; ++bj) { u32x4 w; w.x = cvtpk(v[bj][0][0], v[bj][0][1]); w.y = cvtpk(v[bj][0][2], v[bj][0][3]); w.z = cvtpk(v[bj][1][0], v[bj][1][1]); w.w = cvtpk(v[bj][1][2], v[bj][1][3]);
;                     *(u32x4*)(rowp + 32 * bj) = w; }
.LBB0_208:
	v_or_b32_e32 v112, 32, v168
	v_ashrrev_i32_e32 v113, 31, v112
	v_lshlrev_b64 v[112:113], 10, v[112:113]
	v_lshl_add_u64 v[112:113], s[8:9], 0, v[112:113]
	v_lshl_add_u64 v[112:113], s[20:21], 1, v[112:113]
	v_lshl_add_u64 v[112:113], v[112:113], 0, s[84:85]
	v_lshl_add_u64 v[112:113], v[112:113], 0, v[144:145]
	v_cvt_pk_bf16_f32 v92, v92, v93
	v_cvt_pk_bf16_f32 v93, v94, v95
	v_cvt_pk_bf16_f32 v94, v88, v89
	v_cvt_pk_bf16_f32 v95, v90, v91
	v_cvt_pk_bf16_f32 v84, v84, v85
	v_cvt_pk_bf16_f32 v85, v86, v87
	v_cvt_pk_bf16_f32 v86, v80, v81
	v_cvt_pk_bf16_f32 v87, v82, v83
	global_store_dwordx4 v[112:113], v[92:95], off
	global_store_dwordx4 v[112:113], v[84:87], off offset:64
	s_and_b64 vcc, exec, s[4:5]
	s_cbranch_vccnz .LBB0_210
	v_pk_mul_f32 v[80:81], v[78:79], v[78:79]
	v_pk_mul_f32 v[82:83], v[76:77], v[76:77]
	s_nop 0
	v_pk_mov_b32 v[84:85], v[82:83], v[80:81] op_sel:[1,0]
	v_mov_b32_e32 v83, v81
	v_pk_add_f32 v[80:81], v[84:85], v[82:83]
	v_pk_mul_f32 v[82:83], v[74:75], v[74:75]
	v_pk_mul_f32 v[84:85], v[72:73], v[72:73]
	v_pk_add_f32 v[80:81], v[80:81], v[80:81] op_sel:[0,1] op_sel_hi:[1,0]
	v_pk_mov_b32 v[86:87], v[84:85], v[82:83] op_sel:[1,0]
	v_mov_b32_e32 v85, v83
	v_pk_add_f32 v[82:83], v[86:87], v[84:85]
	v_mul_f32_e32 v84, v64, v64
	v_mul_f32_e32 v85, v65, v65
	v_pk_add_f32 v[82:83], v[82:83], v[82:83] op_sel:[0,1] op_sel_hi:[1,0]
	v_mov_b32_e32 v81, v84
	v_mov_b32_e32 v83, v85
	v_pk_add_f32 v[80:81], v[80:81], v[82:83]
	v_mul_f32_e32 v82, v69, v69
	v_mul_f32_e32 v84, v71, v71
	v_mul_f32_e32 v86, v66, v66
	v_mul_f32_e32 v87, v67, v67
	v_pk_fma_f32 v[82:83], v[68:69], v[68:69], v[82:83] op_sel_hi:[1,1,0]
	v_pk_fma_f32 v[84:85], v[70:71], v[70:71], v[84:85] op_sel_hi:[1,1,0]
	v_mov_b32_e32 v83, v86
	v_mov_b32_e32 v85, v87
	v_pk_add_f32 v[82:83], v[82:83], v[84:85]
	s_nop 0
	v_pk_add_f32 v[80:81], v[80:81], v[82:83]
	s_nop 0
	v_add_f32_e32 v80, v80, v81
	v_mov_b32_e32 v81, v80
	s_nop 1
	v_permlane16_swap_b32_e32 v80, v81
	s_waitcnt lgkmcnt(0)
	v_add_f32_e32 v80, v80, v81
	v_mov_b32_e32 v81, v80
	s_nop 1
	v_permlane32_swap_b32_e32 v80, v81
	v_add_f32_e32 v80, v80, v81
	v_fmamk_f32 v80, v80, 0x3c800000, v173
	v_mul_f32_e32 v81, 0x4b800000, v80
	v_cmp_gt_f32_e32 vcc, s62, v80
	s_nop 1
	v_cndmask_b32_e32 v80, v80, v81, vcc
	v_rsq_f32_e32 v80, v80
	s_nop 0
	v_mul_f32_e32 v81, 0x45800000, v80
	v_cndmask_b32_e32 v80, v80, v81, vcc
	v_pk_mul_f32 v[76:77], v[76:77], v[80:81] op_sel_hi:[1,0]
	v_pk_mul_f32 v[78:79], v[78:79], v[80:81] op_sel_hi:[1,0]
	v_pk_mul_f32 v[72:73], v[72:73], v[80:81] op_sel_hi:[1,0]
	v_pk_mul_f32 v[74:75], v[74:75], v[80:81] op_sel_hi:[1,0]
	v_pk_mul_f32 v[68:69], v[68:69], v[80:81] op_sel_hi:[1,0]
	v_pk_mul_f32 v[70:71], v[70:71], v[80:81] op_sel_hi:[1,0]
	v_pk_mul_f32 v[64:65], v[64:65], v[80:81] op_sel_hi:[1,0]
	v_pk_mul_f32 v[66:67], v[66:67], v[80:81] op_sel_hi:[1,0]
	s_waitcnt vmcnt(0)
	v_pk_mul_f32 v[78:79], v[102:103], v[78:79]
	v_pk_mul_f32 v[76:77], v[100:101], v[76:77]
	v_pk_mul_f32 v[74:75], v[98:99], v[74:75]
	v_pk_mul_f32 v[72:73], v[96:97], v[72:73]
	v_pk_mul_f32 v[70:71], v[110:111], v[70:71]
	v_pk_mul_f32 v[68:69], v[108:109], v[68:69]
	v_pk_mul_f32 v[66:67], v[106:107], v[66:67]
	v_pk_mul_f32 v[64:65], v[104:105], v[64:65]
.LBB0_210:
	v_or_b32_e32 v80, 48, v168
	v_ashrrev_i32_e32 v81, 31, v80
	v_lshlrev_b64 v[80:81], 10, v[80:81]
	v_lshl_add_u64 v[80:81], s[8:9], 0, v[80:81]
	v_lshl_add_u64 v[80:81], s[20:21], 1, v[80:81]
	v_lshl_add_u64 v[80:81], v[80:81], 0, s[84:85]
	v_lshl_add_u64 v[80:81], v[80:81], 0, v[144:145]
	v_cvt_pk_bf16_f32 v76, v76, v77
	v_cvt_pk_bf16_f32 v77, v78, v79
	v_cvt_pk_bf16_f32 v78, v72, v73
	v_cvt_pk_bf16_f32 v79, v74, v75
	v_cvt_pk_bf16_f32 v68, v68, v69
	v_cvt_pk_bf16_f32 v69, v70, v71
	v_cvt_pk_bf16_f32 v70, v64, v65
	v_cvt_pk_bf16_f32 v71, v66, v67
	global_store_dwordx4 v[80:81], v[76:79], off
	global_store_dwordx4 v[80:81], v[68:71], off offset:64
	s_and_b64 vcc, exec, s[4:5]
	s_cbranch_vccnz .LBB0_212
	v_pk_mul_f32 v[64:65], v[62:63], v[62:63]
	v_pk_mul_f32 v[66:67], v[60:61], v[60:61]
	s_nop 0
	v_pk_mov_b32 v[68:69], v[66:67], v[64:65] op_sel:[1,0]
	v_mov_b32_e32 v67, v65
	v_pk_add_f32 v[64:65], v[68:69], v[66:67]
	v_pk_mul_f32 v[66:67], v[58:59], v[58:59]
	v_pk_mul_f32 v[68:69], v[56:57], v[56:57]
	v_pk_add_f32 v[64:65], v[64:65], v[64:65] op_sel:[0,1] op_sel_hi:[1,0]
	v_pk_mov_b32 v[70:71], v[68:69], v[66:67] op_sel:[1,0]
	v_mov_b32_e32 v69, v67
	v_pk_add_f32 v[66:67], v[70:71], v[68:69]
	v_mul_f32_e32 v68, v48, v48
	v_mul_f32_e32 v69, v49, v49
	v_pk_add_f32 v[66:67], v[66:67], v[66:67] op_sel:[0,1] op_sel_hi:[1,0]
	v_mov_b32_e32 v65, v68
	v_mov_b32_e32 v67, v69
	v_pk_add_f32 v[64:65], v[64:65], v[66:67]
	v_mul_f32_e32 v66, v53, v53
	v_mul_f32_e32 v68, v55, v55
	v_mul_f32_e32 v70, v50, v50
	v_mul_f32_e32 v71, v51, v51
	v_pk_fma_f32 v[66:67], v[52:53], v[52:53], v[66:67] op_sel_hi:[1,1,0]
	v_pk_fma_f32 v[68:69], v[54:55], v[54:55], v[68:69] op_sel_hi:[1,1,0]
	v_mov_b32_e32 v67, v70
	v_mov_b32_e32 v69, v71
	v_pk_add_f32 v[66:67], v[66:67], v[68:69]
	s_nop 0
	v_pk_add_f32 v[64:65], v[64:65], v[66:67]
	s_nop 0
	v_add_f32_e32 v64, v64, v65
	v_mov_b32_e32 v65, v64
	s_nop 1
	v_permlane16_swap_b32_e32 v64, v65
	s_waitcnt lgkmcnt(0)
	v_add_f32_e32 v64, v64, v65
	v_mov_b32_e32 v65, v64
	s_nop 1
	v_permlane32_swap_b32_e32 v64, v65
	v_add_f32_e32 v64, v64, v65
	v_fmamk_f32 v64, v64, 0x3c800000, v173
	v_mul_f32_e32 v65, 0x4b800000, v64
	v_cmp_gt_f32_e32 vcc, s62, v64
	s_nop 1
	v_cndmask_b32_e32 v64, v64, v65, vcc
	v_rsq_f32_e32 v64, v64
	s_nop 0
	v_mul_f32_e32 v65, 0x45800000, v64
	v_cndmask_b32_e32 v64, v64, v65, vcc
	v_pk_mul_f32 v[60:61], v[60:61], v[64:65] op_sel_hi:[1,0]
	v_pk_mul_f32 v[62:63], v[62:63], v[64:65] op_sel_hi:[1,0]
	v_pk_mul_f32 v[56:57], v[56:57], v[64:65] op_sel_hi:[1,0]
	v_pk_mul_f32 v[58:59], v[58:59], v[64:65] op_sel_hi:[1,0]
	v_pk_mul_f32 v[52:53], v[52:53], v[64:65] op_sel_hi:[1,0]
	v_pk_mul_f32 v[54:55], v[54:55], v[64:65] op_sel_hi:[1,0]
	v_pk_mul_f32 v[48:49], v[48:49], v[64:65] op_sel_hi:[1,0]
	v_pk_mul_f32 v[50:51], v[50:51], v[64:65] op_sel_hi:[1,0]
	s_waitcnt vmcnt(0)
	v_pk_mul_f32 v[62:63], v[102:103], v[62:63]
	v_pk_mul_f32 v[60:61], v[100:101], v[60:61]
	v_pk_mul_f32 v[58:59], v[98:99], v[58:59]
	v_pk_mul_f32 v[56:57], v[96:97], v[56:57]
	v_pk_mul_f32 v[54:55], v[110:111], v[54:55]
	v_pk_mul_f32 v[52:53], v[108:109], v[52:53]
	v_pk_mul_f32 v[50:51], v[106:107], v[50:51]
	v_pk_mul_f32 v[48:49], v[104:105], v[48:49]
; __device__ __forceinline__ unsigned cvtpk(float lo, float hi) { f32x2 v = {lo, hi}; bf16x2_t b = __builtin_convertvector(v, bf16x2_t); return __builtin_bit_cast(unsigned, b); }
;     __device__ __forceinline__ void operator()(const f32x4 (&acc)[2][2][4][2], const Unit& u, int wr, int wc, int fr, int fq) const {
;     ...
;                 if (nrm) { ss = bfly_add<16>(ss); ss = bfly_add<32>(ss); const float r2 = rsqrtf(ss * (1.f / 64.f) + EPS);
; #pragma unroll
;                     for (int bj = 0; bj < 2; ++bj)
; #pragma unroll
;                         for (int n = 0; n < 2; ++n) v[bj][n] = v[bj][n] * r2 * gv[bj][n]; }
;                 bf16_t* rowp = Z + (size_t)row * ldz + u.pn * BM + 64 * wc + 8 * fq;
; #pragma unroll
;                 for (int bj = 0; bj < 2; ++bj) { u32x4 w; w.x = cvtpk(v[bj][0][0], v[bj][0][1]); w.y = cvtpk(v[bj][0][2], v[bj][0][3]); w.z = cvtpk(v[bj][1][0], v[bj][1][1]); w.w = cvtpk(v[bj][1][2], v[bj][1][3]);
;                     *(u32x4*)(rowp + 32 * bj) = w; }
.LBB0_212:
	v_add_u32_e32 v64, 0x80, v168
	v_ashrrev_i32_e32 v65, 31, v64
	v_lshlrev_b64 v[64:65], 10, v[64:65]
	v_lshl_add_u64 v[64:65], s[8:9], 0, v[64:65]
	v_lshl_add_u64 v[64:65], s[20:21], 1, v[64:65]
	v_lshl_add_u64 v[64:65], v[64:65], 0, s[84:85]
	v_lshl_add_u64 v[64:65], v[64:65], 0, v[144:145]
	v_cvt_pk_bf16_f32 v60, v60, v61
	v_cvt_pk_bf16_f32 v61, v62, v63
	v_cvt_pk_bf16_f32 v62, v56, v57
	v_cvt_pk_bf16_f32 v63, v58, v59
	v_cvt_pk_bf16_f32 v52, v52, v53
	v_cvt_pk_bf16_f32 v53, v54, v55
	v_cvt_pk_bf16_f32 v54, v48, v49
	v_cvt_pk_bf16_f32 v55, v50, v51
	global_store_dwordx4 v[64:65], v[60:63], off
	global_store_dwordx4 v[64:65], v[52:55], off offset:64
	s_and_b64 vcc, exec, s[4:5]
	s_cbranch_vccnz .LBB0_214
	v_pk_mul_f32 v[48:49], v[46:47], v[46:47]
	v_pk_mul_f32 v[50:51], v[44:45], v[44:45]
	s_nop 0
	v_pk_mov_b32 v[52:53], v[50:51], v[48:49] op_sel:[1,0]
	v_mov_b32_e32 v51, v49
	v_pk_add_f32 v[48:49], v[52:53], v[50:51]
	v_pk_mul_f32 v[50:51], v[42:43], v[42:43]
	v_pk_mul_f32 v[52:53], v[40:41], v[40:41]
	v_pk_add_f32 v[48:49], v[48:49], v[48:49] op_sel:[0,1] op_sel_hi:[1,0]
	v_pk_mov_b32 v[54:55], v[52:53], v[50:51] op_sel:[1,0]
	v_mov_b32_e32 v53, v51
	v_pk_add_f32 v[50:51], v[54:55], v[52:53]
	v_mul_f32_e32 v52, v32, v32
	v_mul_f32_e32 v53, v33, v33
	v_pk_add_f32 v[50:51], v[50:51], v[50:51] op_sel:[0,1] op_sel_hi:[1,0]
	v_mov_b32_e32 v49, v52
	v_mov_b32_e32 v51, v53
	v_pk_add_f32 v[48:49], v[48:49], v[50:51]
	v_mul_f32_e32 v50, v37, v37
	v_mul_f32_e32 v52, v39, v39
	v_mul_f32_e32 v54, v34, v34
	v_mul_f32_e32 v55, v35, v35
	v_pk_fma_f32 v[50:51], v[36:37], v[36:37], v[50:51] op_sel_hi:[1,1,0]
	v_pk_fma_f32 v[52:53], v[38:39], v[38:39], v[52:53] op_sel_hi:[1,1,0]
	v_mov_b32_e32 v51, v54
	v_mov_b32_e32 v53, v55
	v_pk_add_f32 v[50:51], v[50:51], v[52:53]
	s_nop 0
	v_pk_add_f32 v[48:49], v[48:49], v[50:51]
	s_nop 0
	v_add_f32_e32 v48, v48, v49
	v_mov_b32_e32 v49, v48
	s_nop 1
	v_permlane16_swap_b32_e32 v48, v49
	s_waitcnt lgkmcnt(0)
	v_add_f32_e32 v48, v48, v49
	v_mov_b32_e32 v49, v48
	s_nop 1
	v_permlane32_swap_b32_e32 v48, v49
	v_add_f32_e32 v48, v48, v49
	v_fmamk_f32 v48, v48, 0x3c800000, v173
	v_mul_f32_e32 v49, 0x4b800000, v48
	v_cmp_gt_f32_e32 vcc, s62, v48
	s_nop 1
	v_cndmask_b32_e32 v48, v48, v49, vcc
	v_rsq_f32_e32 v48, v48
	s_nop 0
	v_mul_f32_e32 v49, 0x45800000, v48
	v_cndmask_b32_e32 v48, v48, v49, vcc
	v_pk_mul_f32 v[44:45], v[44:45], v[48:49] op_sel_hi:[1,0]
	v_pk_mul_f32 v[46:47], v[46:47], v[48:49] op_sel_hi:[1,0]
	v_pk_mul_f32 v[40:41], v[40:41], v[48:49] op_sel_hi:[1,0]
	v_pk_mul_f32 v[42:43], v[42:43], v[48:49] op_sel_hi:[1,0]
	v_pk_mul_f32 v[36:37], v[36:37], v[48:49] op_sel_hi:[1,0]
	v_pk_mul_f32 v[38:39], v[38:39], v[48:49] op_sel_hi:[1,0]
	v_pk_mul_f32 v[32:33], v[32:33], v[48:49] op_sel_hi:[1,0]
	v_pk_mul_f32 v[34:35], v[34:35], v[48:49] op_sel_hi:[1,0]
	s_waitcnt vmcnt(0)
	v_pk_mul_f32 v[46:47], v[102:103], v[46:47]
	v_pk_mul_f32 v[44:45], v[100:101], v[44:45]
	v_pk_mul_f32 v[42:43], v[98:99], v[42:43]
	v_pk_mul_f32 v[40:41], v[96:97], v[40:41]
	v_pk_mul_f32 v[38:39], v[110:111], v[38:39]
	v_pk_mul_f32 v[36:37], v[108:109], v[36:37]
	v_pk_mul_f32 v[34:35], v[106:107], v[34:35]
	v_pk_mul_f32 v[32:33], v[104:105], v[32:33]
; __device__ __forceinline__ unsigned cvtpk(float lo, float hi) { f32x2 v = {lo, hi}; bf16x2_t b = __builtin_convertvector(v, bf16x2_t); return __builtin_bit_cast(unsigned, b); }
;     __device__ __forceinline__ void operator()(const f32x4 (&acc)[2][2][4][2], const Unit& u, int wr, int wc, int fr, int fq) const {
;     ...
;                 const int row = u.pm * BM + ai * HALF + wr * 64 + m * 16 + fr;
;                 float rs = 1.f;
;                 if (PS) { const f32x4 p = *(const f32x4*)(PS + (size_t)row * 16 + 4 * fq); float s = (p[0] + p[1]) + (p[2] + p[3]); s = bfly_add<16>(s); s = bfly_add<32>(s); rs = rsqrtf(s * (1.f / DM) + EPS); }
;                 f32x4 v[2][2]; float ss = 0.f;
; #pragma unroll
;                 for (int bj = 0; bj < 2; ++bj)
; #pragma unroll
;                     for (int n = 0; n < 2; ++n) { v[bj][n] = acc[ai][bj][m][n] * rs; const f32x4 x = v[bj][n]; ss += (x[0] * x[0] + x[1] * x[1]) + (x[2] * x[2] + x[3] * x[3]); }
;                 if (nrm) { ss = bfly_add<16>(ss); ss = bfly_add<32>(ss); const float r2 = rsqrtf(ss * (1.f / 64.f) + EPS);
; #pragma unroll
;                     for (int bj = 0; bj < 2; ++bj)
; #pragma unroll
;                         for (int n = 0; n < 2; ++n) v[bj][n] = v[bj][n] * r2 * gv[bj][n]; }
;                 bf16_t* rowp = Z + (size_t)row * ldz + u.pn * BM + 64 * wc + 8 * fq;
; #pragma unroll
;                 for (int bj = 0; bj < 2; ++bj) { u32x4 w; w.x = cvtpk(v[bj][0][0], v[bj][0][1]); w.y = cvtpk(v[bj][0][2], v[bj][0][3]); w.z = cvtpk(v[bj][1][0], v[bj][1][1]); w.w = cvtpk(v[bj][1][2], v[bj][1][3]);
;                     *(u32x4*)(rowp + 32 * bj) = w; }
.LBB0_214:
	v_add_u32_e32 v48, 0x90, v168
	v_ashrrev_i32_e32 v49, 31, v48
	v_lshlrev_b64 v[48:49], 10, v[48:49]
	v_lshl_add_u64 v[48:49], s[8:9], 0, v[48:49]
	v_lshl_add_u64 v[48:49], s[20:21], 1, v[48:49]
	v_lshl_add_u64 v[48:49], v[48:49], 0, s[84:85]
	v_lshl_add_u64 v[48:49], v[48:49], 0, v[144:145]
	v_cvt_pk_bf16_f32 v44, v44, v45
	v_cvt_pk_bf16_f32 v45, v46, v47
	v_cvt_pk_bf16_f32 v46, v40, v41
	v_cvt_pk_bf16_f32 v47, v42, v43
	v_cvt_pk_bf16_f32 v36, v36, v37
	v_cvt_pk_bf16_f32 v37, v38, v39
	v_cvt_pk_bf16_f32 v38, v32, v33
	v_cvt_pk_bf16_f32 v39, v34, v35
	global_store_dwordx4 v[48:49], v[44:47], off
	global_store_dwordx4 v[48:49], v[36:39], off offset:64
	s_and_b64 vcc, exec, s[4:5]
	s_cbranch_vccnz .LBB0_216
	v_pk_mul_f32 v[32:33], v[30:31], v[30:31]
	v_pk_mul_f32 v[34:35], v[28:29], v[28:29]
	s_nop 0
	v_pk_mov_b32 v[36:37], v[34:35], v[32:33] op_sel:[1,0]
	v_mov_b32_e32 v35, v33
	v_pk_add_f32 v[32:33], v[36:37], v[34:35]
	v_pk_mul_f32 v[34:35], v[26:27], v[26:27]
	v_pk_mul_f32 v[36:37], v[24:25], v[24:25]
	v_pk_add_f32 v[32:33], v[32:33], v[32:33] op_sel:[0,1] op_sel_hi:[1,0]
	v_pk_mov_b32 v[38:39], v[36:37], v[34:35] op_sel:[1,0]
	v_mov_b32_e32 v37, v35
	v_pk_add_f32 v[34:35], v[38:39], v[36:37]
	v_mul_f32_e32 v36, v16, v16
	v_mul_f32_e32 v37, v17, v17
	v_pk_add_f32 v[34:35], v[34:35], v[34:35] op_sel:[0,1] op_sel_hi:[1,0]
	v_mov_b32_e32 v33, v36
	v_mov_b32_e32 v35, v37
	v_pk_add_f32 v[32:33], v[32:33], v[34:35]
	v_mul_f32_e32 v34, v21, v21
	v_mul_f32_e32 v36, v23, v23
	v_mul_f32_e32 v38, v18, v18
	v_mul_f32_e32 v39, v19, v19
	v_pk_fma_f32 v[34:35], v[20:21], v[20:21], v[34:35] op_sel_hi:[1,1,0]
	v_pk_fma_f32 v[36:37], v[22:23], v[22:23], v[36:37] op_sel_hi:[1,1,0]
	v_mov_b32_e32 v35, v38
	v_mov_b32_e32 v37, v39
	v_pk_add_f32 v[34:35], v[34:35], v[36:37]
	s_nop 0
	v_pk_add_f32 v[32:33], v[32:33], v[34:35]
	s_nop 0
	v_add_f32_e32 v32, v32, v33
	v_mov_b32_e32 v33, v32
	s_nop 1
	v_permlane16_swap_b32_e32 v32, v33
	s_waitcnt lgkmcnt(0)
	v_add_f32_e32 v32, v32, v33
	v_mov_b32_e32 v33, v32
	s_nop 1
	v_permlane32_swap_b32_e32 v32, v33
	v_add_f32_e32 v32, v32, v33
	v_fmamk_f32 v32, v32, 0x3c800000, v173
	v_mul_f32_e32 v33, 0x4b800000, v32
	v_cmp_gt_f32_e32 vcc, s62, v32
	s_nop 1
	v_cndmask_b32_e32 v32, v32, v33, vcc
	v_rsq_f32_e32 v32, v32
	s_nop 0
	v_mul_f32_e32 v33, 0x45800000, v32
	v_cndmask_b32_e32 v32, v32, v33, vcc
	v_pk_mul_f32 v[28:29], v[28:29], v[32:33] op_sel_hi:[1,0]
	v_pk_mul_f32 v[30:31], v[30:31], v[32:33] op_sel_hi:[1,0]
	v_pk_mul_f32 v[24:25], v[24:25], v[32:33] op_sel_hi:[1,0]
	v_pk_mul_f32 v[26:27], v[26:27], v[32:33] op_sel_hi:[1,0]
	v_pk_mul_f32 v[20:21], v[20:21], v[32:33] op_sel_hi:[1,0]
	v_pk_mul_f32 v[22:23], v[22:23], v[32:33] op_sel_hi:[1,0]
	v_pk_mul_f32 v[16:17], v[16:17], v[32:33] op_sel_hi:[1,0]
	v_pk_mul_f32 v[18:19], v[18:19], v[32:33] op_sel_hi:[1,0]
	s_waitcnt vmcnt(0)
	v_pk_mul_f32 v[30:31], v[102:103], v[30:31]
	v_pk_mul_f32 v[28:29], v[100:101], v[28:29]
	v_pk_mul_f32 v[26:27], v[98:99], v[26:27]
	v_pk_mul_f32 v[24:25], v[96:97], v[24:25]
	v_pk_mul_f32 v[22:23], v[110:111], v[22:23]
	v_pk_mul_f32 v[20:21], v[108:109], v[20:21]
	v_pk_mul_f32 v[18:19], v[106:107], v[18:19]
	v_pk_mul_f32 v[16:17], v[104:105], v[16:17]
.LBB0_216:
	v_add_u32_e32 v32, 0xa0, v168
	v_ashrrev_i32_e32 v33, 31, v32
	v_lshlrev_b64 v[32:33], 10, v[32:33]
	v_lshl_add_u64 v[32:33], s[8:9], 0, v[32:33]
	v_lshl_add_u64 v[32:33], s[20:21], 1, v[32:33]
	v_lshl_add_u64 v[32:33], v[32:33], 0, s[84:85]
	v_lshl_add_u64 v[32:33], v[32:33], 0, v[144:145]
	v_cvt_pk_bf16_f32 v28, v28, v29
	v_cvt_pk_bf16_f32 v29, v30, v31
	v_cvt_pk_bf16_f32 v30, v24, v25
	v_cvt_pk_bf16_f32 v31, v26, v27
	v_cvt_pk_bf16_f32 v20, v20, v21
	v_cvt_pk_bf16_f32 v21, v22, v23
	v_cvt_pk_bf16_f32 v22, v16, v17
	v_cvt_pk_bf16_f32 v23, v18, v19
	global_store_dwordx4 v[32:33], v[28:31], off
	global_store_dwordx4 v[32:33], v[20:23], off offset:64
	s_and_b64 vcc, exec, s[4:5]
	s_cbranch_vccnz .LBB0_218
	v_pk_mul_f32 v[16:17], v[14:15], v[14:15]
	v_pk_mul_f32 v[18:19], v[12:13], v[12:13]
	s_nop 0
	v_pk_mov_b32 v[20:21], v[18:19], v[16:17] op_sel:[1,0]
	v_mov_b32_e32 v19, v17
	v_pk_add_f32 v[16:17], v[20:21], v[18:19]
	v_pk_mul_f32 v[18:19], v[10:11], v[10:11]
	v_pk_mul_f32 v[20:21], v[8:9], v[8:9]
	v_pk_add_f32 v[16:17], v[16:17], v[16:17] op_sel:[0,1] op_sel_hi:[1,0]
	v_pk_mov_b32 v[22:23], v[20:21], v[18:19] op_sel:[1,0]
	v_mov_b32_e32 v21, v19
	v_pk_add_f32 v[18:19], v[22:23], v[20:21]
	v_mul_f32_e32 v20, v0, v0
	v_mul_f32_e32 v21, v1, v1
	v_pk_add_f32 v[18:19], v[18:19], v[18:19] op_sel:[0,1] op_sel_hi:[1,0]
	v_mov_b32_e32 v17, v20
	v_mov_b32_e32 v19, v21
	v_pk_add_f32 v[16:17], v[16:17], v[18:19]
	v_mul_f32_e32 v18, v5, v5
	v_mul_f32_e32 v20, v7, v7
	v_mul_f32_e32 v22, v2, v2
	v_mul_f32_e32 v23, v3, v3
	v_pk_fma_f32 v[18:19], v[4:5], v[4:5], v[18:19] op_sel_hi:[1,1,0]
	v_pk_fma_f32 v[20:21], v[6:7], v[6:7], v[20:21] op_sel_hi:[1,1,0]
	v_mov_b32_e32 v19, v22
	v_mov_b32_e32 v21, v23
	v_pk_add_f32 v[18:19], v[18:19], v[20:21]
	s_nop 0
	v_pk_add_f32 v[16:17], v[16:17], v[18:19]
	s_nop 0
	v_add_f32_e32 v16, v16, v17
	v_mov_b32_e32 v17, v16
	s_nop 1
	v_permlane16_swap_b32_e32 v16, v17
	s_waitcnt lgkmcnt(0)
	v_add_f32_e32 v16, v16, v17
	v_mov_b32_e32 v17, v16
	s_nop 1
	v_permlane32_swap_b32_e32 v16, v17
	v_add_f32_e32 v16, v16, v17
	v_fmamk_f32 v16, v16, 0x3c800000, v173
	v_mul_f32_e32 v17, 0x4b800000, v16
	v_cmp_gt_f32_e32 vcc, s62, v16
	s_nop 1
	v_cndmask_b32_e32 v16, v16, v17, vcc
	v_rsq_f32_e32 v16, v16
	s_nop 0
	v_mul_f32_e32 v17, 0x45800000, v16
	v_cndmask_b32_e32 v16, v16, v17, vcc
	v_pk_mul_f32 v[12:13], v[12:13], v[16:17] op_sel_hi:[1,0]
	v_pk_mul_f32 v[14:15], v[14:15], v[16:17] op_sel_hi:[1,0]
	v_pk_mul_f32 v[8:9], v[8:9], v[16:17] op_sel_hi:[1,0]
	v_pk_mul_f32 v[10:11], v[10:11], v[16:17] op_sel_hi:[1,0]
	v_pk_mul_f32 v[4:5], v[4:5], v[16:17] op_sel_hi:[1,0]
	v_pk_mul_f32 v[6:7], v[6:7], v[16:17] op_sel_hi:[1,0]
	v_pk_mul_f32 v[0:1], v[0:1], v[16:17] op_sel_hi:[1,0]
	v_pk_mul_f32 v[2:3], v[2:3], v[16:17] op_sel_hi:[1,0]
	s_waitcnt vmcnt(0)
	v_pk_mul_f32 v[14:15], v[102:103], v[14:15]
	v_pk_mul_f32 v[12:13], v[100:101], v[12:13]
	v_pk_mul_f32 v[10:11], v[98:99], v[10:11]
	v_pk_mul_f32 v[8:9], v[96:97], v[8:9]
	v_pk_mul_f32 v[6:7], v[110:111], v[6:7]
	v_pk_mul_f32 v[4:5], v[108:109], v[4:5]
	v_pk_mul_f32 v[2:3], v[106:107], v[2:3]
	v_pk_mul_f32 v[0:1], v[104:105], v[0:1]

;     __device__ __forceinline__ void operator()(const f32x4 (&acc)[2][2][4][2], const Unit& u, int wr, int wc, int fr, int fq) const {
;     ...
;                 f32x4 v[2][2]; float ss = 0.f;
; #pragma unroll
;                 for (int bj = 0; bj < 2; ++bj)
; #pragma unroll
;                     for (int n = 0; n < 2; ++n) { v[bj][n] = acc[ai][bj][m][n] * rs; const f32x4 x = v[bj][n]; ss += (x[0] * x[0] + x[1] * x[1]) + (x[2] * x[2] + x[3] * x[3]); }
;                 if (nrm) { ss = bfly_add<16>(ss); ss = bfly_add<32>(ss); const float r2 = rsqrtf(ss * (1.f / 64.f) + EPS);
; #pragma unroll
;                     for (int bj = 0; bj < 2; ++bj)
; #pragma unroll
;                         for (int n = 0; n < 2; ++n) v[bj][n] = v[bj][n] * r2 * gv[bj][n]; }
.LBB0_222:
	v_pk_mul_f32 v[168:169], v[142:143], v[142:143]
	v_pk_mul_f32 v[178:179], v[140:141], v[140:141]
	v_mul_f32_e32 v144, v128, v128
	v_pk_mov_b32 v[180:181], v[178:179], v[168:169] op_sel:[1,0]
	v_mov_b32_e32 v179, v169
	v_pk_add_f32 v[168:169], v[180:181], v[178:179]
	v_pk_mul_f32 v[178:179], v[138:139], v[138:139]
	v_pk_mul_f32 v[180:181], v[136:137], v[136:137]
	v_mul_f32_e32 v172, v129, v129
	v_pk_mov_b32 v[186:187], v[180:181], v[178:179] op_sel:[1,0]
	v_mov_b32_e32 v181, v179
	v_pk_add_f32 v[178:179], v[186:187], v[180:181]
	v_pk_add_f32 v[168:169], v[168:169], v[168:169] op_sel:[0,1] op_sel_hi:[1,0]
	v_pk_add_f32 v[178:179], v[178:179], v[178:179] op_sel:[0,1] op_sel_hi:[1,0]
	v_mov_b32_e32 v169, v144
	v_mov_b32_e32 v179, v172
	v_mul_f32_e32 v144, v133, v133
	v_pk_add_f32 v[168:169], v[168:169], v[178:179]
	v_pk_fma_f32 v[178:179], v[132:133], v[132:133], v[144:145] op_sel_hi:[1,1,0]
	v_mul_f32_e32 v144, v135, v135
	v_mul_f32_e32 v174, v130, v130
	v_mul_f32_e32 v176, v131, v131
	v_pk_fma_f32 v[180:181], v[134:135], v[134:135], v[144:145] op_sel_hi:[1,1,0]
	v_mov_b32_e32 v179, v174
	v_mov_b32_e32 v181, v176
	v_pk_add_f32 v[178:179], v[178:179], v[180:181]
	s_nop 0
	v_pk_add_f32 v[168:169], v[168:169], v[178:179]
	s_nop 0
	v_add_f32_e32 v144, v168, v169
	v_mov_b32_e32 v168, v144
	s_nop 1
	v_permlane16_swap_b32_e32 v144, v168
	s_waitcnt lgkmcnt(0)
	v_add_f32_e32 v144, v144, v168
	v_mov_b32_e32 v168, v144
	s_nop 1
	v_permlane32_swap_b32_e32 v144, v168
	v_add_f32_e32 v144, v144, v168
	v_fmamk_f32 v144, v144, 0x3c800000, v173
	v_mul_f32_e32 v168, 0x4b800000, v144
	v_cmp_gt_f32_e32 vcc, s62, v144
	s_nop 1
	v_cndmask_b32_e32 v144, v144, v168, vcc
	v_rsq_f32_e32 v144, v144
	s_nop 0
	v_mul_f32_e32 v168, 0x45800000, v144
	v_cndmask_b32_e32 v144, v144, v168, vcc
	v_pk_mul_f32 v[140:141], v[140:141], v[144:145] op_sel_hi:[1,0]
	v_pk_mul_f32 v[142:143], v[142:143], v[144:145] op_sel_hi:[1,0]
	v_pk_mul_f32 v[136:137], v[136:137], v[144:145] op_sel_hi:[1,0]
	v_pk_mul_f32 v[138:139], v[138:139], v[144:145] op_sel_hi:[1,0]
	v_pk_mul_f32 v[132:133], v[132:133], v[144:145] op_sel_hi:[1,0]
	v_pk_mul_f32 v[134:135], v[134:135], v[144:145] op_sel_hi:[1,0]
	v_pk_mul_f32 v[128:129], v[128:129], v[144:145] op_sel_hi:[1,0]
	v_pk_mul_f32 v[130:131], v[130:131], v[144:145] op_sel_hi:[1,0]
	s_waitcnt vmcnt(0)
	v_pk_mul_f32 v[142:143], v[102:103], v[142:143]
	v_pk_mul_f32 v[140:141], v[100:101], v[140:141]
	v_pk_mul_f32 v[138:139], v[98:99], v[138:139]
	v_pk_mul_f32 v[136:137], v[96:97], v[136:137]
	v_pk_mul_f32 v[134:135], v[110:111], v[134:135]
	v_pk_mul_f32 v[132:133], v[108:109], v[132:133]
	v_pk_mul_f32 v[130:131], v[106:107], v[130:131]
	v_pk_mul_f32 v[128:129], v[104:105], v[128:129]
	s_branch .LBB0_204

; __device__ __forceinline__ float wave_sum(float v) { v = bfly_add<1>(v); v = bfly_add<2>(v); v = bfly_add<4>(v); v = bfly_add<8>(v); v = bfly_add<16>(v); v = bfly_add<32>(v); return v; }
; __global__ void __launch_bounds__(NTHREADS, 2) hymba_fwd(Args args) {
;     ...
;             if (wave == 0) { const float a = wave_sum(ap_->in[I_LQ1][l * 64 + lane] * ap_->in[I_LK1][l * 64 + lane]), b = wave_sum(ap_->in[I_LQ2][l * 64 + lane] * ap_->in[I_LK2][l * 64 + lane]);
;                 const float lam_init = 0.8f - 0.6f * expf(-0.3f * (float)l); if (lane == 0) { misc[0] = expf(a) - expf(b) + lam_init; misc[1] = 1.f - lam_init; }
.LBB0_293:
	s_or_b64 exec, exec, s[6:7]
	v_readlane_b32 s4, v254, 8
	v_readlane_b32 s5, v254, 9
	s_and_b64 vcc, exec, s[4:5]
	s_cbranch_vccz .LBB0_305
	s_waitcnt lgkmcnt(0)
	s_load_dwordx8 s[4:11], s[2:3], 0x40
	v_and_b32_e32 v0, 63, v0
	v_readlane_b32 s12, v255, 4
	v_cmp_eq_u32_e32 vcc, 0, v0
	v_readlane_b32 s13, v255, 5
	v_lshl_or_b32 v144, s12, 6, v0
	v_lshlrev_b64 v[2:3], 2, v[144:145]
	s_waitcnt lgkmcnt(0)
	v_lshl_add_u64 v[4:5], s[4:5], 0, v[2:3]
	global_load_dword v1, v[4:5], off
	v_lshl_add_u64 v[4:5], s[6:7], 0, v[2:3]
	global_load_dword v4, v[4:5], off
	v_lshl_add_u64 v[6:7], s[8:9], 0, v[2:3]
	s_waitcnt vmcnt(0)
	v_mul_f32_e32 v5, v1, v4
	ds_swizzle_b32 v5, v5 offset:swizzle(SWAP,1)
	s_waitcnt lgkmcnt(0)
	v_fmac_f32_e32 v5, v1, v4
	ds_swizzle_b32 v1, v5 offset:swizzle(SWAP,2)
	s_waitcnt lgkmcnt(0)
	v_add_f32_e32 v1, v5, v1
	global_load_dword v5, v[6:7], off
	v_lshl_add_u64 v[6:7], s[10:11], 0, v[2:3]
	global_load_dword v6, v[6:7], off
	ds_swizzle_b32 v4, v1 offset:swizzle(SWAP,4)
	s_waitcnt lgkmcnt(0)
	v_add_f32_e32 v1, v1, v4
	ds_swizzle_b32 v4, v1 offset:swizzle(SWAP,8)
	s_waitcnt lgkmcnt(0)
	v_add_f32_e32 v1, v1, v4
	v_mov_b32_e32 v4, v1
	s_nop 1
	v_permlane16_swap_b32_e32 v1, v4
	s_waitcnt lgkmcnt(0)
	v_add_f32_e32 v1, v1, v4
	v_mov_b32_e32 v4, v1
	s_nop 1
	v_permlane32_swap_b32_e32 v1, v4
	s_waitcnt vmcnt(0)
	v_mul_f32_e32 v7, v5, v6
	ds_swizzle_b32 v7, v7 offset:swizzle(SWAP,1)
	s_waitcnt lgkmcnt(0)
	v_fmac_f32_e32 v7, v5, v6
	ds_swizzle_b32 v5, v7 offset:swizzle(SWAP,2)
	s_waitcnt lgkmcnt(0)
	v_add_f32_e32 v5, v7, v5
	ds_swizzle_b32 v6, v5 offset:swizzle(SWAP,4)
	s_waitcnt lgkmcnt(0)
	v_add_f32_e32 v5, v5, v6
	ds_swizzle_b32 v6, v5 offset:swizzle(SWAP,8)
	s_waitcnt lgkmcnt(0)
	v_add_f32_e32 v5, v5, v6
	v_mov_b32_e32 v6, v5
	s_nop 1
	v_permlane16_swap_b32_e32 v5, v6
	s_waitcnt lgkmcnt(0)
	v_add_f32_e32 v5, v5, v6
	v_mov_b32_e32 v6, v5
	s_nop 1
	v_permlane32_swap_b32_e32 v5, v6
	s_and_saveexec_b64 s[6:7], vcc
	s_cbranch_execz .LBB0_296
	v_readlane_b32 s4, v255, 4
	v_add_f32_e32 v1, v1, v4
	v_mul_f32_e32 v4, 0x3fb8aa3b, v1
	v_cvt_f32_u32_e32 v7, s4
	v_readlane_b32 s5, v255, 5
	s_mov_b32 s1, 0xc2ce8ed0
	s_mov_b32 s8, 0x42b17218
	v_mul_f32_e32 v7, 0xbe99999a, v7
	v_mul_f32_e32 v8, 0x3fb8aa3b, v7
	v_fma_f32 v9, v7, s36, -v8
	v_rndne_f32_e32 v10, v8
	v_fmac_f32_e32 v9, 0x32a5705f, v7
	v_sub_f32_e32 v8, v8, v10
	v_add_f32_e32 v8, v8, v9
	v_cvt_i32_f32_e32 v10, v10
	v_exp_f32_e32 v8, v8
	v_fma_f32 v9, v1, s36, -v4
	v_fmac_f32_e32 v9, 0x32a5705f, v1
	v_cmp_ngt_f32_e64 s[4:5], s1, v7
	v_ldexp_f32 v8, v8, v10
	v_rndne_f32_e32 v10, v4
	v_sub_f32_e32 v4, v4, v10
	v_add_f32_e32 v4, v4, v9
	v_exp_f32_e32 v4, v4
	v_cvt_i32_f32_e32 v9, v10
	v_cndmask_b32_e64 v8, 0, v8, s[4:5]
	v_cmp_nlt_f32_e64 s[4:5], s8, v7
	v_mov_b32_e32 v10, 0x7f800000
	v_add_f32_e32 v5, v5, v6
	v_cndmask_b32_e64 v7, v10, v8, s[4:5]
	v_mov_b32_e32 v6, 0x3f4ccccd
	v_fmamk_f32 v6, v7, 0xbf19999a, v6
	v_mul_f32_e32 v7, 0x3fb8aa3b, v5
	v_ldexp_f32 v4, v4, v9
	v_fma_f32 v8, v5, s36, -v7
	v_rndne_f32_e32 v9, v7
	v_fmac_f32_e32 v8, 0x32a5705f, v5
	v_sub_f32_e32 v7, v7, v9
	v_add_f32_e32 v7, v7, v8
	v_exp_f32_e32 v7, v7
	v_cvt_i32_f32_e32 v8, v9
	v_cmp_ngt_f32_e64 s[4:5], s1, v1
	s_nop 1
	v_cndmask_b32_e64 v4, 0, v4, s[4:5]
	v_cmp_nlt_f32_e64 s[4:5], s8, v1
	s_nop 1
	v_cndmask_b32_e64 v1, v10, v4, s[4:5]
	v_ldexp_f32 v4, v7, v8
	v_cmp_ngt_f32_e64 s[4:5], s1, v5
	s_add_i32 s1, 0, 0x1c000
	s_nop 0
	v_cndmask_b32_e64 v4, 0, v4, s[4:5]
	v_cmp_nlt_f32_e64 s[4:5], s8, v5
	v_sub_f32_e32 v5, 1.0, v6
	s_nop 0
	v_cndmask_b32_e64 v4, v10, v4, s[4:5]
	v_sub_f32_e32 v1, v1, v4
	v_add_f32_e32 v4, v6, v1
	v_mov_b32_e32 v1, s1
	ds_write_b64 v1, v[4:5]

; __device__ __forceinline__ unsigned cvtpk(float lo, float hi) { f32x2 v = {lo, hi}; bf16x2_t b = __builtin_convertvector(v, bf16x2_t); return __builtin_bit_cast(unsigned, b); }
;     __device__ __forceinline__ void operator()(const f32x4 (&acc)[2][2][4][2], const Unit& u, int wr, int wc, int fr, int fq) const {
;     ...
;                 const int row = u.pm * BM + ai * HALF + wr * 64 + m * 16 + fr;
;                 float ss = 0.f;
; #pragma unroll
;                 for (int bj = 0; bj < 2; ++bj) { const int col = u.pn * BM + bj * HALF + wc * 32 + 8 * fq;
;                     f32x4 v0, v1;
;                     if (xin_p) { const float* xr = (row < MP ? xin_p + (size_t)row * DM : xin_s + (size_t)(row - MP) * DM) + col; v0 = *(const f32x4*)xr; v1 = *(const f32x4*)(xr + 4); }
;                     else { const u32x4 w = *(const u32x4*)(XR + (size_t)row * DM + col);
;                         v0 = (f32x4){__uint_as_float(w.x << 16), __uint_as_float(w.x & 0xffff0000u), __uint_as_float(w.y << 16), __uint_as_float(w.y & 0xffff0000u)};
;                         v1 = (f32x4){__uint_as_float(w.z << 16), __uint_as_float(w.z & 0xffff0000u), __uint_as_float(w.w << 16), __uint_as_float(w.w & 0xffff0000u)}; }
;                     v0 = v0 + acc[ai][bj][m][0]; v1 = v1 + acc[ai][bj][m][1];
;                     if (fout) { *(f32x4*)(fout + (size_t)row * DM + col) = v0; *(f32x4*)(fout + (size_t)row * DM + col + 4) = v1; }
;                     else { u32x4 w; w.x = cvtpk(v0[0], v0[1]); w.y = cvtpk(v0[2], v0[3]); w.z = cvtpk(v1[0], v1[1]); w.w = cvtpk(v1[2], v1[3]); *(u32x4*)(XR + (size_t)row * DM + col) = w; }
;                     if (PS) ss += (v0[0] * v0[0] + v0[1] * v0[1]) + (v0[2] * v0[2] + v0[3] * v0[3]) + (v1[0] * v1[0] + v1[1] * v1[1]) + (v1[2] * v1[2] + v1[3] * v1[3]); }
;                 if (PS) { ss = bfly_add<16>(ss); ss = bfly_add<32>(ss); if (fq == 0) PS[(size_t)row * 16 + 4 * u.pn + wc] = ss; }
.LBB0_700:
	v_lshl_add_u32 v140, s43, 8, v152
	v_ashrrev_i32_e32 v141, 31, v140
	v_lshl_or_b32 v138, s33, 8, v154
	v_lshlrev_b64 v[142:143], 11, v[140:141]
	v_lshl_add_u64 v[142:143], s[10:11], 0, v[142:143]
	v_ashrrev_i32_e32 v139, 31, v138
	v_lshl_add_u64 v[142:143], v[138:139], 1, v[142:143]
	global_load_dwordx4 v[156:159], v[142:143], off
	s_lshl_b32 s24, s33, 2
	s_ashr_i32 s25, s24, 31
	s_waitcnt vmcnt(0)
	v_lshlrev_b32_e32 v160, 16, v156
	v_and_b32_e32 v161, 0xffff0000, v156
	v_lshlrev_b32_e32 v156, 16, v157
	v_and_b32_e32 v157, 0xffff0000, v157
	v_lshlrev_b32_e32 v162, 16, v158
	v_and_b32_e32 v163, 0xffff0000, v158
	v_lshlrev_b32_e32 v158, 16, v159
	v_and_b32_e32 v159, 0xffff0000, v159
	v_pk_add_f32 v[126:127], v[126:127], v[156:157]
	v_pk_add_f32 v[124:125], v[124:125], v[160:161]
	v_pk_add_f32 v[156:157], v[122:123], v[158:159]
	v_pk_add_f32 v[158:159], v[120:121], v[162:163]
	v_cvt_pk_bf16_f32 v120, v124, v125
	v_cvt_pk_bf16_f32 v121, v126, v127
	v_cvt_pk_bf16_f32 v122, v158, v159
	v_cvt_pk_bf16_f32 v123, v156, v157
	global_store_dwordx4 v[142:143], v[120:123], off
	s_nop 1
	v_mul_f32_e32 v120, v125, v125
	v_mul_f32_e32 v121, v127, v127
	v_fmac_f32_e32 v120, v124, v124
	v_fmac_f32_e32 v121, v126, v126
	v_add_f32_e32 v120, v120, v121
	v_mul_f32_e32 v121, v159, v159
	v_fmac_f32_e32 v121, v158, v158
	v_add_f32_e32 v120, v121, v120
	v_mul_f32_e32 v121, v157, v157
	v_fmac_f32_e32 v121, v156, v156
	v_add_f32_e32 v156, v121, v120
	global_load_dwordx4 v[120:123], v[142:143], off offset:256
	s_waitcnt vmcnt(0)
	v_lshlrev_b32_e32 v124, 16, v120
	v_and_b32_e32 v125, 0xffff0000, v120
	v_lshlrev_b32_e32 v120, 16, v121
	v_and_b32_e32 v121, 0xffff0000, v121
	v_lshlrev_b32_e32 v126, 16, v122
	v_and_b32_e32 v127, 0xffff0000, v122
	v_lshlrev_b32_e32 v122, 16, v123
	v_and_b32_e32 v123, 0xffff0000, v123
	v_pk_add_f32 v[118:119], v[118:119], v[120:121]
	v_pk_add_f32 v[116:117], v[116:117], v[124:125]
	v_pk_add_f32 v[120:121], v[114:115], v[122:123]
	v_pk_add_f32 v[122:123], v[112:113], v[126:127]
	v_cvt_pk_bf16_f32 v112, v116, v117
	v_cvt_pk_bf16_f32 v113, v118, v119
	v_cvt_pk_bf16_f32 v114, v122, v123
	v_cvt_pk_bf16_f32 v115, v120, v121
	global_store_dwordx4 v[142:143], v[112:115], off offset:256
	s_nop 1
	v_mul_f32_e32 v112, v117, v117
	v_mul_f32_e32 v113, v119, v119
	v_fmac_f32_e32 v112, v116, v116
	v_fmac_f32_e32 v113, v118, v118
	v_add_f32_e32 v112, v112, v113
	v_mul_f32_e32 v113, v123, v123
	v_fmac_f32_e32 v113, v122, v122
	v_add_f32_e32 v112, v113, v112
	v_mul_f32_e32 v113, v121, v121
	v_fmac_f32_e32 v113, v120, v120
	v_add_f32_e32 v112, v113, v112
	v_add_f32_e32 v112, v156, v112
	v_mov_b32_e32 v113, v112
	s_nop 1
	v_permlane16_swap_b32_e32 v112, v113
	s_waitcnt lgkmcnt(0)
	v_add_f32_e32 v112, v112, v113
	v_mov_b32_e32 v113, v112
	s_nop 1
	v_permlane32_swap_b32_e32 v112, v113
	s_and_saveexec_b64 s[26:27], s[4:5]
	s_cbranch_execz .LBB0_702
	v_lshlrev_b64 v[114:115], 6, v[140:141]
	v_lshl_add_u64 v[114:115], s[12:13], 0, v[114:115]
	v_lshl_add_u64 v[114:115], s[24:25], 2, v[114:115]
	s_lshl_b32 s84, s39, 2
	v_lshl_add_u64 v[114:115], v[114:115], 0, s[84:85]
	v_add_f32_e32 v112, v112, v113
	global_store_dword v[114:115], v112, off
.LBB0_702:
	s_or_b64 exec, exec, s[26:27]
	v_or_b32_e32 v112, 16, v140
	v_ashrrev_i32_e32 v113, 31, v112
	v_lshlrev_b64 v[114:115], 11, v[112:113]
	v_lshl_add_u64 v[114:115], s[10:11], 0, v[114:115]
	v_lshl_add_u64 v[114:115], v[138:139], 1, v[114:115]
	global_load_dwordx4 v[116:119], v[114:115], off
	s_waitcnt vmcnt(0)
	v_lshlrev_b32_e32 v120, 16, v116
	v_and_b32_e32 v121, 0xffff0000, v116
	v_lshlrev_b32_e32 v116, 16, v117
	v_and_b32_e32 v117, 0xffff0000, v117
	v_lshlrev_b32_e32 v122, 16, v118
	v_and_b32_e32 v123, 0xffff0000, v118
	v_lshlrev_b32_e32 v118, 16, v119
	v_and_b32_e32 v119, 0xffff0000, v119
	v_pk_add_f32 v[110:111], v[110:111], v[116:117]
	v_pk_add_f32 v[108:109], v[108:109], v[120:121]
	v_pk_add_f32 v[116:117], v[106:107], v[118:119]
	v_pk_add_f32 v[118:119], v[104:105], v[122:123]
	v_cvt_pk_bf16_f32 v104, v108, v109
	v_cvt_pk_bf16_f32 v105, v110, v111
	v_cvt_pk_bf16_f32 v106, v118, v119
	v_cvt_pk_bf16_f32 v107, v116, v117
	global_store_dwordx4 v[114:115], v[104:107], off
	s_nop 1
	v_mul_f32_e32 v104, v109, v109
	v_mul_f32_e32 v105, v111, v111
	v_fmac_f32_e32 v104, v108, v108
	v_fmac_f32_e32 v105, v110, v110
	v_add_f32_e32 v104, v104, v105
	v_mul_f32_e32 v105, v119, v119
	v_fmac_f32_e32 v105, v118, v118
	v_add_f32_e32 v104, v105, v104
	v_mul_f32_e32 v105, v117, v117
	v_fmac_f32_e32 v105, v116, v116
	v_add_f32_e32 v116, v105, v104
	global_load_dwordx4 v[104:107], v[114:115], off offset:256
	s_waitcnt vmcnt(0)
	v_lshlrev_b32_e32 v108, 16, v104
	v_and_b32_e32 v109, 0xffff0000, v104
	v_lshlrev_b32_e32 v104, 16, v105
	v_and_b32_e32 v105, 0xffff0000, v105
	v_lshlrev_b32_e32 v110, 16, v106
	v_and_b32_e32 v111, 0xffff0000, v106
	v_lshlrev_b32_e32 v106, 16, v107
	v_and_b32_e32 v107, 0xffff0000, v107
	v_pk_add_f32 v[102:103], v[102:103], v[104:105]
	v_pk_add_f32 v[100:101], v[100:101], v[108:109]
	v_pk_add_f32 v[104:105], v[98:99], v[106:107]
	v_pk_add_f32 v[106:107], v[96:97], v[110:111]
	v_cvt_pk_bf16_f32 v96, v100, v101
	v_cvt_pk_bf16_f32 v97, v102, v103
	v_cvt_pk_bf16_f32 v98, v106, v107
	v_cvt_pk_bf16_f32 v99, v104, v105
	global_store_dwordx4 v[114:115], v[96:99], off offset:256
	s_nop 1
	v_mul_f32_e32 v96, v101, v101
	v_mul_f32_e32 v97, v103, v103
	v_fmac_f32_e32 v96, v100, v100
	v_fmac_f32_e32 v97, v102, v102
	v_add_f32_e32 v96, v96, v97
	v_mul_f32_e32 v97, v107, v107
	v_fmac_f32_e32 v97, v106, v106
	v_add_f32_e32 v96, v97, v96
	v_mul_f32_e32 v97, v105, v105
	v_fmac_f32_e32 v97, v104, v104
	v_add_f32_e32 v96, v97, v96
	v_add_f32_e32 v96, v116, v96
	v_mov_b32_e32 v97, v96
	s_nop 1
	v_permlane16_swap_b32_e32 v96, v97
	s_waitcnt lgkmcnt(0)
	v_add_f32_e32 v96, v96, v97
	v_mov_b32_e32 v97, v96
	s_nop 1
	v_permlane32_swap_b32_e32 v96, v97
	s_and_saveexec_b64 s[26:27], s[4:5]
	s_cbranch_execz .LBB0_704
	v_lshlrev_b64 v[98:99], 6, v[112:113]
	v_lshl_add_u64 v[98:99], s[12:13], 0, v[98:99]
	v_lshl_add_u64 v[98:99], s[24:25], 2, v[98:99]
	s_lshl_b32 s84, s39, 2
	v_lshl_add_u64 v[98:99], v[98:99], 0, s[84:85]
	v_add_f32_e32 v96, v96, v97
	global_store_dword v[98:99], v96, off
; __device__ __forceinline__ unsigned cvtpk(float lo, float hi) { f32x2 v = {lo, hi}; bf16x2_t b = __builtin_convertvector(v, bf16x2_t); return __builtin_bit_cast(unsigned, b); }
;     __device__ __forceinline__ void operator()(const f32x4 (&acc)[2][2][4][2], const Unit& u, int wr, int wc, int fr, int fq) const {
;     ...
;                 const int row = u.pm * BM + ai * HALF + wr * 64 + m * 16 + fr;
;                 float ss = 0.f;
; #pragma unroll
;                 for (int bj = 0; bj < 2; ++bj) { const int col = u.pn * BM + bj * HALF + wc * 32 + 8 * fq;
;                     f32x4 v0, v1;
;                     if (xin_p) { const float* xr = (row < MP ? xin_p + (size_t)row * DM : xin_s + (size_t)(row - MP) * DM) + col; v0 = *(const f32x4*)xr; v1 = *(const f32x4*)(xr + 4); }
;                     else { const u32x4 w = *(const u32x4*)(XR + (size_t)row * DM + col);
;                         v0 = (f32x4){__uint_as_float(w.x << 16), __uint_as_float(w.x & 0xffff0000u), __uint_as_float(w.y << 16), __uint_as_float(w.y & 0xffff0000u)};
;                         v1 = (f32x4){__uint_as_float(w.z << 16), __uint_as_float(w.z & 0xffff0000u), __uint_as_float(w.w << 16), __uint_as_float(w.w & 0xffff0000u)}; }
;                     v0 = v0 + acc[ai][bj][m][0]; v1 = v1 + acc[ai][bj][m][1];
;                     if (fout) { *(f32x4*)(fout + (size_t)row * DM + col) = v0; *(f32x4*)(fout + (size_t)row * DM + col + 4) = v1; }
;                     else { u32x4 w; w.x = cvtpk(v0[0], v0[1]); w.y = cvtpk(v0[2], v0[3]); w.z = cvtpk(v1[0], v1[1]); w.w = cvtpk(v1[2], v1[3]); *(u32x4*)(XR + (size_t)row * DM + col) = w; }
;                     if (PS) ss += (v0[0] * v0[0] + v0[1] * v0[1]) + (v0[2] * v0[2] + v0[3] * v0[3]) + (v1[0] * v1[0] + v1[1] * v1[1]) + (v1[2] * v1[2] + v1[3] * v1[3]); }
;                 if (PS) { ss = bfly_add<16>(ss); ss = bfly_add<32>(ss); if (fq == 0) PS[(size_t)row * 16 + 4 * u.pn + wc] = ss; }
.LBB0_704:
	s_or_b64 exec, exec, s[26:27]
	v_or_b32_e32 v96, 32, v140
	v_ashrrev_i32_e32 v97, 31, v96
	v_lshlrev_b64 v[98:99], 11, v[96:97]
	v_lshl_add_u64 v[98:99], s[10:11], 0, v[98:99]
	v_lshl_add_u64 v[98:99], v[138:139], 1, v[98:99]
	global_load_dwordx4 v[100:103], v[98:99], off
	s_waitcnt vmcnt(0)
	v_lshlrev_b32_e32 v104, 16, v100
	v_and_b32_e32 v105, 0xffff0000, v100
	v_lshlrev_b32_e32 v100, 16, v101
	v_and_b32_e32 v101, 0xffff0000, v101
	v_lshlrev_b32_e32 v106, 16, v102
	v_and_b32_e32 v107, 0xffff0000, v102
	v_lshlrev_b32_e32 v102, 16, v103
	v_and_b32_e32 v103, 0xffff0000, v103
	v_pk_add_f32 v[94:95], v[94:95], v[100:101]
	v_pk_add_f32 v[92:93], v[92:93], v[104:105]
	v_pk_add_f32 v[100:101], v[90:91], v[102:103]
	v_pk_add_f32 v[102:103], v[88:89], v[106:107]
	v_cvt_pk_bf16_f32 v88, v92, v93
	v_cvt_pk_bf16_f32 v89, v94, v95
	v_cvt_pk_bf16_f32 v90, v102, v103
	v_cvt_pk_bf16_f32 v91, v100, v101
	global_store_dwordx4 v[98:99], v[88:91], off
	s_nop 1
	v_mul_f32_e32 v88, v93, v93
	v_mul_f32_e32 v89, v95, v95
	v_fmac_f32_e32 v88, v92, v92
	v_fmac_f32_e32 v89, v94, v94
	v_add_f32_e32 v88, v88, v89
	v_mul_f32_e32 v89, v103, v103
	v_fmac_f32_e32 v89, v102, v102
	v_add_f32_e32 v88, v89, v88
	v_mul_f32_e32 v89, v101, v101
	v_fmac_f32_e32 v89, v100, v100
	v_add_f32_e32 v100, v89, v88
	global_load_dwordx4 v[88:91], v[98:99], off offset:256
	s_waitcnt vmcnt(0)
	v_lshlrev_b32_e32 v92, 16, v88
	v_and_b32_e32 v93, 0xffff0000, v88
	v_lshlrev_b32_e32 v88, 16, v89
	v_and_b32_e32 v89, 0xffff0000, v89
	v_lshlrev_b32_e32 v94, 16, v90
	v_and_b32_e32 v95, 0xffff0000, v90
	v_lshlrev_b32_e32 v90, 16, v91
	v_and_b32_e32 v91, 0xffff0000, v91
	v_pk_add_f32 v[86:87], v[86:87], v[88:89]
	v_pk_add_f32 v[84:85], v[84:85], v[92:93]
	v_pk_add_f32 v[88:89], v[82:83], v[90:91]
	v_pk_add_f32 v[90:91], v[80:81], v[94:95]
	v_cvt_pk_bf16_f32 v80, v84, v85
	v_cvt_pk_bf16_f32 v81, v86, v87
	v_cvt_pk_bf16_f32 v82, v90, v91
	v_cvt_pk_bf16_f32 v83, v88, v89
	global_store_dwordx4 v[98:99], v[80:83], off offset:256
	s_nop 1
	v_mul_f32_e32 v80, v85, v85
	v_mul_f32_e32 v81, v87, v87
	v_fmac_f32_e32 v80, v84, v84
	v_fmac_f32_e32 v81, v86, v86
	v_add_f32_e32 v80, v80, v81
	v_mul_f32_e32 v81, v91, v91
	v_fmac_f32_e32 v81, v90, v90
	v_add_f32_e32 v80, v81, v80
	v_mul_f32_e32 v81, v89, v89
	v_fmac_f32_e32 v81, v88, v88
	v_add_f32_e32 v80, v81, v80
	v_add_f32_e32 v80, v100, v80
	v_mov_b32_e32 v81, v80
	s_nop 1
	v_permlane16_swap_b32_e32 v80, v81
	s_waitcnt lgkmcnt(0)
	v_add_f32_e32 v80, v80, v81
	v_mov_b32_e32 v81, v80
	s_nop 1
	v_permlane32_swap_b32_e32 v80, v81
	s_and_saveexec_b64 s[26:27], s[4:5]
	s_cbranch_execz .LBB0_706
	v_lshlrev_b64 v[82:83], 6, v[96:97]
	v_lshl_add_u64 v[82:83], s[12:13], 0, v[82:83]
	v_lshl_add_u64 v[82:83], s[24:25], 2, v[82:83]
	s_lshl_b32 s84, s39, 2
	v_lshl_add_u64 v[82:83], v[82:83], 0, s[84:85]
	v_add_f32_e32 v80, v80, v81
	global_store_dword v[82:83], v80, off
.LBB0_706:
	s_or_b64 exec, exec, s[26:27]
	v_or_b32_e32 v80, 48, v140
	v_ashrrev_i32_e32 v81, 31, v80
	v_lshlrev_b64 v[82:83], 11, v[80:81]
	v_lshl_add_u64 v[82:83], s[10:11], 0, v[82:83]
	v_lshl_add_u64 v[82:83], v[138:139], 1, v[82:83]
	global_load_dwordx4 v[84:87], v[82:83], off
	s_waitcnt vmcnt(0)
	v_lshlrev_b32_e32 v88, 16, v84
	v_and_b32_e32 v89, 0xffff0000, v84
	v_lshlrev_b32_e32 v84, 16, v85
	v_and_b32_e32 v85, 0xffff0000, v85
	v_lshlrev_b32_e32 v90, 16, v86
	v_and_b32_e32 v91, 0xffff0000, v86
	v_lshlrev_b32_e32 v86, 16, v87
	v_and_b32_e32 v87, 0xffff0000, v87
	v_pk_add_f32 v[78:79], v[78:79], v[84:85]
	v_pk_add_f32 v[76:77], v[76:77], v[88:89]
	v_pk_add_f32 v[84:85], v[74:75], v[86:87]
	v_pk_add_f32 v[86:87], v[72:73], v[90:91]
	v_cvt_pk_bf16_f32 v72, v76, v77
	v_cvt_pk_bf16_f32 v73, v78, v79
	v_cvt_pk_bf16_f32 v74, v86, v87
	v_cvt_pk_bf16_f32 v75, v84, v85
	global_store_dwordx4 v[82:83], v[72:75], off
	s_nop 1
	v_mul_f32_e32 v72, v77, v77
	v_mul_f32_e32 v73, v79, v79
	v_fmac_f32_e32 v72, v76, v76
	v_fmac_f32_e32 v73, v78, v78
	v_add_f32_e32 v72, v72, v73
	v_mul_f32_e32 v73, v87, v87
	v_fmac_f32_e32 v73, v86, v86
	v_add_f32_e32 v72, v73, v72
	v_mul_f32_e32 v73, v85, v85
	v_fmac_f32_e32 v73, v84, v84
	v_add_f32_e32 v84, v73, v72
	global_load_dwordx4 v[72:75], v[82:83], off offset:256
	s_waitcnt vmcnt(0)
	v_lshlrev_b32_e32 v76, 16, v72
	v_and_b32_e32 v77, 0xffff0000, v72
	v_lshlrev_b32_e32 v72, 16, v73
	v_and_b32_e32 v73, 0xffff0000, v73
	v_lshlrev_b32_e32 v78, 16, v74
	v_and_b32_e32 v79, 0xffff0000, v74
	v_lshlrev_b32_e32 v74, 16, v75
	v_and_b32_e32 v75, 0xffff0000, v75
	v_pk_add_f32 v[70:71], v[70:71], v[72:73]
	v_pk_add_f32 v[68:69], v[68:69], v[76:77]
	v_pk_add_f32 v[72:73], v[66:67], v[74:75]
	v_pk_add_f32 v[74:75], v[64:65], v[78:79]
	v_cvt_pk_bf16_f32 v64, v68, v69
	v_cvt_pk_bf16_f32 v65, v70, v71
	v_cvt_pk_bf16_f32 v66, v74, v75
	v_cvt_pk_bf16_f32 v67, v72, v73
	global_store_dwordx4 v[82:83], v[64:67], off offset:256
	s_nop 1
	v_mul_f32_e32 v64, v69, v69
	v_mul_f32_e32 v65, v71, v71
	v_fmac_f32_e32 v64, v68, v68
	v_fmac_f32_e32 v65, v70, v70
	v_add_f32_e32 v64, v64, v65
	v_mul_f32_e32 v65, v75, v75
	v_fmac_f32_e32 v65, v74, v74
	v_add_f32_e32 v64, v65, v64
	v_mul_f32_e32 v65, v73, v73
	v_fmac_f32_e32 v65, v72, v72
	v_add_f32_e32 v64, v65, v64
	v_add_f32_e32 v64, v84, v64
	v_mov_b32_e32 v65, v64
	s_nop 1
	v_permlane16_swap_b32_e32 v64, v65
	s_waitcnt lgkmcnt(0)
	v_add_f32_e32 v64, v64, v65
	v_mov_b32_e32 v65, v64
	s_nop 1
	v_permlane32_swap_b32_e32 v64, v65
	s_and_saveexec_b64 s[26:27], s[4:5]
	s_cbranch_execz .LBB0_708
	v_lshlrev_b64 v[66:67], 6, v[80:81]
	v_lshl_add_u64 v[66:67], s[12:13], 0, v[66:67]
	v_lshl_add_u64 v[66:67], s[24:25], 2, v[66:67]
	s_lshl_b32 s84, s39, 2
	v_lshl_add_u64 v[66:67], v[66:67], 0, s[84:85]
	v_add_f32_e32 v64, v64, v65
	global_store_dword v[66:67], v64, off
; __device__ __forceinline__ unsigned cvtpk(float lo, float hi) { f32x2 v = {lo, hi}; bf16x2_t b = __builtin_convertvector(v, bf16x2_t); return __builtin_bit_cast(unsigned, b); }
;     __device__ __forceinline__ void operator()(const f32x4 (&acc)[2][2][4][2], const Unit& u, int wr, int wc, int fr, int fq) const {
;     ...
;                 const int row = u.pm * BM + ai * HALF + wr * 64 + m * 16 + fr;
;                 float ss = 0.f;
; #pragma unroll
;                 for (int bj = 0; bj < 2; ++bj) { const int col = u.pn * BM + bj * HALF + wc * 32 + 8 * fq;
;                     f32x4 v0, v1;
;                     if (xin_p) { const float* xr = (row < MP ? xin_p + (size_t)row * DM : xin_s + (size_t)(row - MP) * DM) + col; v0 = *(const f32x4*)xr; v1 = *(const f32x4*)(xr + 4); }
;                     else { const u32x4 w = *(const u32x4*)(XR + (size_t)row * DM + col);
;                         v0 = (f32x4){__uint_as_float(w.x << 16), __uint_as_float(w.x & 0xffff0000u), __uint_as_float(w.y << 16), __uint_as_float(w.y & 0xffff0000u)};
;                         v1 = (f32x4){__uint_as_float(w.z << 16), __uint_as_float(w.z & 0xffff0000u), __uint_as_float(w.w << 16), __uint_as_float(w.w & 0xffff0000u)}; }
;                     v0 = v0 + acc[ai][bj][m][0]; v1 = v1 + acc[ai][bj][m][1];
;                     if (fout) { *(f32x4*)(fout + (size_t)row * DM + col) = v0; *(f32x4*)(fout + (size_t)row * DM + col + 4) = v1; }
;                     else { u32x4 w; w.x = cvtpk(v0[0], v0[1]); w.y = cvtpk(v0[2], v0[3]); w.z = cvtpk(v1[0], v1[1]); w.w = cvtpk(v1[2], v1[3]); *(u32x4*)(XR + (size_t)row * DM + col) = w; }
;                     if (PS) ss += (v0[0] * v0[0] + v0[1] * v0[1]) + (v0[2] * v0[2] + v0[3] * v0[3]) + (v1[0] * v1[0] + v1[1] * v1[1]) + (v1[2] * v1[2] + v1[3] * v1[3]); }
;                 if (PS) { ss = bfly_add<16>(ss); ss = bfly_add<32>(ss); if (fq == 0) PS[(size_t)row * 16 + 4 * u.pn + wc] = ss; }
.LBB0_708:
	s_or_b64 exec, exec, s[26:27]
	v_add_u32_e32 v64, 0x80, v140
	v_ashrrev_i32_e32 v65, 31, v64
	v_lshlrev_b64 v[66:67], 11, v[64:65]
	v_lshl_add_u64 v[66:67], s[10:11], 0, v[66:67]
	v_lshl_add_u64 v[66:67], v[138:139], 1, v[66:67]
	global_load_dwordx4 v[68:71], v[66:67], off
	s_waitcnt vmcnt(0)
	v_lshlrev_b32_e32 v72, 16, v68
	v_and_b32_e32 v73, 0xffff0000, v68
	v_lshlrev_b32_e32 v68, 16, v69
	v_and_b32_e32 v69, 0xffff0000, v69
	v_lshlrev_b32_e32 v74, 16, v70
	v_and_b32_e32 v75, 0xffff0000, v70
	v_lshlrev_b32_e32 v70, 16, v71
	v_and_b32_e32 v71, 0xffff0000, v71
	v_pk_add_f32 v[62:63], v[62:63], v[68:69]
	v_pk_add_f32 v[60:61], v[60:61], v[72:73]
	v_pk_add_f32 v[68:69], v[58:59], v[70:71]
	v_pk_add_f32 v[70:71], v[56:57], v[74:75]
	v_cvt_pk_bf16_f32 v56, v60, v61
	v_cvt_pk_bf16_f32 v57, v62, v63
	v_cvt_pk_bf16_f32 v58, v70, v71
	v_cvt_pk_bf16_f32 v59, v68, v69
	global_store_dwordx4 v[66:67], v[56:59], off
	s_nop 1
	v_mul_f32_e32 v56, v61, v61
	v_mul_f32_e32 v57, v63, v63
	v_fmac_f32_e32 v56, v60, v60
	v_fmac_f32_e32 v57, v62, v62
	v_add_f32_e32 v56, v56, v57
	v_mul_f32_e32 v57, v71, v71
	v_fmac_f32_e32 v57, v70, v70
	v_add_f32_e32 v56, v57, v56
	v_mul_f32_e32 v57, v69, v69
	v_fmac_f32_e32 v57, v68, v68
	v_add_f32_e32 v68, v57, v56
	global_load_dwordx4 v[56:59], v[66:67], off offset:256
	s_waitcnt vmcnt(0)
	v_lshlrev_b32_e32 v60, 16, v56
	v_and_b32_e32 v61, 0xffff0000, v56
	v_lshlrev_b32_e32 v56, 16, v57
	v_and_b32_e32 v57, 0xffff0000, v57
	v_lshlrev_b32_e32 v62, 16, v58
	v_and_b32_e32 v63, 0xffff0000, v58
	v_lshlrev_b32_e32 v58, 16, v59
	v_and_b32_e32 v59, 0xffff0000, v59
	v_pk_add_f32 v[54:55], v[54:55], v[56:57]
	v_pk_add_f32 v[52:53], v[52:53], v[60:61]
	v_pk_add_f32 v[56:57], v[50:51], v[58:59]
	v_pk_add_f32 v[58:59], v[48:49], v[62:63]
	v_cvt_pk_bf16_f32 v48, v52, v53
	v_cvt_pk_bf16_f32 v49, v54, v55
	v_cvt_pk_bf16_f32 v50, v58, v59
	v_cvt_pk_bf16_f32 v51, v56, v57
	global_store_dwordx4 v[66:67], v[48:51], off offset:256
	s_nop 1
	v_mul_f32_e32 v48, v53, v53
	v_mul_f32_e32 v49, v55, v55
	v_fmac_f32_e32 v48, v52, v52
	v_fmac_f32_e32 v49, v54, v54
	v_add_f32_e32 v48, v48, v49
	v_mul_f32_e32 v49, v59, v59
	v_fmac_f32_e32 v49, v58, v58
	v_add_f32_e32 v48, v49, v48
	v_mul_f32_e32 v49, v57, v57
	v_fmac_f32_e32 v49, v56, v56
	v_add_f32_e32 v48, v49, v48
	v_add_f32_e32 v48, v68, v48
	v_mov_b32_e32 v49, v48
	s_nop 1
	v_permlane16_swap_b32_e32 v48, v49
	s_waitcnt lgkmcnt(0)
	v_add_f32_e32 v48, v48, v49
	v_mov_b32_e32 v49, v48
	s_nop 1
	v_permlane32_swap_b32_e32 v48, v49
	s_and_saveexec_b64 s[26:27], s[4:5]
	s_cbranch_execz .LBB0_710
	v_lshlrev_b64 v[50:51], 6, v[64:65]
	v_lshl_add_u64 v[50:51], s[12:13], 0, v[50:51]
	v_lshl_add_u64 v[50:51], s[24:25], 2, v[50:51]
	s_lshl_b32 s84, s39, 2
	v_lshl_add_u64 v[50:51], v[50:51], 0, s[84:85]
	v_add_f32_e32 v48, v48, v49
	global_store_dword v[50:51], v48, off
.LBB0_710:
	s_or_b64 exec, exec, s[26:27]
	v_add_u32_e32 v48, 0x90, v140
	v_ashrrev_i32_e32 v49, 31, v48
	v_lshlrev_b64 v[50:51], 11, v[48:49]
	v_lshl_add_u64 v[50:51], s[10:11], 0, v[50:51]
	v_lshl_add_u64 v[50:51], v[138:139], 1, v[50:51]
	global_load_dwordx4 v[52:55], v[50:51], off
	s_waitcnt vmcnt(0)
	v_lshlrev_b32_e32 v56, 16, v52
	v_and_b32_e32 v57, 0xffff0000, v52
	v_lshlrev_b32_e32 v52, 16, v53
	v_and_b32_e32 v53, 0xffff0000, v53
	v_lshlrev_b32_e32 v58, 16, v54
	v_and_b32_e32 v59, 0xffff0000, v54
	v_lshlrev_b32_e32 v54, 16, v55
	v_and_b32_e32 v55, 0xffff0000, v55
	v_pk_add_f32 v[46:47], v[46:47], v[52:53]
	v_pk_add_f32 v[44:45], v[44:45], v[56:57]
	v_pk_add_f32 v[52:53], v[42:43], v[54:55]
	v_pk_add_f32 v[54:55], v[40:41], v[58:59]
	v_cvt_pk_bf16_f32 v40, v44, v45
	v_cvt_pk_bf16_f32 v41, v46, v47
	v_cvt_pk_bf16_f32 v42, v54, v55
	v_cvt_pk_bf16_f32 v43, v52, v53
	global_store_dwordx4 v[50:51], v[40:43], off
	s_nop 1
	v_mul_f32_e32 v40, v45, v45
	v_mul_f32_e32 v41, v47, v47
	v_fmac_f32_e32 v40, v44, v44
	v_fmac_f32_e32 v41, v46, v46
	v_add_f32_e32 v40, v40, v41
	v_mul_f32_e32 v41, v55, v55
	v_fmac_f32_e32 v41, v54, v54
	v_add_f32_e32 v40, v41, v40
	v_mul_f32_e32 v41, v53, v53
	v_fmac_f32_e32 v41, v52, v52
	v_add_f32_e32 v52, v41, v40
	global_load_dwordx4 v[40:43], v[50:51], off offset:256
	s_waitcnt vmcnt(0)
	v_lshlrev_b32_e32 v44, 16, v40
	v_and_b32_e32 v45, 0xffff0000, v40
	v_lshlrev_b32_e32 v40, 16, v41
	v_and_b32_e32 v41, 0xffff0000, v41
	v_lshlrev_b32_e32 v46, 16, v42
	v_and_b32_e32 v47, 0xffff0000, v42
	v_lshlrev_b32_e32 v42, 16, v43
	v_and_b32_e32 v43, 0xffff0000, v43
	v_pk_add_f32 v[38:39], v[38:39], v[40:41]
	v_pk_add_f32 v[36:37], v[36:37], v[44:45]
	v_pk_add_f32 v[40:41], v[34:35], v[42:43]
	v_pk_add_f32 v[42:43], v[32:33], v[46:47]
	v_cvt_pk_bf16_f32 v32, v36, v37
	v_cvt_pk_bf16_f32 v33, v38, v39
	v_cvt_pk_bf16_f32 v34, v42, v43
	v_cvt_pk_bf16_f32 v35, v40, v41
	global_store_dwordx4 v[50:51], v[32:35], off offset:256
	s_nop 1
	v_mul_f32_e32 v32, v37, v37
	v_mul_f32_e32 v33, v39, v39
	v_fmac_f32_e32 v32, v36, v36
	v_fmac_f32_e32 v33, v38, v38
	v_add_f32_e32 v32, v32, v33
	v_mul_f32_e32 v33, v43, v43
	v_fmac_f32_e32 v33, v42, v42
	v_add_f32_e32 v32, v33, v32
	v_mul_f32_e32 v33, v41, v41
	v_fmac_f32_e32 v33, v40, v40
	v_add_f32_e32 v32, v33, v32
	v_add_f32_e32 v32, v52, v32
	v_mov_b32_e32 v33, v32
	s_nop 1
	v_permlane16_swap_b32_e32 v32, v33
	s_waitcnt lgkmcnt(0)
	v_add_f32_e32 v32, v32, v33
	v_mov_b32_e32 v33, v32
	s_nop 1
	v_permlane32_swap_b32_e32 v32, v33
	s_and_saveexec_b64 s[26:27], s[4:5]
	s_cbranch_execz .LBB0_712
	v_lshlrev_b64 v[34:35], 6, v[48:49]
	v_lshl_add_u64 v[34:35], s[12:13], 0, v[34:35]
	v_lshl_add_u64 v[34:35], s[24:25], 2, v[34:35]
	s_lshl_b32 s84, s39, 2
	v_lshl_add_u64 v[34:35], v[34:35], 0, s[84:85]
	v_add_f32_e32 v32, v32, v33
	global_store_dword v[34:35], v32, off
; __device__ __forceinline__ unsigned cvtpk(float lo, float hi) { f32x2 v = {lo, hi}; bf16x2_t b = __builtin_convertvector(v, bf16x2_t); return __builtin_bit_cast(unsigned, b); }
;     __device__ __forceinline__ void operator()(const f32x4 (&acc)[2][2][4][2], const Unit& u, int wr, int wc, int fr, int fq) const {
;     ...
;                 const int row = u.pm * BM + ai * HALF + wr * 64 + m * 16 + fr;
;                 float ss = 0.f;
; #pragma unroll
;                 for (int bj = 0; bj < 2; ++bj) { const int col = u.pn * BM + bj * HALF + wc * 32 + 8 * fq;
;                     f32x4 v0, v1;
;                     if (xin_p) { const float* xr = (row < MP ? xin_p + (size_t)row * DM : xin_s + (size_t)(row - MP) * DM) + col; v0 = *(const f32x4*)xr; v1 = *(const f32x4*)(xr + 4); }
;                     else { const u32x4 w = *(const u32x4*)(XR + (size_t)row * DM + col);
;                         v0 = (f32x4){__uint_as_float(w.x << 16), __uint_as_float(w.x & 0xffff0000u), __uint_as_float(w.y << 16), __uint_as_float(w.y & 0xffff0000u)};
;                         v1 = (f32x4){__uint_as_float(w.z << 16), __uint_as_float(w.z & 0xffff0000u), __uint_as_float(w.w << 16), __uint_as_float(w.w & 0xffff0000u)}; }
;                     v0 = v0 + acc[ai][bj][m][0]; v1 = v1 + acc[ai][bj][m][1];
;                     if (fout) { *(f32x4*)(fout + (size_t)row * DM + col) = v0; *(f32x4*)(fout + (size_t)row * DM + col + 4) = v1; }
;                     else { u32x4 w; w.x = cvtpk(v0[0], v0[1]); w.y = cvtpk(v0[2], v0[3]); w.z = cvtpk(v1[0], v1[1]); w.w = cvtpk(v1[2], v1[3]); *(u32x4*)(XR + (size_t)row * DM + col) = w; }
;                     if (PS) ss += (v0[0] * v0[0] + v0[1] * v0[1]) + (v0[2] * v0[2] + v0[3] * v0[3]) + (v1[0] * v1[0] + v1[1] * v1[1]) + (v1[2] * v1[2] + v1[3] * v1[3]); }
;                 if (PS) { ss = bfly_add<16>(ss); ss = bfly_add<32>(ss); if (fq == 0) PS[(size_t)row * 16 + 4 * u.pn + wc] = ss; }
.LBB0_712:
	s_or_b64 exec, exec, s[26:27]
	v_add_u32_e32 v32, 0xa0, v140
	v_ashrrev_i32_e32 v33, 31, v32
	v_lshlrev_b64 v[34:35], 11, v[32:33]
	v_lshl_add_u64 v[34:35], s[10:11], 0, v[34:35]
	v_lshl_add_u64 v[34:35], v[138:139], 1, v[34:35]
	global_load_dwordx4 v[36:39], v[34:35], off
	s_waitcnt vmcnt(0)
	v_lshlrev_b32_e32 v40, 16, v36
	v_and_b32_e32 v41, 0xffff0000, v36
	v_lshlrev_b32_e32 v36, 16, v37
	v_and_b32_e32 v37, 0xffff0000, v37
	v_lshlrev_b32_e32 v42, 16, v38
	v_and_b32_e32 v43, 0xffff0000, v38
	v_lshlrev_b32_e32 v38, 16, v39
	v_and_b32_e32 v39, 0xffff0000, v39
	v_pk_add_f32 v[30:31], v[30:31], v[36:37]
	v_pk_add_f32 v[28:29], v[28:29], v[40:41]
	v_pk_add_f32 v[36:37], v[26:27], v[38:39]
	v_pk_add_f32 v[38:39], v[24:25], v[42:43]
	v_cvt_pk_bf16_f32 v24, v28, v29
	v_cvt_pk_bf16_f32 v25, v30, v31
	v_cvt_pk_bf16_f32 v26, v38, v39
	v_cvt_pk_bf16_f32 v27, v36, v37
	global_store_dwordx4 v[34:35], v[24:27], off
	s_nop 1
	v_mul_f32_e32 v24, v29, v29
	v_mul_f32_e32 v25, v31, v31
	v_fmac_f32_e32 v24, v28, v28
	v_fmac_f32_e32 v25, v30, v30
	v_add_f32_e32 v24, v24, v25
	v_mul_f32_e32 v25, v39, v39
	v_fmac_f32_e32 v25, v38, v38
	v_add_f32_e32 v24, v25, v24
	v_mul_f32_e32 v25, v37, v37
	v_fmac_f32_e32 v25, v36, v36
	v_add_f32_e32 v36, v25, v24
	global_load_dwordx4 v[24:27], v[34:35], off offset:256
	s_waitcnt vmcnt(0)
	v_lshlrev_b32_e32 v28, 16, v24
	v_and_b32_e32 v29, 0xffff0000, v24
	v_lshlrev_b32_e32 v24, 16, v25
	v_and_b32_e32 v25, 0xffff0000, v25
	v_lshlrev_b32_e32 v30, 16, v26
	v_and_b32_e32 v31, 0xffff0000, v26
	v_lshlrev_b32_e32 v26, 16, v27
	v_and_b32_e32 v27, 0xffff0000, v27
	v_pk_add_f32 v[22:23], v[22:23], v[24:25]
	v_pk_add_f32 v[20:21], v[20:21], v[28:29]
	v_pk_add_f32 v[24:25], v[18:19], v[26:27]
	v_pk_add_f32 v[26:27], v[16:17], v[30:31]
	v_cvt_pk_bf16_f32 v16, v20, v21
	v_cvt_pk_bf16_f32 v17, v22, v23
	v_cvt_pk_bf16_f32 v18, v26, v27
	v_cvt_pk_bf16_f32 v19, v24, v25
	global_store_dwordx4 v[34:35], v[16:19], off offset:256
	s_nop 1
	v_mul_f32_e32 v16, v21, v21
	v_mul_f32_e32 v17, v23, v23
	v_fmac_f32_e32 v16, v20, v20
	v_fmac_f32_e32 v17, v22, v22
	v_add_f32_e32 v16, v16, v17
	v_mul_f32_e32 v17, v27, v27
	v_fmac_f32_e32 v17, v26, v26
	v_add_f32_e32 v16, v17, v16
	v_mul_f32_e32 v17, v25, v25
	v_fmac_f32_e32 v17, v24, v24
	v_add_f32_e32 v16, v17, v16
	v_add_f32_e32 v16, v36, v16
	v_mov_b32_e32 v17, v16
	s_nop 1
	v_permlane16_swap_b32_e32 v16, v17
	s_waitcnt lgkmcnt(0)
	v_add_f32_e32 v16, v16, v17
	v_mov_b32_e32 v17, v16
	s_nop 1
	v_permlane32_swap_b32_e32 v16, v17
	s_and_saveexec_b64 s[26:27], s[4:5]
	s_cbranch_execz .LBB0_714
	v_lshlrev_b64 v[18:19], 6, v[32:33]
	v_lshl_add_u64 v[18:19], s[12:13], 0, v[18:19]
	v_lshl_add_u64 v[18:19], s[24:25], 2, v[18:19]
	s_lshl_b32 s84, s39, 2
	v_lshl_add_u64 v[18:19], v[18:19], 0, s[84:85]
	v_add_f32_e32 v16, v16, v17
	global_store_dword v[18:19], v16, off
.LBB0_714:
	s_or_b64 exec, exec, s[26:27]
	v_add_u32_e32 v16, 0xb0, v140
	v_ashrrev_i32_e32 v17, 31, v16
	v_lshlrev_b64 v[18:19], 11, v[16:17]
	v_lshl_add_u64 v[18:19], s[10:11], 0, v[18:19]
	v_lshl_add_u64 v[18:19], v[138:139], 1, v[18:19]
	global_load_dwordx4 v[20:23], v[18:19], off
	s_waitcnt vmcnt(0)
	v_lshlrev_b32_e32 v24, 16, v20
	v_and_b32_e32 v25, 0xffff0000, v20
	v_lshlrev_b32_e32 v20, 16, v21
	v_and_b32_e32 v21, 0xffff0000, v21
	v_lshlrev_b32_e32 v26, 16, v22
	v_and_b32_e32 v27, 0xffff0000, v22
	v_lshlrev_b32_e32 v22, 16, v23
	v_and_b32_e32 v23, 0xffff0000, v23
	v_pk_add_f32 v[14:15], v[14:15], v[20:21]
	v_pk_add_f32 v[12:13], v[12:13], v[24:25]
	v_pk_add_f32 v[20:21], v[10:11], v[22:23]
	v_pk_add_f32 v[22:23], v[8:9], v[26:27]
	v_cvt_pk_bf16_f32 v8, v12, v13
	v_cvt_pk_bf16_f32 v9, v14, v15
	v_cvt_pk_bf16_f32 v10, v22, v23
	v_cvt_pk_bf16_f32 v11, v20, v21
	global_store_dwordx4 v[18:19], v[8:11], off
	s_nop 1
	v_mul_f32_e32 v8, v13, v13
	v_mul_f32_e32 v9, v15, v15
	v_fmac_f32_e32 v8, v12, v12
	v_fmac_f32_e32 v9, v14, v14
	v_add_f32_e32 v8, v8, v9
	v_mul_f32_e32 v9, v23, v23
	v_fmac_f32_e32 v9, v22, v22
	v_add_f32_e32 v8, v9, v8
	v_mul_f32_e32 v9, v21, v21
	v_fmac_f32_e32 v9, v20, v20
	v_add_f32_e32 v20, v9, v8
	global_load_dwordx4 v[8:11], v[18:19], off offset:256
	s_waitcnt vmcnt(0)
	v_lshlrev_b32_e32 v12, 16, v8
	v_and_b32_e32 v13, 0xffff0000, v8
	v_lshlrev_b32_e32 v8, 16, v9
	v_and_b32_e32 v9, 0xffff0000, v9
	v_lshlrev_b32_e32 v14, 16, v10
	v_and_b32_e32 v15, 0xffff0000, v10
	v_lshlrev_b32_e32 v10, 16, v11
	v_and_b32_e32 v11, 0xffff0000, v11
	v_pk_add_f32 v[6:7], v[6:7], v[8:9]
	v_pk_add_f32 v[4:5], v[4:5], v[12:13]
	v_pk_add_f32 v[8:9], v[2:3], v[10:11]
	v_pk_add_f32 v[10:11], v[0:1], v[14:15]
	v_cvt_pk_bf16_f32 v0, v4, v5
	v_cvt_pk_bf16_f32 v1, v6, v7
	v_cvt_pk_bf16_f32 v2, v10, v11
	v_cvt_pk_bf16_f32 v3, v8, v9
	global_store_dwordx4 v[18:19], v[0:3], off offset:256
	s_nop 1
	v_mul_f32_e32 v0, v5, v5
	v_mul_f32_e32 v1, v7, v7
	v_fmac_f32_e32 v0, v4, v4
	v_fmac_f32_e32 v1, v6, v6
	v_add_f32_e32 v0, v0, v1
	v_mul_f32_e32 v1, v11, v11
	v_fmac_f32_e32 v1, v10, v10
	v_add_f32_e32 v0, v1, v0
	v_mul_f32_e32 v1, v9, v9
	v_fmac_f32_e32 v1, v8, v8
	v_add_f32_e32 v0, v1, v0
	v_add_f32_e32 v0, v20, v0
	v_mov_b32_e32 v1, v0
	s_nop 1
	v_permlane16_swap_b32_e32 v0, v1
	s_waitcnt lgkmcnt(0)
	v_add_f32_e32 v0, v0, v1
	v_mov_b32_e32 v1, v0
	s_nop 1
	v_permlane32_swap_b32_e32 v0, v1
	s_and_saveexec_b64 s[26:27], s[4:5]
	s_cbranch_execz .LBB0_716
	v_lshlrev_b64 v[2:3], 6, v[16:17]
	v_lshl_add_u64 v[2:3], s[12:13], 0, v[2:3]
	v_lshl_add_u64 v[2:3], s[24:25], 2, v[2:3]
	s_lshl_b32 s84, s39, 2
	v_lshl_add_u64 v[2:3], v[2:3], 0, s[84:85]
	v_add_f32_e32 v0, v0, v1
	global_store_dword v[2:3], v0, off

; __device__ __forceinline__ float dpp_ror1(float x) { return __builtin_bit_cast(float, __builtin_amdgcn_mov_dpp(__builtin_bit_cast(int, x), 0x121, 0xF, 0xF, true)); }
; __device__ __forceinline__ float dpp_ror15(float x) { return __builtin_bit_cast(float, __builtin_amdgcn_mov_dpp(__builtin_bit_cast(int, x), 0x12F, 0xF, 0xF, true)); }
;     __device__ __forceinline__ void operator()(const f32x4 (&acc)[2][2][4][2], const Unit& u, int wr, int wc, int fr, int fq) const {
;     ...
;             for (int m = 0; m < 4; ++m) { const int t = tbase + 16 * m + fr; const bool vin = (t >= 0) && (t < slen); const int grow = seqbase + (vin ? t : 0);
;                 const f32x4 p = *(const f32x4*)(PS + (size_t)grow * 16 + 4 * fq); float s = (p[0] + p[1]) + (p[2] + p[3]); s = bfly_add<16>(s); s = bfly_add<32>(s); rs[m] = vin ? rsqrtf(s * (1.f / DM) + EPS) : 0.f; }
;     ...
;                     const f32x4 c0a = ct[cidx], c0b = ct[cidx + 1], c1a = ct[cidx + 2], c1b = ct[cidx + 3];
;                     const f32x2 wv0 = {c0a[0], c1a[0]}, wv1 = {c0a[1], c1a[1]}, wv2 = {c0a[2], c1a[2]}, bv = {c0a[3], c1a[3]};
;                     const f32x2 wg0 = {c0b[0], c1b[0]}, wg1 = {c0b[1], c1b[1]}, wg2 = {c0b[2], c1b[2]}, bg = {c0b[3], c1b[3]};
;                     f32x2 uv[4], ug[4], cv[4];
; #pragma unroll
;                     for (int m = 0; m < 4; ++m) { uv[m] = (f32x2){acc[ai][0][m][n][2 * jp], acc[ai][0][m][n][2 * jp + 1]}; ug[m] = (f32x2){acc[ai][1][m][n][2 * jp], acc[ai][1][m][n][2 * jp + 1]}; }
;                     asm volatile("" : "+v"(uv[0]), "+v"(uv[1]), "+v"(uv[2]), "+v"(uv[3]), "+v"(ug[0]), "+v"(ug[1]), "+v"(ug[2]), "+v"(ug[3]));
;                     {
;                         f32x2 rv[4], lv[4];
; #pragma unroll
;                         for (int m = 0; m < 4; ++m) { uv[m] = uv[m] * rs[m]; rv[m] = (f32x2){dpp_ror1(uv[m][0]), dpp_ror1(uv[m][1])}; lv[m] = (f32x2){dpp_ror15(uv[m][0]), dpp_ror15(uv[m][1])}; }
; #pragma unroll
;                         for (int m = 0; m < 4; ++m) { const f32x2 pv_ = (m > 0 && f0) ? rv[m > 0 ? m - 1 : 0] : rv[m], nv_ = (m < 3 && f15) ? lv[m < 3 ? m + 1 : 3] : lv[m];
;                             cv[m] = bv + wv0 * pv_ + wv1 * uv[m] + wv2 * nv_; }
.LBB0_794:
	s_mul_i32 s52, s14, 0xf8
	s_add_i32 s52, s52, s49
	v_add_u32_e32 v190, s52, v161
	v_cmp_gt_u32_e32 vcc, s51, v190
	s_lshl_b32 s36, s33, 7
	s_ashr_i32 s37, s36, 31
	v_cndmask_b32_e32 v128, 0, v190, vcc
	v_add_u32_e32 v128, s29, v128
	v_ashrrev_i32_e32 v129, 31, v128
	v_lshlrev_b64 v[128:129], 6, v[128:129]
	v_lshl_add_u64 v[128:129], v[164:165], 0, v[128:129]
	global_load_dwordx4 v[128:131], v[128:129], off
	s_lshl_b64 s[2:3], s[36:37], 5
	v_lshl_add_u64 v[170:171], v[162:163], 0, s[2:3]
	s_waitcnt vmcnt(0)
	v_mov_b32_e32 v132, v129
	v_mov_b32_e32 v133, v130
	v_mov_b32_e32 v129, v131
	v_pk_add_f32 v[128:129], v[132:133], v[128:129]
	s_nop 0
	v_add_f32_e32 v128, v128, v129
	v_mov_b32_e32 v129, v128
	s_nop 1
	v_permlane16_swap_b32_e32 v128, v129
	s_waitcnt lgkmcnt(0)
	v_add_f32_e32 v133, v128, v129
	v_add_u32_e32 v128, 16, v190
	v_cmp_gt_u32_e64 s[14:15], s51, v128
	v_mov_b32_e32 v135, v133
	s_nop 1
	v_permlane32_swap_b32_e32 v133, v135
	v_cndmask_b32_e64 v128, 0, v128, s[14:15]
	v_add_u32_e32 v128, s29, v128
	v_ashrrev_i32_e32 v129, 31, v128
	v_lshlrev_b64 v[128:129], 6, v[128:129]
	v_lshl_add_u64 v[128:129], v[164:165], 0, v[128:129]
	global_load_dwordx4 v[128:131], v[128:129], off
	s_waitcnt vmcnt(0)
	v_mov_b32_e32 v136, v129
	v_mov_b32_e32 v137, v130
	v_mov_b32_e32 v129, v131
	v_pk_add_f32 v[128:129], v[136:137], v[128:129]
	s_nop 0
	v_add_f32_e32 v128, v128, v129
	v_mov_b32_e32 v129, v128
	s_nop 1
	v_permlane16_swap_b32_e32 v128, v129
	s_waitcnt lgkmcnt(0)
	v_add_f32_e32 v132, v128, v129
	v_mov_b32_e32 v134, v132
	s_nop 1
	v_permlane32_swap_b32_e32 v132, v134
	v_pk_add_f32 v[128:129], v[132:133], v[134:135]
	v_mov_b64_e32 v[132:133], s[78:79]
	v_pk_fma_f32 v[128:129], v[128:129], s[82:83], v[132:133] op_sel_hi:[1,0,0]
	s_nop 0
	v_mul_f32_e32 v130, 0x4b800000, v129
	v_cmp_gt_f32_e64 s[20:21], s62, v129
	v_cmp_gt_f32_e64 s[18:19], s62, v128
	s_nop 0
	v_cndmask_b32_e64 v129, v129, v130, s[20:21]
	v_rsq_f32_e32 v129, v129
	s_nop 0
	v_mul_f32_e32 v130, 0x45800000, v129
	v_cndmask_b32_e64 v129, v129, v130, s[20:21]
	v_cndmask_b32_e32 v172, 0, v129, vcc
	v_mul_f32_e32 v129, 0x4b800000, v128
	v_cndmask_b32_e64 v128, v128, v129, s[18:19]
	v_rsq_f32_e32 v128, v128
	s_nop 0
	v_mul_f32_e32 v129, 0x45800000, v128
	v_cndmask_b32_e64 v128, v128, v129, s[18:19]
	v_cndmask_b32_e64 v144, 0, v128, s[14:15]
	v_add_u32_e32 v128, 32, v190
	v_cmp_gt_u32_e32 vcc, s51, v128
	s_nop 1
	v_cndmask_b32_e32 v128, 0, v128, vcc
	v_add_u32_e32 v128, s29, v128
	v_ashrrev_i32_e32 v129, 31, v128
	v_lshlrev_b64 v[128:129], 6, v[128:129]
	v_lshl_add_u64 v[128:129], v[164:165], 0, v[128:129]
	global_load_dwordx4 v[128:131], v[128:129], off
	s_waitcnt vmcnt(0)
	v_mov_b32_e32 v134, v129
	v_mov_b32_e32 v135, v130
	v_mov_b32_e32 v129, v131
	v_pk_add_f32 v[128:129], v[134:135], v[128:129]
	s_nop 0
	v_add_f32_e32 v128, v128, v129
	v_mov_b32_e32 v129, v128
	s_nop 1
	v_permlane16_swap_b32_e32 v128, v129
	s_waitcnt lgkmcnt(0)
	v_add_f32_e32 v135, v128, v129
	v_add_u32_e32 v128, 48, v190
	v_cmp_gt_u32_e64 s[14:15], s51, v128
	v_mov_b32_e32 v137, v135
	s_nop 1
	v_permlane32_swap_b32_e32 v135, v137
	v_cndmask_b32_e64 v128, 0, v128, s[14:15]
	v_add_u32_e32 v128, s29, v128
	v_ashrrev_i32_e32 v129, 31, v128
	v_lshlrev_b64 v[128:129], 6, v[128:129]
	v_lshl_add_u64 v[128:129], v[164:165], 0, v[128:129]
	global_load_dwordx4 v[128:131], v[128:129], off
	s_waitcnt vmcnt(0)
	v_mov_b32_e32 v138, v129
	v_mov_b32_e32 v139, v130
	v_mov_b32_e32 v129, v131
	v_pk_add_f32 v[128:129], v[138:139], v[128:129]
	s_nop 0
	v_add_f32_e32 v128, v128, v129
	v_mov_b32_e32 v129, v128
	s_nop 1
	v_permlane16_swap_b32_e32 v128, v129
	s_waitcnt lgkmcnt(0)
	v_add_f32_e32 v134, v128, v129
	v_mov_b32_e32 v136, v134
	s_nop 1
	v_permlane32_swap_b32_e32 v134, v136
	v_pk_add_f32 v[128:129], v[134:135], v[136:137]
	s_nop 0
	v_pk_fma_f32 v[128:129], v[128:129], s[82:83], v[132:133] op_sel_hi:[1,0,0]
	s_nop 0
	v_mul_f32_e32 v130, 0x4b800000, v129
	v_cmp_gt_f32_e64 s[20:21], s62, v129
	v_cmp_gt_f32_e64 s[18:19], s62, v128
	s_nop 0
	v_cndmask_b32_e64 v129, v129, v130, s[20:21]
	v_rsq_f32_e32 v129, v129
	s_nop 0
	v_mul_f32_e32 v130, 0x45800000, v129
	v_cndmask_b32_e64 v129, v129, v130, s[20:21]
	v_cndmask_b32_e32 v174, 0, v129, vcc
	v_mul_f32_e32 v129, 0x4b800000, v128
	v_cndmask_b32_e64 v128, v128, v129, s[18:19]
	v_rsq_f32_e32 v128, v128
	s_nop 0
	v_mul_f32_e32 v129, 0x45800000, v128
	v_cndmask_b32_e64 v128, v128, v129, s[18:19]
	v_cndmask_b32_e64 v176, 0, v128, s[14:15]
	global_load_dwordx4 v[132:135], v[170:171], off offset:16
	global_load_dwordx4 v[128:131], v[170:171], off offset:48
	global_load_dwordx4 v[140:143], v[170:171], off
	global_load_dwordx4 v[136:139], v[170:171], off offset:32
	s_waitcnt vmcnt(3)
	v_mov_b32_e32 v178, v132
	v_pk_mul_f32 v[124:125], v[172:173], v[124:125] op_sel_hi:[0,1]
	v_pk_mul_f32 v[120:121], v[120:121], v[144:145] op_sel_hi:[1,0]
	s_waitcnt vmcnt(1)
	v_mov_b32_e32 v182, v140
	s_waitcnt vmcnt(0)
;     __device__ __forceinline__ void operator()(const f32x4 (&acc)[2][2][4][2], const Unit& u, int wr, int wc, int fr, int fq) const {
;     ...
;                     const f32x4 c0a = ct[cidx], c0b = ct[cidx + 1], c1a = ct[cidx + 2], c1b = ct[cidx + 3];
;                     const f32x2 wv0 = {c0a[0], c1a[0]}, wv1 = {c0a[1], c1a[1]}, wv2 = {c0a[2], c1a[2]}, bv = {c0a[3], c1a[3]};
;                     const f32x2 wg0 = {c0b[0], c1b[0]}, wg1 = {c0b[1], c1b[1]}, wg2 = {c0b[2], c1b[2]}, bg = {c0b[3], c1b[3]};
;                     f32x2 uv[4], ug[4], cv[4];
; #pragma unroll
;                     for (int m = 0; m < 4; ++m) { uv[m] = (f32x2){acc[ai][0][m][n][2 * jp], acc[ai][0][m][n][2 * jp + 1]}; ug[m] = (f32x2){acc[ai][1][m][n][2 * jp], acc[ai][1][m][n][2 * jp + 1]}; }
;                     asm volatile("" : "+v"(uv[0]), "+v"(uv[1]), "+v"(uv[2]), "+v"(uv[3]), "+v"(ug[0]), "+v"(ug[1]), "+v"(ug[2]), "+v"(ug[3]));
;                     {
;                         f32x2 rv[4], lv[4];
; #pragma unroll
;                         for (int m = 0; m < 4; ++m) { uv[m] = uv[m] * rs[m]; rv[m] = (f32x2){dpp_ror1(uv[m][0]), dpp_ror1(uv[m][1])}; lv[m] = (f32x2){dpp_ror15(uv[m][0]), dpp_ror15(uv[m][1])}; }
; #pragma unroll
;                         for (int m = 0; m < 4; ++m) { const f32x2 pv_ = (m > 0 && f0) ? rv[m > 0 ? m - 1 : 0] : rv[m], nv_ = (m < 3 && f15) ? lv[m < 3 ? m + 1 : 3] : lv[m];
;                             cv[m] = bv + wv0 * pv_ + wv1 * uv[m] + wv2 * nv_; }
;                     }
;                     asm volatile("" : "+v"(cv[0]), "+v"(cv[1]), "+v"(cv[2]), "+v"(cv[3]));
;                     {
;                         f32x2 rg[4], lg[4];
; #pragma unroll
;                         for (int m = 0; m < 4; ++m) { ug[m] = ug[m] * rs[m]; rg[m] = (f32x2){dpp_ror1(ug[m][0]), dpp_ror1(ug[m][1])}; lg[m] = (f32x2){dpp_ror15(ug[m][0]), dpp_ror15(ug[m][1])}; }
; #pragma unroll
;                         for (int m = 0; m < 4; ++m) { const f32x2 pg_ = (m > 0 && f0) ? rg[m > 0 ? m - 1 : 0] : rg[m], ng_ = (m < 3 && f15) ? lg[m < 3 ? m + 1 : 3] : lg[m];
;                             const f32x2 cgt = bg + wg0 * pg_ + wg1 * ug[m] + wg2 * ng_;
;                             const f32x2 e = cgt * (-LOG2E);
;                             const f32x2 d = (f32x2){__builtin_amdgcn_exp2f(e[0]), __builtin_amdgcn_exp2f(e[1])} + 1.f;
	v_mov_b32_e32 v183, v136
	v_mov_b32_e32 v193, v138
	v_mov_b32_e32 v179, v128
	v_mov_b32_e32 v128, v133
	v_mov_b32_dpp v132, v124 row_ror:1 row_mask:0xf bank_mask:0xf bound_ctrl:1
	v_mov_b32_dpp v133, v125 row_ror:1 row_mask:0xf bank_mask:0xf bound_ctrl:1
	v_mov_b32_dpp v191, v120 row_ror:1 row_mask:0xf bank_mask:0xf bound_ctrl:1
	v_mov_b32_dpp v196, v121 row_ror:1 row_mask:0xf bank_mask:0xf bound_ctrl:1
	v_mov_b32_e32 v138, v143
	v_pk_mul_f32 v[116:117], v[116:117], v[174:175] op_sel_hi:[1,0]
	v_pk_fma_f32 v[194:195], v[182:183], v[132:133], v[138:139]
	v_cndmask_b32_e64 v133, v196, v133, s[4:5]
	v_cndmask_b32_e64 v132, v191, v132, s[4:5]
	v_mov_b32_e32 v136, v141
	v_mov_b32_dpp v199, v116 row_ror:1 row_mask:0xf bank_mask:0xf bound_ctrl:1
	v_mov_b32_dpp v200, v117 row_ror:1 row_mask:0xf bank_mask:0xf bound_ctrl:1
	v_pk_fma_f32 v[132:133], v[182:183], v[132:133], v[138:139]
	v_mov_b32_dpp v197, v120 row_ror:15 row_mask:0xf bank_mask:0xf bound_ctrl:1
	v_mov_b32_dpp v198, v121 row_ror:15 row_mask:0xf bank_mask:0xf bound_ctrl:1
	v_pk_mul_f32 v[112:113], v[112:113], v[176:177] op_sel_hi:[1,0]
	v_pk_fma_f32 v[120:121], v[136:137], v[120:121], v[132:133]
	v_cndmask_b32_e64 v133, v200, v196, s[4:5]
	v_cndmask_b32_e64 v132, v199, v191, s[4:5]
	v_mov_b32_e32 v180, v134
	v_mov_b32_e32 v181, v130
	v_mov_b32_dpp v130, v124 row_ror:15 row_mask:0xf bank_mask:0xf bound_ctrl:1
	v_mov_b32_dpp v134, v125 row_ror:15 row_mask:0xf bank_mask:0xf bound_ctrl:1
	v_mov_b32_dpp v203, v112 row_ror:1 row_mask:0xf bank_mask:0xf bound_ctrl:1
	v_mov_b32_dpp v204, v113 row_ror:1 row_mask:0xf bank_mask:0xf bound_ctrl:1
	v_pk_fma_f32 v[132:133], v[182:183], v[132:133], v[138:139]
	v_mov_b32_e32 v192, v142
	v_mov_b32_dpp v201, v116 row_ror:15 row_mask:0xf bank_mask:0xf bound_ctrl:1
	v_mov_b32_dpp v202, v117 row_ror:15 row_mask:0xf bank_mask:0xf bound_ctrl:1
	v_cndmask_b32_e64 v143, v134, v198, s[6:7]
	v_cndmask_b32_e64 v142, v130, v197, s[6:7]
	v_pk_fma_f32 v[124:125], v[136:137], v[124:125], v[194:195]
	v_pk_fma_f32 v[116:117], v[136:137], v[116:117], v[132:133]
	v_cndmask_b32_e64 v133, v204, v200, s[4:5]
	v_cndmask_b32_e64 v132, v203, v199, s[4:5]
	v_mov_b32_dpp v140, v112 row_ror:15 row_mask:0xf bank_mask:0xf bound_ctrl:1
	v_mov_b32_dpp v141, v113 row_ror:15 row_mask:0xf bank_mask:0xf bound_ctrl:1
	v_pk_fma_f32 v[124:125], v[192:193], v[142:143], v[124:125]
	v_cndmask_b32_e64 v143, v198, v202, s[6:7]
	v_cndmask_b32_e64 v142, v197, v201, s[6:7]
	v_pk_fma_f32 v[132:133], v[182:183], v[132:133], v[138:139]
	v_pk_mul_f32 v[108:109], v[172:173], v[108:109] op_sel_hi:[0,1]
	v_pk_fma_f32 v[120:121], v[192:193], v[142:143], v[120:121]
	v_cndmask_b32_e64 v143, v202, v141, s[6:7]
	v_cndmask_b32_e64 v142, v201, v140, s[6:7]
	v_pk_fma_f32 v[112:113], v[136:137], v[112:113], v[132:133]
	v_mov_b32_dpp v132, v108 row_ror:1 row_mask:0xf bank_mask:0xf bound_ctrl:1
	v_mov_b32_dpp v133, v109 row_ror:1 row_mask:0xf bank_mask:0xf bound_ctrl:1
	v_pk_mul_f32 v[104:105], v[104:105], v[144:145] op_sel_hi:[1,0]
	v_mov_b32_e32 v130, v135
	v_pk_fma_f32 v[116:117], v[192:193], v[142:143], v[116:117]
	v_mov_b32_dpp v134, v108 row_ror:15 row_mask:0xf bank_mask:0xf bound_ctrl:1
	v_mov_b32_dpp v142, v109 row_ror:15 row_mask:0xf bank_mask:0xf bound_ctrl:1
	v_mov_b32_dpp v183, v104 row_ror:15 row_mask:0xf bank_mask:0xf bound_ctrl:1
	v_mov_b32_dpp v191, v105 row_ror:15 row_mask:0xf bank_mask:0xf bound_ctrl:1
	v_pk_mul_f32 v[136:137], v[100:101], v[174:175] op_sel_hi:[1,0]
	v_pk_fma_f32 v[100:101], v[178:179], v[132:133], v[130:131]
	v_pk_mul_f32 v[138:139], v[96:97], v[176:177] op_sel_hi:[1,0]
	v_cndmask_b32_e64 v97, v142, v191, s[6:7]
	v_cndmask_b32_e64 v96, v134, v183, s[6:7]
	v_pk_fma_f32 v[100:101], v[128:129], v[108:109], v[100:101]
	v_pk_fma_f32 v[112:113], v[192:193], v[140:141], v[112:113]
	v_pk_fma_f32 v[96:97], v[180:181], v[96:97], v[100:101]
	v_mov_b32_dpp v143, v104 row_ror:1 row_mask:0xf bank_mask:0xf bound_ctrl:1
	v_pk_mul_f32 v[100:101], v[96:97], s[76:77] op_sel_hi:[1,0]
	v_mov_b32_dpp v182, v105 row_ror:1 row_mask:0xf bank_mask:0xf bound_ctrl:1
	v_exp_f32_e32 v100, v100
	v_exp_f32_e32 v101, v101
	v_pk_mul_f32 v[96:97], v[124:125], v[96:97]
	v_mov_b32_dpp v194, v136 row_ror:15 row_mask:0xf bank_mask:0xf bound_ctrl:1
	v_mov_b32_dpp v195, v137 row_ror:15 row_mask:0xf bank_mask:0xf bound_ctrl:1
	v_pk_add_f32 v[100:101], v[100:101], 1.0 op_sel_hi:[1,0]
	v_cndmask_b32_e64 v109, v191, v195, s[6:7]
	v_rcp_f32_e32 v100, v100
	v_rcp_f32_e32 v101, v101
	v_cndmask_b32_e64 v108, v183, v194, s[6:7]
	v_mov_b32_dpp v192, v136 row_ror:1 row_mask:0xf bank_mask:0xf bound_ctrl:1
	v_mov_b32_dpp v193, v137 row_ror:1 row_mask:0xf bank_mask:0xf bound_ctrl:1
	v_pk_mul_f32 v[96:97], v[96:97], v[100:101]
	v_cndmask_b32_e64 v101, v182, v133, s[4:5]
	v_cndmask_b32_e64 v100, v143, v132, s[4:5]
	v_pk_fma_f32 v[100:101], v[178:179], v[100:101], v[130:131]
	v_mov_b32_dpp v140, v138 row_ror:15 row_mask:0xf bank_mask:0xf bound_ctrl:1
	v_pk_fma_f32 v[100:101], v[128:129], v[104:105], v[100:101]
	v_mov_b32_dpp v141, v139 row_ror:15 row_mask:0xf bank_mask:0xf bound_ctrl:1
	v_pk_fma_f32 v[100:101], v[180:181], v[108:109], v[100:101]
	v_cndmask_b32_e64 v109, v195, v141, s[6:7]
	v_pk_mul_f32 v[104:105], v[100:101], s[76:77] op_sel_hi:[1,0]
	v_pk_mul_f32 v[100:101], v[120:121], v[100:101]
	v_exp_f32_e32 v104, v104
	v_exp_f32_e32 v105, v105
	v_cndmask_b32_e64 v108, v194, v140, s[6:7]
	v_mov_b32_dpp v196, v138 row_ror:1 row_mask:0xf bank_mask:0xf bound_ctrl:1
	v_mov_b32_dpp v197, v139 row_ror:1 row_mask:0xf bank_mask:0xf bound_ctrl:1
	v_pk_add_f32 v[104:105], v[104:105], 1.0 op_sel_hi:[1,0]
	v_cvt_pk_bf16_f32 v96, v96, v97
;     __device__ __forceinline__ void operator()(const f32x4 (&acc)[2][2][4][2], const Unit& u, int wr, int wc, int fr, int fq) const {
;     ...
;                     const f32x4 c0a = ct[cidx], c0b = ct[cidx + 1], c1a = ct[cidx + 2], c1b = ct[cidx + 3];
;                     const f32x2 wv0 = {c0a[0], c1a[0]}, wv1 = {c0a[1], c1a[1]}, wv2 = {c0a[2], c1a[2]}, bv = {c0a[3], c1a[3]};
;                     const f32x2 wg0 = {c0b[0], c1b[0]}, wg1 = {c0b[1], c1b[1]}, wg2 = {c0b[2], c1b[2]}, bg = {c0b[3], c1b[3]};
;                     f32x2 uv[4], ug[4], cv[4];
; #pragma unroll
;                     for (int m = 0; m < 4; ++m) { uv[m] = (f32x2){acc[ai][0][m][n][2 * jp], acc[ai][0][m][n][2 * jp + 1]}; ug[m] = (f32x2){acc[ai][1][m][n][2 * jp], acc[ai][1][m][n][2 * jp + 1]}; }
;                     asm volatile("" : "+v"(uv[0]), "+v"(uv[1]), "+v"(uv[2]), "+v"(uv[3]), "+v"(ug[0]), "+v"(ug[1]), "+v"(ug[2]), "+v"(ug[3]));
;                     {
;                         f32x2 rv[4], lv[4];
; #pragma unroll
;                         for (int m = 0; m < 4; ++m) { uv[m] = uv[m] * rs[m]; rv[m] = (f32x2){dpp_ror1(uv[m][0]), dpp_ror1(uv[m][1])}; lv[m] = (f32x2){dpp_ror15(uv[m][0]), dpp_ror15(uv[m][1])}; }
; #pragma unroll
;                         for (int m = 0; m < 4; ++m) { const f32x2 pv_ = (m > 0 && f0) ? rv[m > 0 ? m - 1 : 0] : rv[m], nv_ = (m < 3 && f15) ? lv[m < 3 ? m + 1 : 3] : lv[m];
;                             cv[m] = bv + wv0 * pv_ + wv1 * uv[m] + wv2 * nv_; }
;                     }
;                     asm volatile("" : "+v"(cv[0]), "+v"(cv[1]), "+v"(cv[2]), "+v"(cv[3]));
;                     {
;                         f32x2 rg[4], lg[4];
; #pragma unroll
;                         for (int m = 0; m < 4; ++m) { ug[m] = ug[m] * rs[m]; rg[m] = (f32x2){dpp_ror1(ug[m][0]), dpp_ror1(ug[m][1])}; lg[m] = (f32x2){dpp_ror15(ug[m][0]), dpp_ror15(ug[m][1])}; }
; #pragma unroll
;                         for (int m = 0; m < 4; ++m) { const f32x2 pg_ = (m > 0 && f0) ? rg[m > 0 ? m - 1 : 0] : rg[m], ng_ = (m < 3 && f15) ? lg[m < 3 ? m + 1 : 3] : lg[m];
;                             const f32x2 cgt = bg + wg0 * pg_ + wg1 * ug[m] + wg2 * ng_;
;                             const f32x2 e = cgt * (-LOG2E);
;                             const f32x2 d = (f32x2){__builtin_amdgcn_exp2f(e[0]), __builtin_amdgcn_exp2f(e[1])} + 1.f;
	v_rcp_f32_e32 v104, v104
	v_rcp_f32_e32 v105, v105
	s_nop 0
	v_pk_mul_f32 v[100:101], v[100:101], v[104:105]
	v_cndmask_b32_e64 v105, v193, v182, s[4:5]
	v_cndmask_b32_e64 v104, v192, v143, s[4:5]
	v_pk_fma_f32 v[104:105], v[178:179], v[104:105], v[130:131]
	v_cvt_pk_bf16_f32 v100, v100, v101
	v_pk_fma_f32 v[104:105], v[128:129], v[136:137], v[104:105]
	s_nop 0
	v_pk_fma_f32 v[104:105], v[180:181], v[108:109], v[104:105]
	s_nop 0
	v_pk_mul_f32 v[108:109], v[104:105], s[76:77] op_sel_hi:[1,0]
	v_pk_mul_f32 v[104:105], v[116:117], v[104:105]
	v_exp_f32_e32 v108, v108
	v_exp_f32_e32 v109, v109
	s_nop 0
	v_pk_add_f32 v[108:109], v[108:109], 1.0 op_sel_hi:[1,0]
	s_nop 0
	v_rcp_f32_e32 v108, v108
	v_rcp_f32_e32 v109, v109
	s_nop 0
	v_pk_mul_f32 v[104:105], v[104:105], v[108:109]
	v_cndmask_b32_e64 v109, v197, v193, s[4:5]
	v_cndmask_b32_e64 v108, v196, v192, s[4:5]
	v_pk_fma_f32 v[108:109], v[178:179], v[108:109], v[130:131]
	v_cvt_pk_bf16_f32 v104, v104, v105
	v_pk_fma_f32 v[108:109], v[128:129], v[138:139], v[108:109]
	s_nop 0
	v_pk_fma_f32 v[108:109], v[180:181], v[140:141], v[108:109]
	s_nop 0
	v_pk_mul_f32 v[116:117], v[108:109], s[76:77] op_sel_hi:[1,0]
	v_pk_mul_f32 v[108:109], v[112:113], v[108:109]
	v_exp_f32_e32 v116, v116
	v_exp_f32_e32 v117, v117
	s_nop 0
	v_pk_add_f32 v[116:117], v[116:117], 1.0 op_sel_hi:[1,0]
	s_nop 0
	v_rcp_f32_e32 v116, v116
	v_rcp_f32_e32 v117, v117
	s_nop 0
	v_pk_mul_f32 v[108:109], v[108:109], v[116:117]
	s_nop 0
	v_cvt_pk_bf16_f32 v108, v108, v109
	global_load_dwordx4 v[132:135], v[170:171], off offset:80
	global_load_dwordx4 v[128:131], v[170:171], off offset:112
	global_load_dwordx4 v[136:139], v[170:171], off offset:64
	global_load_dwordx4 v[140:143], v[170:171], off offset:96
	s_waitcnt vmcnt(3)
	v_mov_b32_e32 v116, v132
	v_pk_mul_f32 v[120:121], v[172:173], v[126:127] op_sel_hi:[0,1]
	s_waitcnt vmcnt(1)
	v_mov_b32_e32 v124, v136
	s_waitcnt vmcnt(0)
	v_mov_b32_e32 v125, v140
	v_mov_b32_e32 v179, v142
	v_mov_b32_e32 v117, v128
	v_mov_b32_e32 v128, v133
	v_mov_b32_dpp v126, v120 row_ror:1 row_mask:0xf bank_mask:0xf bound_ctrl:1
	v_mov_b32_dpp v127, v121 row_ror:1 row_mask:0xf bank_mask:0xf bound_ctrl:1
	v_pk_mul_f32 v[132:133], v[144:145], v[122:123] op_sel_hi:[0,1]
	v_mov_b32_e32 v142, v139
	v_mov_b32_e32 v178, v138
	v_mov_b32_e32 v112, v134
	v_mov_b32_e32 v113, v130
	v_mov_b32_e32 v140, v137
	v_mov_b32_dpp v97, v120 row_ror:15 row_mask:0xf bank_mask:0xf bound_ctrl:1
	v_mov_b32_dpp v101, v121 row_ror:15 row_mask:0xf bank_mask:0xf bound_ctrl:1
	v_mov_b32_dpp v130, v132 row_ror:15 row_mask:0xf bank_mask:0xf bound_ctrl:1
	v_mov_b32_dpp v134, v133 row_ror:15 row_mask:0xf bank_mask:0xf bound_ctrl:1
	v_pk_fma_f32 v[138:139], v[124:125], v[126:127], v[142:143]
	v_mov_b32_dpp v105, v132 row_ror:1 row_mask:0xf bank_mask:0xf bound_ctrl:1
	v_mov_b32_dpp v109, v133 row_ror:1 row_mask:0xf bank_mask:0xf bound_ctrl:1
	v_cndmask_b32_e64 v123, v101, v134, s[6:7]
	v_cndmask_b32_e64 v122, v97, v130, s[6:7]
	v_pk_fma_f32 v[120:121], v[140:141], v[120:121], v[138:139]
	v_pk_mul_f32 v[118:119], v[174:175], v[118:119] op_sel_hi:[0,1]
	v_pk_fma_f32 v[122:123], v[178:179], v[122:123], v[120:121]
	v_cndmask_b32_e64 v121, v109, v127, s[4:5]
	v_cndmask_b32_e64 v120, v105, v126, s[4:5]
	v_mov_b32_dpp v182, v118 row_ror:15 row_mask:0xf bank_mask:0xf bound_ctrl:1
	v_mov_b32_dpp v183, v119 row_ror:15 row_mask:0xf bank_mask:0xf bound_ctrl:1
	v_pk_fma_f32 v[120:121], v[124:125], v[120:121], v[142:143]
	v_mov_b32_dpp v180, v118 row_ror:1 row_mask:0xf bank_mask:0xf bound_ctrl:1
	v_mov_b32_dpp v181, v119 row_ror:1 row_mask:0xf bank_mask:0xf bound_ctrl:1
	v_cndmask_b32_e64 v127, v134, v183, s[6:7]
	v_cndmask_b32_e64 v126, v130, v182, s[6:7]
	v_pk_fma_f32 v[120:121], v[140:141], v[132:133], v[120:121]
	v_pk_mul_f32 v[114:115], v[176:177], v[114:115] op_sel_hi:[0,1]
	v_pk_fma_f32 v[120:121], v[178:179], v[126:127], v[120:121]
	v_cndmask_b32_e64 v127, v181, v109, s[4:5]
	v_cndmask_b32_e64 v126, v180, v105, s[4:5]
	v_mov_b32_dpp v191, v114 row_ror:1 row_mask:0xf bank_mask:0xf bound_ctrl:1
	v_mov_b32_dpp v192, v115 row_ror:1 row_mask:0xf bank_mask:0xf bound_ctrl:1
	v_pk_fma_f32 v[126:127], v[124:125], v[126:127], v[142:143]
	v_mov_b32_dpp v136, v114 row_ror:15 row_mask:0xf bank_mask:0xf bound_ctrl:1
	v_pk_fma_f32 v[118:119], v[140:141], v[118:119], v[126:127]
	v_cndmask_b32_e64 v127, v192, v181, s[4:5]
	v_cndmask_b32_e64 v126, v191, v180, s[4:5]
	v_pk_fma_f32 v[124:125], v[124:125], v[126:127], v[142:143]
	v_mov_b32_dpp v137, v115 row_ror:15 row_mask:0xf bank_mask:0xf bound_ctrl:1
	v_pk_fma_f32 v[114:115], v[140:141], v[114:115], v[124:125]
	v_pk_mul_f32 v[124:125], v[172:173], v[110:111] op_sel_hi:[0,1]
	v_pk_mul_f32 v[106:107], v[144:145], v[106:107] op_sel_hi:[0,1]
	v_mov_b32_e32 v130, v135
	v_mov_b32_dpp v110, v124 row_ror:1 row_mask:0xf bank_mask:0xf bound_ctrl:1
	v_mov_b32_dpp v111, v125 row_ror:1 row_mask:0xf bank_mask:0xf bound_ctrl:1
	v_cndmask_b32_e64 v133, v183, v137, s[6:7]
	v_cndmask_b32_e64 v132, v182, v136, s[6:7]
	v_pk_fma_f32 v[114:115], v[178:179], v[136:137], v[114:115]
	v_mov_b32_dpp v97, v124 row_ror:15 row_mask:0xf bank_mask:0xf bound_ctrl:1
	v_mov_b32_dpp v101, v125 row_ror:15 row_mask:0xf bank_mask:0xf bound_ctrl:1
	v_mov_b32_dpp v136, v106 row_ror:15 row_mask:0xf bank_mask:0xf bound_ctrl:1
	v_mov_b32_dpp v137, v107 row_ror:15 row_mask:0xf bank_mask:0xf bound_ctrl:1
	v_pk_fma_f32 v[134:135], v[116:117], v[110:111], v[130:131]
	v_pk_fma_f32 v[118:119], v[178:179], v[132:133], v[118:119]
	v_cndmask_b32_e64 v133, v101, v137, s[6:7]
	v_cndmask_b32_e64 v132, v97, v136, s[6:7]
	v_pk_fma_f32 v[124:125], v[128:129], v[124:125], v[134:135]
;     __device__ __forceinline__ void operator()(const f32x4 (&acc)[2][2][4][2], const Unit& u, int wr, int wc, int fr, int fq) const {
;     ...
;                     const f32x4 c0a = ct[cidx], c0b = ct[cidx + 1], c1a = ct[cidx + 2], c1b = ct[cidx + 3];
;                     const f32x2 wv0 = {c0a[0], c1a[0]}, wv1 = {c0a[1], c1a[1]}, wv2 = {c0a[2], c1a[2]}, bv = {c0a[3], c1a[3]};
;                     const f32x2 wg0 = {c0b[0], c1b[0]}, wg1 = {c0b[1], c1b[1]}, wg2 = {c0b[2], c1b[2]}, bg = {c0b[3], c1b[3]};
;                     f32x2 uv[4], ug[4], cv[4];
; #pragma unroll
;                     for (int m = 0; m < 4; ++m) { uv[m] = (f32x2){acc[ai][0][m][n][2 * jp], acc[ai][0][m][n][2 * jp + 1]}; ug[m] = (f32x2){acc[ai][1][m][n][2 * jp], acc[ai][1][m][n][2 * jp + 1]}; }
;                     asm volatile("" : "+v"(uv[0]), "+v"(uv[1]), "+v"(uv[2]), "+v"(uv[3]), "+v"(ug[0]), "+v"(ug[1]), "+v"(ug[2]), "+v"(ug[3]));
;                     {
;                         f32x2 rv[4], lv[4];
; #pragma unroll
;                         for (int m = 0; m < 4; ++m) { uv[m] = uv[m] * rs[m]; rv[m] = (f32x2){dpp_ror1(uv[m][0]), dpp_ror1(uv[m][1])}; lv[m] = (f32x2){dpp_ror15(uv[m][0]), dpp_ror15(uv[m][1])}; }
; #pragma unroll
;                         for (int m = 0; m < 4; ++m) { const f32x2 pv_ = (m > 0 && f0) ? rv[m > 0 ? m - 1 : 0] : rv[m], nv_ = (m < 3 && f15) ? lv[m < 3 ? m + 1 : 3] : lv[m];
;                             cv[m] = bv + wv0 * pv_ + wv1 * uv[m] + wv2 * nv_; }
;                     }
;                     asm volatile("" : "+v"(cv[0]), "+v"(cv[1]), "+v"(cv[2]), "+v"(cv[3]));
;                     {
;                         f32x2 rg[4], lg[4];
; #pragma unroll
;                         for (int m = 0; m < 4; ++m) { ug[m] = ug[m] * rs[m]; rg[m] = (f32x2){dpp_ror1(ug[m][0]), dpp_ror1(ug[m][1])}; lg[m] = (f32x2){dpp_ror15(ug[m][0]), dpp_ror15(ug[m][1])}; }
; #pragma unroll
;                         for (int m = 0; m < 4; ++m) { const f32x2 pg_ = (m > 0 && f0) ? rg[m > 0 ? m - 1 : 0] : rg[m], ng_ = (m < 3 && f15) ? lg[m < 3 ? m + 1 : 3] : lg[m];
;                             const f32x2 cgt = bg + wg0 * pg_ + wg1 * ug[m] + wg2 * ng_;
;                             const f32x2 e = cgt * (-LOG2E);
;                             const f32x2 d = (f32x2){__builtin_amdgcn_exp2f(e[0]), __builtin_amdgcn_exp2f(e[1])} + 1.f;
	v_mov_b32_dpp v105, v106 row_ror:1 row_mask:0xf bank_mask:0xf bound_ctrl:1
	v_pk_fma_f32 v[124:125], v[112:113], v[132:133], v[124:125]
	v_mov_b32_dpp v109, v107 row_ror:1 row_mask:0xf bank_mask:0xf bound_ctrl:1
	v_pk_mul_f32 v[132:133], v[124:125], s[76:77] op_sel_hi:[1,0]
	v_pk_mul_f32 v[102:103], v[174:175], v[102:103] op_sel_hi:[0,1]
	v_exp_f32_e32 v132, v132
	v_exp_f32_e32 v133, v133
	v_pk_mul_f32 v[122:123], v[122:123], v[124:125]
	v_cndmask_b32_e64 v111, v109, v111, s[4:5]
	v_cndmask_b32_e64 v110, v105, v110, s[4:5]
	v_pk_add_f32 v[132:133], v[132:133], 1.0 op_sel_hi:[1,0]
	v_mov_b32_dpp v140, v102 row_ror:15 row_mask:0xf bank_mask:0xf bound_ctrl:1
	v_rcp_f32_e32 v132, v132
	v_rcp_f32_e32 v133, v133
	v_mov_b32_dpp v141, v103 row_ror:15 row_mask:0xf bank_mask:0xf bound_ctrl:1
	v_pk_fma_f32 v[110:111], v[116:117], v[110:111], v[130:131]
	v_mov_b32_dpp v138, v102 row_ror:1 row_mask:0xf bank_mask:0xf bound_ctrl:1
	v_pk_mul_f32 v[122:123], v[122:123], v[132:133]
	v_pk_fma_f32 v[106:107], v[128:129], v[106:107], v[110:111]
	v_cvt_pk_bf16_f32 v97, v122, v123
	v_cndmask_b32_e64 v123, v137, v141, s[6:7]
	v_cndmask_b32_e64 v122, v136, v140, s[6:7]
	v_pk_fma_f32 v[106:107], v[112:113], v[122:123], v[106:107]
	v_mov_b32_dpp v139, v103 row_ror:1 row_mask:0xf bank_mask:0xf bound_ctrl:1
	v_pk_mul_f32 v[110:111], v[106:107], s[76:77] op_sel_hi:[1,0]
	v_pk_mul_f32 v[106:107], v[120:121], v[106:107]
	v_exp_f32_e32 v110, v110
	v_exp_f32_e32 v111, v111
	v_pk_mul_f32 v[98:99], v[176:177], v[98:99] op_sel_hi:[0,1]
	v_pk_add_f32 v[110:111], v[110:111], 1.0 op_sel_hi:[1,0]
	s_nop 0
	v_rcp_f32_e32 v110, v110
	v_rcp_f32_e32 v111, v111
	v_mov_b32_dpp v126, v98 row_ror:15 row_mask:0xf bank_mask:0xf bound_ctrl:1
	v_mov_b32_dpp v127, v99 row_ror:15 row_mask:0xf bank_mask:0xf bound_ctrl:1
	v_mov_b32_dpp v142, v98 row_ror:1 row_mask:0xf bank_mask:0xf bound_ctrl:1
	v_pk_mul_f32 v[106:107], v[106:107], v[110:111]
	v_cndmask_b32_e64 v111, v141, v127, s[6:7]
	v_cvt_pk_bf16_f32 v101, v106, v107
	v_cndmask_b32_e64 v107, v139, v109, s[4:5]
	v_cndmask_b32_e64 v106, v138, v105, s[4:5]
	v_pk_fma_f32 v[106:107], v[116:117], v[106:107], v[130:131]
	v_cndmask_b32_e64 v110, v140, v126, s[6:7]
	v_pk_fma_f32 v[102:103], v[128:129], v[102:103], v[106:107]
	v_mov_b32_dpp v143, v99 row_ror:1 row_mask:0xf bank_mask:0xf bound_ctrl:1
	v_pk_fma_f32 v[102:103], v[112:113], v[110:111], v[102:103]
	s_nop 0
	v_pk_mul_f32 v[106:107], v[102:103], s[76:77] op_sel_hi:[1,0]
	v_pk_mul_f32 v[102:103], v[118:119], v[102:103]
	v_exp_f32_e32 v106, v106
	v_exp_f32_e32 v107, v107
	s_nop 0
	v_pk_add_f32 v[106:107], v[106:107], 1.0 op_sel_hi:[1,0]
	s_nop 0
	v_rcp_f32_e32 v106, v106
	v_rcp_f32_e32 v107, v107
	s_nop 0
	v_pk_mul_f32 v[102:103], v[102:103], v[106:107]
	s_nop 0
	v_cvt_pk_bf16_f32 v105, v102, v103
	v_cndmask_b32_e64 v103, v143, v139, s[4:5]
	v_cndmask_b32_e64 v102, v142, v138, s[4:5]
	v_pk_fma_f32 v[102:103], v[116:117], v[102:103], v[130:131]
	s_nop 0
	v_pk_fma_f32 v[98:99], v[128:129], v[98:99], v[102:103]
	s_nop 0
	v_pk_fma_f32 v[98:99], v[112:113], v[126:127], v[98:99]
	s_nop 0
	v_pk_mul_f32 v[102:103], v[98:99], s[76:77] op_sel_hi:[1,0]
	v_pk_mul_f32 v[98:99], v[114:115], v[98:99]
	v_exp_f32_e32 v102, v102
	v_exp_f32_e32 v103, v103
	s_nop 0
	v_pk_add_f32 v[102:103], v[102:103], 1.0 op_sel_hi:[1,0]
	s_nop 0
	v_rcp_f32_e32 v102, v102
	v_rcp_f32_e32 v103, v103
	s_nop 0
	v_pk_mul_f32 v[98:99], v[98:99], v[102:103]
	s_nop 0
	v_cvt_pk_bf16_f32 v109, v98, v99
	global_load_dwordx4 v[114:117], v[170:171], off offset:144
	global_load_dwordx4 v[110:113], v[170:171], off offset:176
	global_load_dwordx4 v[122:125], v[170:171], off offset:128
	global_load_dwordx4 v[126:129], v[170:171], off offset:160
	s_waitcnt vmcnt(3)
	v_mov_b32_e32 v118, v116
	v_pk_mul_f32 v[92:93], v[172:173], v[92:93] op_sel_hi:[0,1]
	v_pk_mul_f32 v[88:89], v[144:145], v[88:89] op_sel_hi:[0,1]
	s_waitcnt vmcnt(1)
	v_mov_b32_e32 v98, v122
	s_waitcnt vmcnt(0)
	v_mov_b32_e32 v99, v126
	v_mov_b32_e32 v103, v128
	v_mov_b32_dpp v106, v92 row_ror:1 row_mask:0xf bank_mask:0xf bound_ctrl:1
	v_mov_b32_dpp v107, v93 row_ror:1 row_mask:0xf bank_mask:0xf bound_ctrl:1
	v_mov_b32_dpp v130, v88 row_ror:1 row_mask:0xf bank_mask:0xf bound_ctrl:1
	v_mov_b32_dpp v131, v89 row_ror:1 row_mask:0xf bank_mask:0xf bound_ctrl:1
	v_mov_b32_e32 v128, v125
	v_mov_b32_e32 v102, v124
	v_pk_mul_f32 v[84:85], v[174:175], v[84:85] op_sel_hi:[0,1]
	v_pk_fma_f32 v[124:125], v[98:99], v[106:107], v[128:129]
	v_cndmask_b32_e64 v107, v131, v107, s[4:5]
	v_cndmask_b32_e64 v106, v130, v106, s[4:5]
	v_mov_b32_e32 v126, v123
	v_mov_b32_dpp v134, v84 row_ror:1 row_mask:0xf bank_mask:0xf bound_ctrl:1
	v_mov_b32_dpp v135, v85 row_ror:1 row_mask:0xf bank_mask:0xf bound_ctrl:1
	v_pk_fma_f32 v[106:107], v[98:99], v[106:107], v[128:129]
	v_mov_b32_dpp v132, v88 row_ror:15 row_mask:0xf bank_mask:0xf bound_ctrl:1
	v_mov_b32_dpp v133, v89 row_ror:15 row_mask:0xf bank_mask:0xf bound_ctrl:1
	v_pk_mul_f32 v[80:81], v[176:177], v[80:81] op_sel_hi:[0,1]
	v_pk_fma_f32 v[88:89], v[126:127], v[88:89], v[106:107]
	v_cndmask_b32_e64 v107, v135, v131, s[4:5]
	v_cndmask_b32_e64 v106, v134, v130, s[4:5]
	v_mov_b32_dpp v138, v80 row_ror:1 row_mask:0xf bank_mask:0xf bound_ctrl:1
	v_mov_b32_dpp v139, v81 row_ror:1 row_mask:0xf bank_mask:0xf bound_ctrl:1
	v_pk_fma_f32 v[106:107], v[98:99], v[106:107], v[128:129]
	v_mov_b32_e32 v119, v112
	v_mov_b32_dpp v112, v92 row_ror:15 row_mask:0xf bank_mask:0xf bound_ctrl:1
	v_mov_b32_dpp v116, v93 row_ror:15 row_mask:0xf bank_mask:0xf bound_ctrl:1
	v_mov_b32_dpp v136, v84 row_ror:15 row_mask:0xf bank_mask:0xf bound_ctrl:1
;     __device__ __forceinline__ void operator()(const f32x4 (&acc)[2][2][4][2], const Unit& u, int wr, int wc, int fr, int fq) const {
;     ...
;                     const f32x4 c0a = ct[cidx], c0b = ct[cidx + 1], c1a = ct[cidx + 2], c1b = ct[cidx + 3];
;                     const f32x2 wv0 = {c0a[0], c1a[0]}, wv1 = {c0a[1], c1a[1]}, wv2 = {c0a[2], c1a[2]}, bv = {c0a[3], c1a[3]};
;                     const f32x2 wg0 = {c0b[0], c1b[0]}, wg1 = {c0b[1], c1b[1]}, wg2 = {c0b[2], c1b[2]}, bg = {c0b[3], c1b[3]};
;                     f32x2 uv[4], ug[4], cv[4];
; #pragma unroll
;                     for (int m = 0; m < 4; ++m) { uv[m] = (f32x2){acc[ai][0][m][n][2 * jp], acc[ai][0][m][n][2 * jp + 1]}; ug[m] = (f32x2){acc[ai][1][m][n][2 * jp], acc[ai][1][m][n][2 * jp + 1]}; }
;                     asm volatile("" : "+v"(uv[0]), "+v"(uv[1]), "+v"(uv[2]), "+v"(uv[3]), "+v"(ug[0]), "+v"(ug[1]), "+v"(ug[2]), "+v"(ug[3]));
;                     {
;                         f32x2 rv[4], lv[4];
; #pragma unroll
;                         for (int m = 0; m < 4; ++m) { uv[m] = uv[m] * rs[m]; rv[m] = (f32x2){dpp_ror1(uv[m][0]), dpp_ror1(uv[m][1])}; lv[m] = (f32x2){dpp_ror15(uv[m][0]), dpp_ror15(uv[m][1])}; }
; #pragma unroll
;                         for (int m = 0; m < 4; ++m) { const f32x2 pv_ = (m > 0 && f0) ? rv[m > 0 ? m - 1 : 0] : rv[m], nv_ = (m < 3 && f15) ? lv[m < 3 ? m + 1 : 3] : lv[m];
;                             cv[m] = bv + wv0 * pv_ + wv1 * uv[m] + wv2 * nv_; }
;                     }
;                     asm volatile("" : "+v"(cv[0]), "+v"(cv[1]), "+v"(cv[2]), "+v"(cv[3]));
;                     {
;                         f32x2 rg[4], lg[4];
; #pragma unroll
;                         for (int m = 0; m < 4; ++m) { ug[m] = ug[m] * rs[m]; rg[m] = (f32x2){dpp_ror1(ug[m][0]), dpp_ror1(ug[m][1])}; lg[m] = (f32x2){dpp_ror15(ug[m][0]), dpp_ror15(ug[m][1])}; }
; #pragma unroll
;                         for (int m = 0; m < 4; ++m) { const f32x2 pg_ = (m > 0 && f0) ? rg[m > 0 ? m - 1 : 0] : rg[m], ng_ = (m < 3 && f15) ? lg[m < 3 ? m + 1 : 3] : lg[m];
;                             const f32x2 cgt = bg + wg0 * pg_ + wg1 * ug[m] + wg2 * ng_;
;                             const f32x2 e = cgt * (-LOG2E);
;                             const f32x2 d = (f32x2){__builtin_amdgcn_exp2f(e[0]), __builtin_amdgcn_exp2f(e[1])} + 1.f;
	v_mov_b32_dpp v137, v85 row_ror:15 row_mask:0xf bank_mask:0xf bound_ctrl:1
	v_pk_fma_f32 v[84:85], v[126:127], v[84:85], v[106:107]
	v_cndmask_b32_e64 v107, v139, v135, s[4:5]
	v_cndmask_b32_e64 v106, v138, v134, s[4:5]
	v_cndmask_b32_e64 v123, v116, v133, s[6:7]
	v_cndmask_b32_e64 v122, v112, v132, s[6:7]
	v_pk_fma_f32 v[92:93], v[126:127], v[92:93], v[124:125]
	v_pk_fma_f32 v[98:99], v[98:99], v[106:107], v[128:129]
	v_mov_b32_e32 v120, v114
	v_mov_b32_e32 v121, v110
	v_mov_b32_e32 v110, v115
	v_mov_b32_dpp v114, v80 row_ror:15 row_mask:0xf bank_mask:0xf bound_ctrl:1
	v_mov_b32_dpp v115, v81 row_ror:15 row_mask:0xf bank_mask:0xf bound_ctrl:1
	v_pk_fma_f32 v[92:93], v[102:103], v[122:123], v[92:93]
	v_cndmask_b32_e64 v123, v133, v137, s[6:7]
	v_cndmask_b32_e64 v122, v132, v136, s[6:7]
	v_pk_fma_f32 v[80:81], v[126:127], v[80:81], v[98:99]
	v_pk_mul_f32 v[98:99], v[172:173], v[76:77] op_sel_hi:[0,1]
	v_pk_fma_f32 v[88:89], v[102:103], v[122:123], v[88:89]
	v_cndmask_b32_e64 v123, v137, v115, s[6:7]
	v_cndmask_b32_e64 v122, v136, v114, s[6:7]
	v_mov_b32_dpp v76, v98 row_ror:1 row_mask:0xf bank_mask:0xf bound_ctrl:1
	v_mov_b32_dpp v77, v99 row_ror:1 row_mask:0xf bank_mask:0xf bound_ctrl:1
	v_pk_mul_f32 v[72:73], v[144:145], v[72:73] op_sel_hi:[0,1]
	v_mov_b32_e32 v112, v117
	v_pk_fma_f32 v[84:85], v[102:103], v[122:123], v[84:85]
	v_pk_fma_f32 v[80:81], v[102:103], v[114:115], v[80:81]
	v_mov_b32_dpp v102, v98 row_ror:15 row_mask:0xf bank_mask:0xf bound_ctrl:1
	v_mov_b32_dpp v103, v99 row_ror:15 row_mask:0xf bank_mask:0xf bound_ctrl:1
	v_mov_b32_dpp v123, v72 row_ror:15 row_mask:0xf bank_mask:0xf bound_ctrl:1
	v_mov_b32_dpp v124, v73 row_ror:15 row_mask:0xf bank_mask:0xf bound_ctrl:1
	v_pk_fma_f32 v[106:107], v[120:121], v[76:77], v[112:113]
	v_cndmask_b32_e64 v103, v103, v124, s[6:7]
	v_cndmask_b32_e64 v102, v102, v123, s[6:7]
	v_pk_fma_f32 v[98:99], v[110:111], v[98:99], v[106:107]
	v_mov_b32_dpp v116, v72 row_ror:1 row_mask:0xf bank_mask:0xf bound_ctrl:1
	v_pk_fma_f32 v[98:99], v[118:119], v[102:103], v[98:99]
	v_mov_b32_dpp v122, v73 row_ror:1 row_mask:0xf bank_mask:0xf bound_ctrl:1
	v_pk_mul_f32 v[102:103], v[98:99], s[76:77] op_sel_hi:[1,0]
	v_pk_mul_f32 v[68:69], v[174:175], v[68:69] op_sel_hi:[0,1]
	v_exp_f32_e32 v102, v102
	v_exp_f32_e32 v103, v103
	v_pk_mul_f32 v[92:93], v[92:93], v[98:99]
	v_cndmask_b32_e64 v77, v122, v77, s[4:5]
	v_cndmask_b32_e64 v76, v116, v76, s[4:5]
	v_pk_add_f32 v[102:103], v[102:103], 1.0 op_sel_hi:[1,0]
	v_mov_b32_dpp v127, v68 row_ror:15 row_mask:0xf bank_mask:0xf bound_ctrl:1
	v_rcp_f32_e32 v102, v102
	v_rcp_f32_e32 v103, v103
	v_mov_b32_dpp v128, v69 row_ror:15 row_mask:0xf bank_mask:0xf bound_ctrl:1
	v_pk_fma_f32 v[76:77], v[120:121], v[76:77], v[112:113]
	v_mov_b32_dpp v125, v68 row_ror:1 row_mask:0xf bank_mask:0xf bound_ctrl:1
	v_pk_mul_f32 v[92:93], v[92:93], v[102:103]
	v_pk_fma_f32 v[72:73], v[110:111], v[72:73], v[76:77]
	v_cvt_pk_bf16_f32 v98, v92, v93
	v_cndmask_b32_e64 v93, v124, v128, s[6:7]
	v_cndmask_b32_e64 v92, v123, v127, s[6:7]
	v_pk_fma_f32 v[72:73], v[118:119], v[92:93], v[72:73]
	v_mov_b32_dpp v126, v69 row_ror:1 row_mask:0xf bank_mask:0xf bound_ctrl:1
	v_pk_mul_f32 v[76:77], v[72:73], s[76:77] op_sel_hi:[1,0]
	v_pk_mul_f32 v[72:73], v[88:89], v[72:73]
	v_exp_f32_e32 v76, v76
	v_exp_f32_e32 v77, v77
	v_pk_mul_f32 v[64:65], v[176:177], v[64:65] op_sel_hi:[0,1]
	v_pk_add_f32 v[76:77], v[76:77], 1.0 op_sel_hi:[1,0]
	s_nop 0
	v_rcp_f32_e32 v76, v76
	v_rcp_f32_e32 v77, v77
	v_mov_b32_dpp v114, v64 row_ror:15 row_mask:0xf bank_mask:0xf bound_ctrl:1
	v_mov_b32_dpp v115, v65 row_ror:15 row_mask:0xf bank_mask:0xf bound_ctrl:1
	v_mov_b32_dpp v129, v64 row_ror:1 row_mask:0xf bank_mask:0xf bound_ctrl:1
	v_pk_mul_f32 v[72:73], v[72:73], v[76:77]
	v_cndmask_b32_e64 v77, v128, v115, s[6:7]
	v_cvt_pk_bf16_f32 v102, v72, v73
	v_cndmask_b32_e64 v73, v126, v122, s[4:5]
	v_cndmask_b32_e64 v72, v125, v116, s[4:5]
	v_pk_fma_f32 v[72:73], v[120:121], v[72:73], v[112:113]
	v_cndmask_b32_e64 v76, v127, v114, s[6:7]
	v_pk_fma_f32 v[68:69], v[110:111], v[68:69], v[72:73]
	v_mov_b32_dpp v130, v65 row_ror:1 row_mask:0xf bank_mask:0xf bound_ctrl:1
	v_pk_fma_f32 v[68:69], v[118:119], v[76:77], v[68:69]
	s_nop 0
	v_pk_mul_f32 v[72:73], v[68:69], s[76:77] op_sel_hi:[1,0]
	v_pk_mul_f32 v[68:69], v[84:85], v[68:69]
	v_exp_f32_e32 v72, v72
	v_exp_f32_e32 v73, v73
	s_nop 0
	v_pk_add_f32 v[72:73], v[72:73], 1.0 op_sel_hi:[1,0]
	s_nop 0
	v_rcp_f32_e32 v72, v72
	v_rcp_f32_e32 v73, v73
	s_nop 0
	v_pk_mul_f32 v[68:69], v[68:69], v[72:73]
	s_nop 0
	v_cvt_pk_bf16_f32 v106, v68, v69
	v_cndmask_b32_e64 v69, v130, v126, s[4:5]
	v_cndmask_b32_e64 v68, v129, v125, s[4:5]
	v_pk_fma_f32 v[68:69], v[120:121], v[68:69], v[112:113]
	s_nop 0
	v_pk_fma_f32 v[64:65], v[110:111], v[64:65], v[68:69]
	s_nop 0
	v_pk_fma_f32 v[64:65], v[118:119], v[114:115], v[64:65]
	s_nop 0
	v_pk_mul_f32 v[68:69], v[64:65], s[76:77] op_sel_hi:[1,0]
	v_pk_mul_f32 v[64:65], v[80:81], v[64:65]
	v_exp_f32_e32 v68, v68
	v_exp_f32_e32 v69, v69
	s_nop 0
	v_pk_add_f32 v[68:69], v[68:69], 1.0 op_sel_hi:[1,0]
	s_nop 0
	v_rcp_f32_e32 v68, v68
	v_rcp_f32_e32 v69, v69
	s_nop 0
	v_pk_mul_f32 v[64:65], v[64:65], v[68:69]
	s_nop 0
	v_cvt_pk_bf16_f32 v110, v64, v65
	global_load_dwordx4 v[116:119], v[170:171], off offset:192
	global_load_dwordx4 v[120:123], v[170:171], off offset:224
	global_load_dwordx4 v[124:127], v[170:171], off offset:208
	global_load_dwordx4 v[112:115], v[170:171], off offset:240
	s_waitcnt vmcnt(3)
	v_mov_b32_e32 v134, v118
	v_pk_mul_f32 v[78:79], v[172:173], v[78:79] op_sel_hi:[0,1]
	v_pk_mul_f32 v[74:75], v[144:145], v[74:75] op_sel_hi:[0,1]
	s_waitcnt vmcnt(1)
;     __device__ __forceinline__ void operator()(const f32x4 (&acc)[2][2][4][2], const Unit& u, int wr, int wc, int fr, int fq) const {
;     ...
;                     const f32x4 c0a = ct[cidx], c0b = ct[cidx + 1], c1a = ct[cidx + 2], c1b = ct[cidx + 3];
;                     const f32x2 wv0 = {c0a[0], c1a[0]}, wv1 = {c0a[1], c1a[1]}, wv2 = {c0a[2], c1a[2]}, bv = {c0a[3], c1a[3]};
;                     const f32x2 wg0 = {c0b[0], c1b[0]}, wg1 = {c0b[1], c1b[1]}, wg2 = {c0b[2], c1b[2]}, bg = {c0b[3], c1b[3]};
;                     f32x2 uv[4], ug[4], cv[4];
; #pragma unroll
;                     for (int m = 0; m < 4; ++m) { uv[m] = (f32x2){acc[ai][0][m][n][2 * jp], acc[ai][0][m][n][2 * jp + 1]}; ug[m] = (f32x2){acc[ai][1][m][n][2 * jp], acc[ai][1][m][n][2 * jp + 1]}; }
;                     asm volatile("" : "+v"(uv[0]), "+v"(uv[1]), "+v"(uv[2]), "+v"(uv[3]), "+v"(ug[0]), "+v"(ug[1]), "+v"(ug[2]), "+v"(ug[3]));
;                     {
;                         f32x2 rv[4], lv[4];
; #pragma unroll
;                         for (int m = 0; m < 4; ++m) { uv[m] = uv[m] * rs[m]; rv[m] = (f32x2){dpp_ror1(uv[m][0]), dpp_ror1(uv[m][1])}; lv[m] = (f32x2){dpp_ror15(uv[m][0]), dpp_ror15(uv[m][1])}; }
; #pragma unroll
;                         for (int m = 0; m < 4; ++m) { const f32x2 pv_ = (m > 0 && f0) ? rv[m > 0 ? m - 1 : 0] : rv[m], nv_ = (m < 3 && f15) ? lv[m < 3 ? m + 1 : 3] : lv[m];
;                             cv[m] = bv + wv0 * pv_ + wv1 * uv[m] + wv2 * nv_; }
;                     }
;                     asm volatile("" : "+v"(cv[0]), "+v"(cv[1]), "+v"(cv[2]), "+v"(cv[3]));
;                     {
;                         f32x2 rg[4], lg[4];
; #pragma unroll
;                         for (int m = 0; m < 4; ++m) { ug[m] = ug[m] * rs[m]; rg[m] = (f32x2){dpp_ror1(ug[m][0]), dpp_ror1(ug[m][1])}; lg[m] = (f32x2){dpp_ror15(ug[m][0]), dpp_ror15(ug[m][1])}; }
; #pragma unroll
;                         for (int m = 0; m < 4; ++m) { const f32x2 pg_ = (m > 0 && f0) ? rg[m > 0 ? m - 1 : 0] : rg[m], ng_ = (m < 3 && f15) ? lg[m < 3 ? m + 1 : 3] : lg[m];
;                             const f32x2 cgt = bg + wg0 * pg_ + wg1 * ug[m] + wg2 * ng_;
;                             const f32x2 e = cgt * (-LOG2E);
;                             const f32x2 d = (f32x2){__builtin_amdgcn_exp2f(e[0]), __builtin_amdgcn_exp2f(e[1])} + 1.f;
	v_mov_b32_e32 v136, v124
	v_mov_b32_dpp v84, v78 row_ror:1 row_mask:0xf bank_mask:0xf bound_ctrl:1
	v_mov_b32_dpp v85, v79 row_ror:1 row_mask:0xf bank_mask:0xf bound_ctrl:1
	s_waitcnt vmcnt(0)
	v_mov_b32_e32 v137, v112
	v_mov_b32_e32 v139, v114
	v_mov_b32_e32 v114, v127
	v_pk_mul_f32 v[64:65], v[172:173], v[94:95] op_sel_hi:[0,1]
	v_pk_mul_f32 v[68:69], v[144:145], v[90:91] op_sel_hi:[0,1]
	v_mov_b32_dpp v130, v78 row_ror:15 row_mask:0xf bank_mask:0xf bound_ctrl:1
	v_mov_b32_dpp v131, v79 row_ror:15 row_mask:0xf bank_mask:0xf bound_ctrl:1
	v_mov_b32_dpp v142, v74 row_ror:15 row_mask:0xf bank_mask:0xf bound_ctrl:1
	v_mov_b32_dpp v143, v75 row_ror:15 row_mask:0xf bank_mask:0xf bound_ctrl:1
	v_mov_b32_e32 v135, v122
	v_mov_b32_e32 v112, v125
	v_mov_b32_e32 v122, v119
	v_pk_fma_f32 v[118:119], v[136:137], v[84:85], v[114:115]
	v_mov_b32_dpp v80, v64 row_ror:1 row_mask:0xf bank_mask:0xf bound_ctrl:1
	v_mov_b32_dpp v81, v65 row_ror:1 row_mask:0xf bank_mask:0xf bound_ctrl:1
	v_mov_b32_dpp v92, v68 row_ror:1 row_mask:0xf bank_mask:0xf bound_ctrl:1
	v_mov_b32_dpp v93, v69 row_ror:1 row_mask:0xf bank_mask:0xf bound_ctrl:1
	v_cndmask_b32_e64 v131, v131, v143, s[6:7]
	v_cndmask_b32_e64 v130, v130, v142, s[6:7]
	v_mov_b32_e32 v132, v116
	v_mov_b32_e32 v133, v120
	v_mov_b32_e32 v138, v126
	v_pk_fma_f32 v[78:79], v[112:113], v[78:79], v[118:119]
	v_cndmask_b32_e64 v89, v93, v81, s[4:5]
	v_cndmask_b32_e64 v88, v92, v80, s[4:5]
	v_mov_b32_e32 v120, v117
	v_pk_fma_f32 v[80:81], v[132:133], v[80:81], v[122:123]
	v_pk_fma_f32 v[78:79], v[138:139], v[130:131], v[78:79]
	v_pk_mul_f32 v[72:73], v[174:175], v[86:87] op_sel_hi:[0,1]
	v_mov_b32_dpp v86, v64 row_ror:15 row_mask:0xf bank_mask:0xf bound_ctrl:1
	v_mov_b32_dpp v87, v65 row_ror:15 row_mask:0xf bank_mask:0xf bound_ctrl:1
	v_pk_fma_f32 v[64:65], v[120:121], v[64:65], v[80:81]
	v_pk_mul_f32 v[80:81], v[78:79], s[76:77] op_sel_hi:[1,0]
	v_mov_b32_dpp v140, v74 row_ror:1 row_mask:0xf bank_mask:0xf bound_ctrl:1
	v_mov_b32_dpp v141, v75 row_ror:1 row_mask:0xf bank_mask:0xf bound_ctrl:1
	v_exp_f32_e32 v80, v80
	v_exp_f32_e32 v81, v81
	v_pk_mul_f32 v[76:77], v[176:177], v[82:83] op_sel_hi:[0,1]
	v_pk_mul_f32 v[70:71], v[174:175], v[70:71] op_sel_hi:[0,1]
	v_mov_b32_dpp v90, v68 row_ror:15 row_mask:0xf bank_mask:0xf bound_ctrl:1
	v_mov_b32_dpp v91, v69 row_ror:15 row_mask:0xf bank_mask:0xf bound_ctrl:1
	v_cndmask_b32_e64 v85, v141, v85, s[4:5]
	v_cndmask_b32_e64 v84, v140, v84, s[4:5]
	v_pk_mul_f32 v[66:67], v[176:177], v[66:67] op_sel_hi:[0,1]
	v_mov_b32_dpp v99, v72 row_ror:1 row_mask:0xf bank_mask:0xf bound_ctrl:1
	v_mov_b32_dpp v103, v73 row_ror:1 row_mask:0xf bank_mask:0xf bound_ctrl:1
	v_mov_b32_dpp v107, v76 row_ror:1 row_mask:0xf bank_mask:0xf bound_ctrl:1
	v_mov_b32_dpp v111, v77 row_ror:1 row_mask:0xf bank_mask:0xf bound_ctrl:1
	v_mov_b32_dpp v174, v70 row_ror:15 row_mask:0xf bank_mask:0xf bound_ctrl:1
	v_mov_b32_dpp v176, v71 row_ror:15 row_mask:0xf bank_mask:0xf bound_ctrl:1
	v_cndmask_b32_e64 v87, v87, v91, s[6:7]
	v_cndmask_b32_e64 v86, v86, v90, s[6:7]
	v_pk_fma_f32 v[84:85], v[136:137], v[84:85], v[114:115]
	v_cndmask_b32_e64 v93, v103, v93, s[4:5]
	v_cndmask_b32_e64 v92, v99, v92, s[4:5]
	v_cndmask_b32_e64 v129, v111, v103, s[4:5]
	v_cndmask_b32_e64 v128, v107, v99, s[4:5]
	v_pk_fma_f32 v[64:65], v[134:135], v[86:87], v[64:65]
	v_cndmask_b32_e64 v87, v143, v176, s[6:7]
	v_cndmask_b32_e64 v86, v142, v174, s[6:7]
	v_pk_fma_f32 v[74:75], v[112:113], v[74:75], v[84:85]
	v_mov_b32_dpp v94, v72 row_ror:15 row_mask:0xf bank_mask:0xf bound_ctrl:1
	v_mov_b32_dpp v95, v73 row_ror:15 row_mask:0xf bank_mask:0xf bound_ctrl:1
	v_mov_b32_dpp v82, v76 row_ror:15 row_mask:0xf bank_mask:0xf bound_ctrl:1
	v_mov_b32_dpp v83, v77 row_ror:15 row_mask:0xf bank_mask:0xf bound_ctrl:1
	v_pk_fma_f32 v[88:89], v[132:133], v[88:89], v[122:123]
	v_pk_fma_f32 v[92:93], v[132:133], v[92:93], v[122:123]
	v_pk_fma_f32 v[116:117], v[132:133], v[128:129], v[122:123]
	v_pk_add_f32 v[80:81], v[80:81], 1.0 op_sel_hi:[1,0]
	v_pk_fma_f32 v[74:75], v[138:139], v[86:87], v[74:75]
	v_cndmask_b32_e64 v91, v91, v95, s[6:7]
	v_cndmask_b32_e64 v90, v90, v94, s[6:7]
	v_cndmask_b32_e64 v95, v95, v83, s[6:7]
	v_cndmask_b32_e64 v94, v94, v82, s[6:7]
	v_pk_fma_f32 v[68:69], v[120:121], v[68:69], v[88:89]
	v_pk_fma_f32 v[72:73], v[120:121], v[72:73], v[92:93]
	v_pk_fma_f32 v[76:77], v[120:121], v[76:77], v[116:117]
	v_rcp_f32_e32 v80, v80
	v_rcp_f32_e32 v81, v81
	v_pk_mul_f32 v[84:85], v[74:75], s[76:77] op_sel_hi:[1,0]
	v_pk_fma_f32 v[68:69], v[134:135], v[90:91], v[68:69]
	v_pk_fma_f32 v[72:73], v[134:135], v[94:95], v[72:73]
	v_pk_fma_f32 v[76:77], v[134:135], v[82:83], v[76:77]
	v_exp_f32_e32 v84, v84
	v_exp_f32_e32 v85, v85
	v_mov_b32_dpp v144, v70 row_ror:1 row_mask:0xf bank_mask:0xf bound_ctrl:1
	v_pk_mul_f32 v[64:65], v[64:65], v[78:79]
	v_mov_b32_dpp v172, v71 row_ror:1 row_mask:0xf bank_mask:0xf bound_ctrl:1
	v_pk_mul_f32 v[64:65], v[64:65], v[80:81]
	v_cndmask_b32_e64 v79, v172, v141, s[4:5]
	v_cvt_pk_bf16_f32 v99, v64, v65
	v_pk_add_f32 v[64:65], v[84:85], 1.0 op_sel_hi:[1,0]
	v_cndmask_b32_e64 v78, v144, v140, s[4:5]
	v_rcp_f32_e32 v64, v64
	v_rcp_f32_e32 v65, v65
	v_mov_b32_dpp v178, v66 row_ror:1 row_mask:0xf bank_mask:0xf bound_ctrl:1
	v_mov_b32_dpp v88, v67 row_ror:1 row_mask:0xf bank_mask:0xf bound_ctrl:1
	v_mov_b32_dpp v82, v66 row_ror:15 row_mask:0xf bank_mask:0xf bound_ctrl:1
	v_mov_b32_dpp v83, v67 row_ror:15 row_mask:0xf bank_mask:0xf bound_ctrl:1
	v_pk_fma_f32 v[78:79], v[136:137], v[78:79], v[114:115]
	v_pk_mul_f32 v[68:69], v[68:69], v[74:75]
	v_cndmask_b32_e64 v81, v176, v83, s[6:7]
	v_cndmask_b32_e64 v80, v174, v82, s[6:7]
	v_pk_fma_f32 v[70:71], v[112:113], v[70:71], v[78:79]
	v_pk_mul_f32 v[64:65], v[68:69], v[64:65]
	v_cndmask_b32_e64 v69, v88, v172, s[4:5]
	v_cndmask_b32_e64 v68, v178, v144, s[4:5]
	v_pk_fma_f32 v[70:71], v[138:139], v[80:81], v[70:71]
	v_pk_fma_f32 v[68:69], v[136:137], v[68:69], v[114:115]
	v_pk_mul_f32 v[78:79], v[70:71], s[76:77] op_sel_hi:[1,0]
	v_pk_fma_f32 v[66:67], v[112:113], v[66:67], v[68:69]
	v_exp_f32_e32 v78, v78
	v_exp_f32_e32 v79, v79
	v_pk_fma_f32 v[66:67], v[138:139], v[82:83], v[66:67]
	v_cvt_pk_bf16_f32 v103, v64, v65
	v_pk_mul_f32 v[68:69], v[66:67], s[76:77] op_sel_hi:[1,0]
	v_pk_add_f32 v[64:65], v[78:79], 1.0 op_sel_hi:[1,0]
	v_exp_f32_e32 v68, v68
	v_exp_f32_e32 v69, v69
	v_rcp_f32_e32 v64, v64
	v_rcp_f32_e32 v65, v65
	v_pk_mul_f32 v[70:71], v[72:73], v[70:71]
	v_pk_add_f32 v[68:69], v[68:69], 1.0 op_sel_hi:[1,0]
	v_pk_mul_f32 v[64:65], v[70:71], v[64:65]
	v_rcp_f32_e32 v68, v68
	v_rcp_f32_e32 v69, v69
	v_cvt_pk_bf16_f32 v107, v64, v65
	v_pk_mul_f32 v[64:65], v[76:77], v[66:67]
	s_nop 0
	v_pk_mul_f32 v[64:65], v[64:65], v[68:69]
	s_nop 0
	v_cvt_pk_bf16_f32 v111, v64, v65
	v_cmp_gt_i32_e32 vcc, s51, v190
	s_and_b64 s[14:15], s[8:9], vcc
	v_lshlrev_b32_e32 v144, 1, v160
	s_and_saveexec_b64 s[2:3], s[14:15]
	s_cbranch_execz .LBB0_796
;     __device__ __forceinline__ void operator()(const f32x4 (&acc)[2][2][4][2], const Unit& u, int wr, int wc, int fr, int fq) const {
;     ...
;             for (int m = 0; m < 4; ++m) { const int i = 16 * m + fr, t = tbase + i;
;                 if (i >= 1 && i <= 62 && t < slen) { u32x4 w; w.x = outw[m][0][0]; w.y = outw[m][0][1]; w.z = outw[m][1][0]; w.w = outw[m][1][1];
;                     *(u32x4*)(Gout + (size_t)(seqbase + t) * DFF + 128 * u.pn + 32 * wc + 8 * fq) = w; } }
	v_add_u32_e32 v66, s29, v190
	v_mov_b64_e32 v[64:65], s[24:25]
	v_mad_i64_i32 v[64:65], s[14:15], v66, s73, v[64:65]
	v_lshl_add_u64 v[64:65], s[36:37], 1, v[64:65]
	s_lshl_b32 s84, s45, 1
	v_lshl_add_u64 v[64:65], v[64:65], 0, s[84:85]
	v_lshl_add_u64 v[64:65], v[64:65], 0, v[144:145]
	global_store_dwordx4 v[64:65], v[96:99], off

;     __device__ __forceinline__ void operator()(const f32x4 (&acc)[2][2][4][2], const Unit& u, int wr, int wc, int fr, int fq) const {
;     ...
;             const int tbase = t0 + 62 * (2 * ai + wr) - 1;
;             float rs[4];
; #pragma unroll
;             for (int m = 0; m < 4; ++m) { const int t = tbase + 16 * m + fr; const bool vin = (t >= 0) && (t < slen); const int grow = seqbase + (vin ? t : 0);
;                 const f32x4 p = *(const f32x4*)(PS + (size_t)grow * 16 + 4 * fq); float s = (p[0] + p[1]) + (p[2] + p[3]); s = bfly_add<16>(s); s = bfly_add<32>(s); rs[m] = vin ? rsqrtf(s * (1.f / DM) + EPS) : 0.f; }
;     ...
;                     const f32x4 c0a = ct[cidx], c0b = ct[cidx + 1], c1a = ct[cidx + 2], c1b = ct[cidx + 3];
.LBB0_802:
	s_or_b64 exec, exec, s[2:3]
	s_addk_i32 s52, 0x7c
	v_add_u32_e32 v81, s52, v161
	v_cmp_gt_u32_e32 vcc, s51, v81
	s_nop 1
	v_cndmask_b32_e32 v64, 0, v81, vcc
	v_add_u32_e32 v64, s29, v64
	v_ashrrev_i32_e32 v65, 31, v64
	v_lshlrev_b64 v[64:65], 6, v[64:65]
	v_lshl_add_u64 v[64:65], v[164:165], 0, v[64:65]
	global_load_dwordx4 v[64:67], v[64:65], off
	s_waitcnt vmcnt(0)
	v_mov_b32_e32 v68, v65
	v_mov_b32_e32 v69, v66
	v_mov_b32_e32 v65, v67
	v_pk_add_f32 v[64:65], v[68:69], v[64:65]
	s_nop 0
	v_add_f32_e32 v64, v64, v65
	v_mov_b32_e32 v65, v64
	s_nop 1
	v_permlane16_swap_b32_e32 v64, v65
	s_waitcnt lgkmcnt(0)
	v_add_f32_e32 v69, v64, v65
	v_add_u32_e32 v64, 16, v81
	v_cmp_gt_u32_e64 s[14:15], s51, v64
	v_mov_b32_e32 v71, v69
	s_nop 1
	v_permlane32_swap_b32_e32 v69, v71
	v_cndmask_b32_e64 v64, 0, v64, s[14:15]
	v_add_u32_e32 v64, s29, v64
	v_ashrrev_i32_e32 v65, 31, v64
	v_lshlrev_b64 v[64:65], 6, v[64:65]
	v_lshl_add_u64 v[64:65], v[164:165], 0, v[64:65]
	global_load_dwordx4 v[64:67], v[64:65], off
	s_waitcnt vmcnt(0)
	v_mov_b32_e32 v72, v65
	v_mov_b32_e32 v73, v66
	v_mov_b32_e32 v65, v67
	v_pk_add_f32 v[64:65], v[72:73], v[64:65]
	s_nop 0
	v_add_f32_e32 v64, v64, v65
	v_mov_b32_e32 v65, v64
	s_nop 1
	v_permlane16_swap_b32_e32 v64, v65
	s_waitcnt lgkmcnt(0)
	v_add_f32_e32 v68, v64, v65
	v_mov_b32_e32 v70, v68
	s_nop 1
	v_permlane32_swap_b32_e32 v68, v70
	v_pk_add_f32 v[64:65], v[68:69], v[70:71]
	v_mov_b64_e32 v[68:69], s[78:79]
	v_pk_fma_f32 v[64:65], v[64:65], s[82:83], v[68:69] op_sel_hi:[1,0,0]
	s_nop 0
	v_mul_f32_e32 v66, 0x4b800000, v65
	v_cmp_gt_f32_e64 s[20:21], s62, v65
	v_cmp_gt_f32_e64 s[18:19], s62, v64
	s_nop 0
	v_cndmask_b32_e64 v65, v65, v66, s[20:21]
	v_rsq_f32_e32 v65, v65
	s_nop 0
	v_mul_f32_e32 v66, 0x45800000, v65
	v_cndmask_b32_e64 v65, v65, v66, s[20:21]
	v_cndmask_b32_e32 v82, 0, v65, vcc
	v_mul_f32_e32 v65, 0x4b800000, v64
	v_cndmask_b32_e64 v64, v64, v65, s[18:19]
	v_rsq_f32_e32 v64, v64
	s_nop 0
	v_mul_f32_e32 v65, 0x45800000, v64
	v_cndmask_b32_e64 v64, v64, v65, s[18:19]
	v_cndmask_b32_e64 v80, 0, v64, s[14:15]
	v_add_u32_e32 v64, 32, v81
	v_cmp_gt_u32_e32 vcc, s51, v64
	s_nop 1
	v_cndmask_b32_e32 v64, 0, v64, vcc
	v_add_u32_e32 v64, s29, v64
	v_ashrrev_i32_e32 v65, 31, v64
	v_lshlrev_b64 v[64:65], 6, v[64:65]
	v_lshl_add_u64 v[64:65], v[164:165], 0, v[64:65]
	global_load_dwordx4 v[64:67], v[64:65], off
	s_waitcnt vmcnt(0)
	v_mov_b32_e32 v70, v65
	v_mov_b32_e32 v71, v66
	v_mov_b32_e32 v65, v67
	v_pk_add_f32 v[64:65], v[70:71], v[64:65]
	s_nop 0
	v_add_f32_e32 v64, v64, v65
	v_mov_b32_e32 v65, v64
	s_nop 1
	v_permlane16_swap_b32_e32 v64, v65
	s_waitcnt lgkmcnt(0)
	v_add_f32_e32 v71, v64, v65
	v_add_u32_e32 v64, 48, v81
	v_cmp_gt_u32_e64 s[14:15], s51, v64
	v_mov_b32_e32 v73, v71
	s_nop 1
	v_permlane32_swap_b32_e32 v71, v73
	v_cndmask_b32_e64 v64, 0, v64, s[14:15]
	v_add_u32_e32 v64, s29, v64
	v_ashrrev_i32_e32 v65, 31, v64
	v_lshlrev_b64 v[64:65], 6, v[64:65]
	v_lshl_add_u64 v[64:65], v[164:165], 0, v[64:65]
	global_load_dwordx4 v[64:67], v[64:65], off
	s_waitcnt vmcnt(0)
	v_mov_b32_e32 v74, v65
	v_mov_b32_e32 v75, v66
	v_mov_b32_e32 v65, v67
	v_pk_add_f32 v[64:65], v[74:75], v[64:65]
	s_nop 0
	v_add_f32_e32 v64, v64, v65
	v_mov_b32_e32 v65, v64
	s_nop 1
	v_permlane16_swap_b32_e32 v64, v65
	s_waitcnt lgkmcnt(0)
	v_add_f32_e32 v70, v64, v65
	v_mov_b32_e32 v72, v70
	s_nop 1
	v_permlane32_swap_b32_e32 v70, v72
	v_pk_add_f32 v[64:65], v[70:71], v[72:73]
	s_nop 0
	v_pk_fma_f32 v[64:65], v[64:65], s[82:83], v[68:69] op_sel_hi:[1,0,0]
	s_nop 0
	v_mul_f32_e32 v66, 0x4b800000, v65
	v_cmp_gt_f32_e64 s[20:21], s62, v65
	v_cmp_gt_f32_e64 s[18:19], s62, v64
	s_nop 0
	v_cndmask_b32_e64 v65, v65, v66, s[20:21]
	v_rsq_f32_e32 v65, v65
	s_nop 0
	v_mul_f32_e32 v66, 0x45800000, v65
	v_cndmask_b32_e64 v65, v65, v66, s[20:21]
	v_cndmask_b32_e32 v84, 0, v65, vcc
	v_mul_f32_e32 v65, 0x4b800000, v64
	v_cndmask_b32_e64 v64, v64, v65, s[18:19]
	v_rsq_f32_e32 v64, v64
	s_nop 0
	v_mul_f32_e32 v65, 0x45800000, v64
	v_cndmask_b32_e64 v64, v64, v65, s[18:19]
	v_cndmask_b32_e64 v86, 0, v64, s[14:15]
	global_load_dwordx4 v[68:71], v[170:171], off offset:16
	global_load_dwordx4 v[64:67], v[170:171], off offset:48
	global_load_dwordx4 v[76:79], v[170:171], off
	global_load_dwordx4 v[72:75], v[170:171], off offset:32
	s_waitcnt vmcnt(3)
	v_mov_b32_e32 v88, v68
	v_pk_mul_f32 v[60:61], v[82:83], v[60:61] op_sel_hi:[0,1]
	v_pk_mul_f32 v[56:57], v[56:57], v[80:81] op_sel_hi:[1,0]
	s_waitcnt vmcnt(1)
	v_mov_b32_e32 v92, v76
	s_waitcnt vmcnt(0)
;     __device__ __forceinline__ void operator()(const f32x4 (&acc)[2][2][4][2], const Unit& u, int wr, int wc, int fr, int fq) const {
;     ...
;                     const f32x4 c0a = ct[cidx], c0b = ct[cidx + 1], c1a = ct[cidx + 2], c1b = ct[cidx + 3];
;                     const f32x2 wv0 = {c0a[0], c1a[0]}, wv1 = {c0a[1], c1a[1]}, wv2 = {c0a[2], c1a[2]}, bv = {c0a[3], c1a[3]};
;                     const f32x2 wg0 = {c0b[0], c1b[0]}, wg1 = {c0b[1], c1b[1]}, wg2 = {c0b[2], c1b[2]}, bg = {c0b[3], c1b[3]};
;                     f32x2 uv[4], ug[4], cv[4];
; #pragma unroll
;                     for (int m = 0; m < 4; ++m) { uv[m] = (f32x2){acc[ai][0][m][n][2 * jp], acc[ai][0][m][n][2 * jp + 1]}; ug[m] = (f32x2){acc[ai][1][m][n][2 * jp], acc[ai][1][m][n][2 * jp + 1]}; }
;                     asm volatile("" : "+v"(uv[0]), "+v"(uv[1]), "+v"(uv[2]), "+v"(uv[3]), "+v"(ug[0]), "+v"(ug[1]), "+v"(ug[2]), "+v"(ug[3]));
;                     {
;                         f32x2 rv[4], lv[4];
; #pragma unroll
;                         for (int m = 0; m < 4; ++m) { uv[m] = uv[m] * rs[m]; rv[m] = (f32x2){dpp_ror1(uv[m][0]), dpp_ror1(uv[m][1])}; lv[m] = (f32x2){dpp_ror15(uv[m][0]), dpp_ror15(uv[m][1])}; }
; #pragma unroll
;                         for (int m = 0; m < 4; ++m) { const f32x2 pv_ = (m > 0 && f0) ? rv[m > 0 ? m - 1 : 0] : rv[m], nv_ = (m < 3 && f15) ? lv[m < 3 ? m + 1 : 3] : lv[m];
;                             cv[m] = bv + wv0 * pv_ + wv1 * uv[m] + wv2 * nv_; }
;                     }
;                     asm volatile("" : "+v"(cv[0]), "+v"(cv[1]), "+v"(cv[2]), "+v"(cv[3]));
;                     {
;                         f32x2 rg[4], lg[4];
; #pragma unroll
;                         for (int m = 0; m < 4; ++m) { ug[m] = ug[m] * rs[m]; rg[m] = (f32x2){dpp_ror1(ug[m][0]), dpp_ror1(ug[m][1])}; lg[m] = (f32x2){dpp_ror15(ug[m][0]), dpp_ror15(ug[m][1])}; }
; #pragma unroll
;                         for (int m = 0; m < 4; ++m) { const f32x2 pg_ = (m > 0 && f0) ? rg[m > 0 ? m - 1 : 0] : rg[m], ng_ = (m < 3 && f15) ? lg[m < 3 ? m + 1 : 3] : lg[m];
;                             const f32x2 cgt = bg + wg0 * pg_ + wg1 * ug[m] + wg2 * ng_;
;                             const f32x2 e = cgt * (-LOG2E);
;                             const f32x2 d = (f32x2){__builtin_amdgcn_exp2f(e[0]), __builtin_amdgcn_exp2f(e[1])} + 1.f;
	v_mov_b32_e32 v93, v72
	v_mov_b32_e32 v95, v74
	v_mov_b32_e32 v89, v64
	v_mov_b32_e32 v64, v69
	v_mov_b32_dpp v68, v60 row_ror:1 row_mask:0xf bank_mask:0xf bound_ctrl:1
	v_mov_b32_dpp v69, v61 row_ror:1 row_mask:0xf bank_mask:0xf bound_ctrl:1
	v_mov_b32_dpp v83, v56 row_ror:1 row_mask:0xf bank_mask:0xf bound_ctrl:1
	v_mov_b32_dpp v85, v57 row_ror:1 row_mask:0xf bank_mask:0xf bound_ctrl:1
	v_mov_b32_e32 v74, v79
	v_pk_mul_f32 v[52:53], v[52:53], v[84:85] op_sel_hi:[1,0]
	v_pk_fma_f32 v[96:97], v[92:93], v[68:69], v[74:75]
	v_cndmask_b32_e64 v69, v85, v69, s[4:5]
	v_cndmask_b32_e64 v68, v83, v68, s[4:5]
	v_mov_b32_e32 v72, v77
	v_mov_b32_dpp v87, v56 row_ror:15 row_mask:0xf bank_mask:0xf bound_ctrl:1
	v_mov_b32_dpp v99, v52 row_ror:1 row_mask:0xf bank_mask:0xf bound_ctrl:1
	v_mov_b32_dpp v100, v53 row_ror:1 row_mask:0xf bank_mask:0xf bound_ctrl:1
	v_pk_fma_f32 v[68:69], v[92:93], v[68:69], v[74:75]
	v_mov_b32_dpp v98, v57 row_ror:15 row_mask:0xf bank_mask:0xf bound_ctrl:1
	v_pk_mul_f32 v[48:49], v[48:49], v[86:87] op_sel_hi:[1,0]
	v_pk_fma_f32 v[56:57], v[72:73], v[56:57], v[68:69]
	v_cndmask_b32_e64 v69, v100, v85, s[4:5]
	v_cndmask_b32_e64 v68, v99, v83, s[4:5]
	v_mov_b32_e32 v90, v70
	v_mov_b32_e32 v91, v66
	v_mov_b32_dpp v66, v60 row_ror:15 row_mask:0xf bank_mask:0xf bound_ctrl:1
	v_mov_b32_dpp v70, v61 row_ror:15 row_mask:0xf bank_mask:0xf bound_ctrl:1
	v_mov_b32_dpp v103, v48 row_ror:1 row_mask:0xf bank_mask:0xf bound_ctrl:1
	v_mov_b32_dpp v104, v49 row_ror:1 row_mask:0xf bank_mask:0xf bound_ctrl:1
	v_pk_fma_f32 v[68:69], v[92:93], v[68:69], v[74:75]
	v_mov_b32_e32 v94, v78
	v_mov_b32_dpp v101, v52 row_ror:15 row_mask:0xf bank_mask:0xf bound_ctrl:1
	v_mov_b32_dpp v102, v53 row_ror:15 row_mask:0xf bank_mask:0xf bound_ctrl:1
	v_cndmask_b32_e64 v79, v70, v98, s[6:7]
	v_cndmask_b32_e64 v78, v66, v87, s[6:7]
	v_pk_fma_f32 v[60:61], v[72:73], v[60:61], v[96:97]
	v_pk_fma_f32 v[52:53], v[72:73], v[52:53], v[68:69]
	v_cndmask_b32_e64 v69, v104, v100, s[4:5]
	v_cndmask_b32_e64 v68, v103, v99, s[4:5]
	v_mov_b32_dpp v76, v48 row_ror:15 row_mask:0xf bank_mask:0xf bound_ctrl:1
	v_mov_b32_dpp v77, v49 row_ror:15 row_mask:0xf bank_mask:0xf bound_ctrl:1
	v_pk_fma_f32 v[60:61], v[94:95], v[78:79], v[60:61]
	v_cndmask_b32_e64 v79, v98, v102, s[6:7]
	v_cndmask_b32_e64 v78, v87, v101, s[6:7]
	v_pk_fma_f32 v[68:69], v[92:93], v[68:69], v[74:75]
	v_pk_mul_f32 v[44:45], v[82:83], v[44:45] op_sel_hi:[0,1]
	v_pk_mul_f32 v[40:41], v[40:41], v[80:81] op_sel_hi:[1,0]
	v_pk_fma_f32 v[56:57], v[94:95], v[78:79], v[56:57]
	v_cndmask_b32_e64 v79, v102, v77, s[6:7]
	v_cndmask_b32_e64 v78, v101, v76, s[6:7]
	v_pk_fma_f32 v[48:49], v[72:73], v[48:49], v[68:69]
	v_mov_b32_dpp v68, v44 row_ror:1 row_mask:0xf bank_mask:0xf bound_ctrl:1
	v_mov_b32_dpp v69, v45 row_ror:1 row_mask:0xf bank_mask:0xf bound_ctrl:1
	v_mov_b32_dpp v85, v40 row_ror:15 row_mask:0xf bank_mask:0xf bound_ctrl:1
	v_mov_b32_e32 v66, v71
	v_pk_fma_f32 v[52:53], v[94:95], v[78:79], v[52:53]
	v_mov_b32_dpp v70, v44 row_ror:15 row_mask:0xf bank_mask:0xf bound_ctrl:1
	v_mov_b32_dpp v78, v45 row_ror:15 row_mask:0xf bank_mask:0xf bound_ctrl:1
	v_mov_b32_dpp v87, v41 row_ror:15 row_mask:0xf bank_mask:0xf bound_ctrl:1
	v_pk_mul_f32 v[72:73], v[36:37], v[84:85] op_sel_hi:[1,0]
	v_pk_fma_f32 v[36:37], v[88:89], v[68:69], v[66:67]
	v_pk_mul_f32 v[74:75], v[32:33], v[86:87] op_sel_hi:[1,0]
	v_cndmask_b32_e64 v33, v78, v87, s[6:7]
	v_cndmask_b32_e64 v32, v70, v85, s[6:7]
	v_pk_fma_f32 v[36:37], v[64:65], v[44:45], v[36:37]
	v_pk_fma_f32 v[48:49], v[94:95], v[76:77], v[48:49]
	v_pk_fma_f32 v[32:33], v[90:91], v[32:33], v[36:37]
	v_mov_b32_dpp v79, v40 row_ror:1 row_mask:0xf bank_mask:0xf bound_ctrl:1
	v_pk_mul_f32 v[36:37], v[32:33], s[76:77] op_sel_hi:[1,0]
	v_mov_b32_dpp v83, v41 row_ror:1 row_mask:0xf bank_mask:0xf bound_ctrl:1
	v_exp_f32_e32 v36, v36
	v_exp_f32_e32 v37, v37
	v_pk_mul_f32 v[32:33], v[60:61], v[32:33]
	v_mov_b32_dpp v94, v72 row_ror:15 row_mask:0xf bank_mask:0xf bound_ctrl:1
	v_mov_b32_dpp v95, v73 row_ror:15 row_mask:0xf bank_mask:0xf bound_ctrl:1
	v_pk_add_f32 v[36:37], v[36:37], 1.0 op_sel_hi:[1,0]
	v_cndmask_b32_e64 v45, v87, v95, s[6:7]
	v_rcp_f32_e32 v36, v36
	v_rcp_f32_e32 v37, v37
	v_cndmask_b32_e64 v44, v85, v94, s[6:7]
	v_mov_b32_dpp v92, v72 row_ror:1 row_mask:0xf bank_mask:0xf bound_ctrl:1
	v_mov_b32_dpp v93, v73 row_ror:1 row_mask:0xf bank_mask:0xf bound_ctrl:1
	v_pk_mul_f32 v[32:33], v[32:33], v[36:37]
	v_cndmask_b32_e64 v37, v83, v69, s[4:5]
	v_cndmask_b32_e64 v36, v79, v68, s[4:5]
	v_pk_fma_f32 v[36:37], v[88:89], v[36:37], v[66:67]
	v_mov_b32_dpp v76, v74 row_ror:15 row_mask:0xf bank_mask:0xf bound_ctrl:1
	v_pk_fma_f32 v[36:37], v[64:65], v[40:41], v[36:37]
	v_mov_b32_dpp v77, v75 row_ror:15 row_mask:0xf bank_mask:0xf bound_ctrl:1
	v_pk_fma_f32 v[36:37], v[90:91], v[44:45], v[36:37]
	v_cndmask_b32_e64 v45, v95, v77, s[6:7]
	v_pk_mul_f32 v[40:41], v[36:37], s[76:77] op_sel_hi:[1,0]
	v_pk_mul_f32 v[36:37], v[56:57], v[36:37]
	v_exp_f32_e32 v40, v40
	v_exp_f32_e32 v41, v41
	v_cndmask_b32_e64 v44, v94, v76, s[6:7]
	v_mov_b32_dpp v96, v74 row_ror:1 row_mask:0xf bank_mask:0xf bound_ctrl:1
	v_mov_b32_dpp v97, v75 row_ror:1 row_mask:0xf bank_mask:0xf bound_ctrl:1
	v_pk_add_f32 v[40:41], v[40:41], 1.0 op_sel_hi:[1,0]
	v_cvt_pk_bf16_f32 v32, v32, v33
	v_rcp_f32_e32 v40, v40
	v_rcp_f32_e32 v41, v41
	s_nop 0
	v_pk_mul_f32 v[36:37], v[36:37], v[40:41]
	v_cndmask_b32_e64 v41, v93, v83, s[4:5]
	v_cndmask_b32_e64 v40, v92, v79, s[4:5]
	v_pk_fma_f32 v[40:41], v[88:89], v[40:41], v[66:67]
	v_cvt_pk_bf16_f32 v36, v36, v37
	v_pk_fma_f32 v[40:41], v[64:65], v[72:73], v[40:41]
	s_nop 0
	v_pk_fma_f32 v[40:41], v[90:91], v[44:45], v[40:41]
	s_nop 0
	v_pk_mul_f32 v[44:45], v[40:41], s[76:77] op_sel_hi:[1,0]
	v_pk_mul_f32 v[40:41], v[52:53], v[40:41]
	v_exp_f32_e32 v44, v44
	v_exp_f32_e32 v45, v45
	s_nop 0
	v_pk_add_f32 v[44:45], v[44:45], 1.0 op_sel_hi:[1,0]
	s_nop 0
	v_rcp_f32_e32 v44, v44
	v_rcp_f32_e32 v45, v45
	s_nop 0
	v_pk_mul_f32 v[40:41], v[40:41], v[44:45]
	v_cndmask_b32_e64 v45, v97, v93, s[4:5]
	v_cndmask_b32_e64 v44, v96, v92, s[4:5]
	v_pk_fma_f32 v[44:45], v[88:89], v[44:45], v[66:67]
	v_cvt_pk_bf16_f32 v40, v40, v41
	v_pk_fma_f32 v[44:45], v[64:65], v[74:75], v[44:45]
	s_nop 0
	v_pk_fma_f32 v[44:45], v[90:91], v[76:77], v[44:45]
	s_nop 0
	v_pk_mul_f32 v[52:53], v[44:45], s[76:77] op_sel_hi:[1,0]
	v_pk_mul_f32 v[44:45], v[48:49], v[44:45]
	v_exp_f32_e32 v52, v52
	v_exp_f32_e32 v53, v53
	s_nop 0
	v_pk_add_f32 v[52:53], v[52:53], 1.0 op_sel_hi:[1,0]
	s_nop 0
	v_rcp_f32_e32 v52, v52
	v_rcp_f32_e32 v53, v53
	s_nop 0
	v_pk_mul_f32 v[44:45], v[44:45], v[52:53]
	s_nop 0
	v_cvt_pk_bf16_f32 v44, v44, v45
	global_load_dwordx4 v[68:71], v[170:171], off offset:80
	global_load_dwordx4 v[64:67], v[170:171], off offset:112
	global_load_dwordx4 v[72:75], v[170:171], off offset:64
	global_load_dwordx4 v[76:79], v[170:171], off offset:96
	s_waitcnt vmcnt(3)
;     __device__ __forceinline__ void operator()(const f32x4 (&acc)[2][2][4][2], const Unit& u, int wr, int wc, int fr, int fq) const {
;     ...
;                     const f32x4 c0a = ct[cidx], c0b = ct[cidx + 1], c1a = ct[cidx + 2], c1b = ct[cidx + 3];
;                     const f32x2 wv0 = {c0a[0], c1a[0]}, wv1 = {c0a[1], c1a[1]}, wv2 = {c0a[2], c1a[2]}, bv = {c0a[3], c1a[3]};
;                     const f32x2 wg0 = {c0b[0], c1b[0]}, wg1 = {c0b[1], c1b[1]}, wg2 = {c0b[2], c1b[2]}, bg = {c0b[3], c1b[3]};
;                     f32x2 uv[4], ug[4], cv[4];
; #pragma unroll
;                     for (int m = 0; m < 4; ++m) { uv[m] = (f32x2){acc[ai][0][m][n][2 * jp], acc[ai][0][m][n][2 * jp + 1]}; ug[m] = (f32x2){acc[ai][1][m][n][2 * jp], acc[ai][1][m][n][2 * jp + 1]}; }
;                     asm volatile("" : "+v"(uv[0]), "+v"(uv[1]), "+v"(uv[2]), "+v"(uv[3]), "+v"(ug[0]), "+v"(ug[1]), "+v"(ug[2]), "+v"(ug[3]));
;                     {
;                         f32x2 rv[4], lv[4];
; #pragma unroll
;                         for (int m = 0; m < 4; ++m) { uv[m] = uv[m] * rs[m]; rv[m] = (f32x2){dpp_ror1(uv[m][0]), dpp_ror1(uv[m][1])}; lv[m] = (f32x2){dpp_ror15(uv[m][0]), dpp_ror15(uv[m][1])}; }
; #pragma unroll
;                         for (int m = 0; m < 4; ++m) { const f32x2 pv_ = (m > 0 && f0) ? rv[m > 0 ? m - 1 : 0] : rv[m], nv_ = (m < 3 && f15) ? lv[m < 3 ? m + 1 : 3] : lv[m];
;                             cv[m] = bv + wv0 * pv_ + wv1 * uv[m] + wv2 * nv_; }
;                     }
;                     asm volatile("" : "+v"(cv[0]), "+v"(cv[1]), "+v"(cv[2]), "+v"(cv[3]));
;                     {
;                         f32x2 rg[4], lg[4];
; #pragma unroll
;                         for (int m = 0; m < 4; ++m) { ug[m] = ug[m] * rs[m]; rg[m] = (f32x2){dpp_ror1(ug[m][0]), dpp_ror1(ug[m][1])}; lg[m] = (f32x2){dpp_ror15(ug[m][0]), dpp_ror15(ug[m][1])}; }
; #pragma unroll
;                         for (int m = 0; m < 4; ++m) { const f32x2 pg_ = (m > 0 && f0) ? rg[m > 0 ? m - 1 : 0] : rg[m], ng_ = (m < 3 && f15) ? lg[m < 3 ? m + 1 : 3] : lg[m];
;                             const f32x2 cgt = bg + wg0 * pg_ + wg1 * ug[m] + wg2 * ng_;
;                             const f32x2 e = cgt * (-LOG2E);
;                             const f32x2 d = (f32x2){__builtin_amdgcn_exp2f(e[0]), __builtin_amdgcn_exp2f(e[1])} + 1.f;
	v_mov_b32_e32 v52, v68
	v_pk_mul_f32 v[56:57], v[82:83], v[62:63] op_sel_hi:[0,1]
	s_waitcnt vmcnt(1)
	v_mov_b32_e32 v60, v72
	s_waitcnt vmcnt(0)
	v_mov_b32_e32 v61, v76
	v_mov_b32_e32 v89, v78
	v_mov_b32_e32 v53, v64
	v_mov_b32_e32 v64, v69
	v_mov_b32_dpp v62, v56 row_ror:1 row_mask:0xf bank_mask:0xf bound_ctrl:1
	v_mov_b32_dpp v63, v57 row_ror:1 row_mask:0xf bank_mask:0xf bound_ctrl:1
	v_pk_mul_f32 v[68:69], v[80:81], v[58:59] op_sel_hi:[0,1]
	v_mov_b32_e32 v78, v75
	v_mov_b32_e32 v88, v74
	v_mov_b32_e32 v48, v70
	v_mov_b32_e32 v49, v66
	v_mov_b32_e32 v76, v73
	v_mov_b32_dpp v33, v56 row_ror:15 row_mask:0xf bank_mask:0xf bound_ctrl:1
	v_mov_b32_dpp v37, v57 row_ror:15 row_mask:0xf bank_mask:0xf bound_ctrl:1
	v_mov_b32_dpp v66, v68 row_ror:15 row_mask:0xf bank_mask:0xf bound_ctrl:1
	v_mov_b32_dpp v70, v69 row_ror:15 row_mask:0xf bank_mask:0xf bound_ctrl:1
	v_pk_fma_f32 v[74:75], v[60:61], v[62:63], v[78:79]
	v_mov_b32_dpp v41, v68 row_ror:1 row_mask:0xf bank_mask:0xf bound_ctrl:1
	v_mov_b32_dpp v45, v69 row_ror:1 row_mask:0xf bank_mask:0xf bound_ctrl:1
	v_cndmask_b32_e64 v59, v37, v70, s[6:7]
	v_cndmask_b32_e64 v58, v33, v66, s[6:7]
	v_pk_fma_f32 v[56:57], v[76:77], v[56:57], v[74:75]
	v_pk_mul_f32 v[54:55], v[84:85], v[54:55] op_sel_hi:[0,1]
	v_pk_fma_f32 v[58:59], v[88:89], v[58:59], v[56:57]
	v_cndmask_b32_e64 v57, v45, v63, s[4:5]
	v_cndmask_b32_e64 v56, v41, v62, s[4:5]
	v_mov_b32_dpp v87, v54 row_ror:15 row_mask:0xf bank_mask:0xf bound_ctrl:1
	v_mov_b32_dpp v90, v55 row_ror:15 row_mask:0xf bank_mask:0xf bound_ctrl:1
	v_pk_fma_f32 v[56:57], v[60:61], v[56:57], v[78:79]
	v_mov_b32_dpp v83, v54 row_ror:1 row_mask:0xf bank_mask:0xf bound_ctrl:1
	v_mov_b32_dpp v85, v55 row_ror:1 row_mask:0xf bank_mask:0xf bound_ctrl:1
	v_cndmask_b32_e64 v63, v70, v90, s[6:7]
	v_cndmask_b32_e64 v62, v66, v87, s[6:7]
	v_pk_fma_f32 v[56:57], v[76:77], v[68:69], v[56:57]
	v_pk_mul_f32 v[50:51], v[86:87], v[50:51] op_sel_hi:[0,1]
	v_pk_fma_f32 v[56:57], v[88:89], v[62:63], v[56:57]
	v_cndmask_b32_e64 v63, v85, v45, s[4:5]
	v_cndmask_b32_e64 v62, v83, v41, s[4:5]
	v_mov_b32_dpp v91, v50 row_ror:1 row_mask:0xf bank_mask:0xf bound_ctrl:1
	v_mov_b32_dpp v92, v51 row_ror:1 row_mask:0xf bank_mask:0xf bound_ctrl:1
	v_pk_fma_f32 v[62:63], v[60:61], v[62:63], v[78:79]
	v_mov_b32_dpp v72, v50 row_ror:15 row_mask:0xf bank_mask:0xf bound_ctrl:1
	v_pk_fma_f32 v[54:55], v[76:77], v[54:55], v[62:63]
	v_cndmask_b32_e64 v63, v92, v85, s[4:5]
	v_cndmask_b32_e64 v62, v91, v83, s[4:5]
	v_pk_fma_f32 v[60:61], v[60:61], v[62:63], v[78:79]
	v_mov_b32_dpp v73, v51 row_ror:15 row_mask:0xf bank_mask:0xf bound_ctrl:1
	v_pk_fma_f32 v[50:51], v[76:77], v[50:51], v[60:61]
	v_pk_mul_f32 v[60:61], v[82:83], v[46:47] op_sel_hi:[0,1]
	v_pk_mul_f32 v[42:43], v[80:81], v[42:43] op_sel_hi:[0,1]
	v_mov_b32_e32 v66, v71
	v_mov_b32_dpp v46, v60 row_ror:1 row_mask:0xf bank_mask:0xf bound_ctrl:1
	v_mov_b32_dpp v47, v61 row_ror:1 row_mask:0xf bank_mask:0xf bound_ctrl:1
	v_cndmask_b32_e64 v69, v90, v73, s[6:7]
	v_cndmask_b32_e64 v68, v87, v72, s[6:7]
	v_pk_fma_f32 v[50:51], v[88:89], v[72:73], v[50:51]
	v_mov_b32_dpp v33, v60 row_ror:15 row_mask:0xf bank_mask:0xf bound_ctrl:1
	v_mov_b32_dpp v37, v61 row_ror:15 row_mask:0xf bank_mask:0xf bound_ctrl:1
	v_mov_b32_dpp v72, v42 row_ror:15 row_mask:0xf bank_mask:0xf bound_ctrl:1
	v_mov_b32_dpp v73, v43 row_ror:15 row_mask:0xf bank_mask:0xf bound_ctrl:1
	v_pk_fma_f32 v[70:71], v[52:53], v[46:47], v[66:67]
	v_pk_fma_f32 v[54:55], v[88:89], v[68:69], v[54:55]
	v_cndmask_b32_e64 v69, v37, v73, s[6:7]
	v_cndmask_b32_e64 v68, v33, v72, s[6:7]
	v_pk_fma_f32 v[60:61], v[64:65], v[60:61], v[70:71]
	v_mov_b32_dpp v41, v42 row_ror:1 row_mask:0xf bank_mask:0xf bound_ctrl:1
	v_pk_fma_f32 v[60:61], v[48:49], v[68:69], v[60:61]
	v_mov_b32_dpp v45, v43 row_ror:1 row_mask:0xf bank_mask:0xf bound_ctrl:1
	v_pk_mul_f32 v[68:69], v[60:61], s[76:77] op_sel_hi:[1,0]
	v_pk_mul_f32 v[38:39], v[84:85], v[38:39] op_sel_hi:[0,1]
	v_exp_f32_e32 v68, v68
	v_exp_f32_e32 v69, v69
	v_pk_mul_f32 v[58:59], v[58:59], v[60:61]
	v_cndmask_b32_e64 v47, v45, v47, s[4:5]
	v_cndmask_b32_e64 v46, v41, v46, s[4:5]
	v_pk_add_f32 v[68:69], v[68:69], 1.0 op_sel_hi:[1,0]
	v_mov_b32_dpp v76, v38 row_ror:15 row_mask:0xf bank_mask:0xf bound_ctrl:1
	v_rcp_f32_e32 v68, v68
	v_rcp_f32_e32 v69, v69
	v_mov_b32_dpp v77, v39 row_ror:15 row_mask:0xf bank_mask:0xf bound_ctrl:1
	v_pk_fma_f32 v[46:47], v[52:53], v[46:47], v[66:67]
	v_mov_b32_dpp v74, v38 row_ror:1 row_mask:0xf bank_mask:0xf bound_ctrl:1
	v_pk_mul_f32 v[58:59], v[58:59], v[68:69]
	v_pk_fma_f32 v[42:43], v[64:65], v[42:43], v[46:47]
	v_cvt_pk_bf16_f32 v33, v58, v59
	v_cndmask_b32_e64 v59, v73, v77, s[6:7]
	v_cndmask_b32_e64 v58, v72, v76, s[6:7]
	v_pk_fma_f32 v[42:43], v[48:49], v[58:59], v[42:43]
	v_mov_b32_dpp v75, v39 row_ror:1 row_mask:0xf bank_mask:0xf bound_ctrl:1
	v_pk_mul_f32 v[46:47], v[42:43], s[76:77] op_sel_hi:[1,0]
	v_pk_mul_f32 v[42:43], v[56:57], v[42:43]
	v_exp_f32_e32 v46, v46
	v_exp_f32_e32 v47, v47
	v_pk_mul_f32 v[34:35], v[86:87], v[34:35] op_sel_hi:[0,1]
	v_pk_add_f32 v[46:47], v[46:47], 1.0 op_sel_hi:[1,0]
	s_nop 0
	v_rcp_f32_e32 v46, v46
	v_rcp_f32_e32 v47, v47
	v_mov_b32_dpp v62, v34 row_ror:15 row_mask:0xf bank_mask:0xf bound_ctrl:1
	v_mov_b32_dpp v63, v35 row_ror:15 row_mask:0xf bank_mask:0xf bound_ctrl:1
	v_mov_b32_dpp v78, v34 row_ror:1 row_mask:0xf bank_mask:0xf bound_ctrl:1
	v_pk_mul_f32 v[42:43], v[42:43], v[46:47]
	v_cndmask_b32_e64 v47, v77, v63, s[6:7]
	v_cvt_pk_bf16_f32 v37, v42, v43
	v_cndmask_b32_e64 v43, v75, v45, s[4:5]
	v_cndmask_b32_e64 v42, v74, v41, s[4:5]
	v_pk_fma_f32 v[42:43], v[52:53], v[42:43], v[66:67]
;     __device__ __forceinline__ void operator()(const f32x4 (&acc)[2][2][4][2], const Unit& u, int wr, int wc, int fr, int fq) const {
;     ...
;                     const f32x4 c0a = ct[cidx], c0b = ct[cidx + 1], c1a = ct[cidx + 2], c1b = ct[cidx + 3];
;                     const f32x2 wv0 = {c0a[0], c1a[0]}, wv1 = {c0a[1], c1a[1]}, wv2 = {c0a[2], c1a[2]}, bv = {c0a[3], c1a[3]};
;                     const f32x2 wg0 = {c0b[0], c1b[0]}, wg1 = {c0b[1], c1b[1]}, wg2 = {c0b[2], c1b[2]}, bg = {c0b[3], c1b[3]};
;                     f32x2 uv[4], ug[4], cv[4];
; #pragma unroll
;                     for (int m = 0; m < 4; ++m) { uv[m] = (f32x2){acc[ai][0][m][n][2 * jp], acc[ai][0][m][n][2 * jp + 1]}; ug[m] = (f32x2){acc[ai][1][m][n][2 * jp], acc[ai][1][m][n][2 * jp + 1]}; }
;                     asm volatile("" : "+v"(uv[0]), "+v"(uv[1]), "+v"(uv[2]), "+v"(uv[3]), "+v"(ug[0]), "+v"(ug[1]), "+v"(ug[2]), "+v"(ug[3]));
;                     {
;                         f32x2 rv[4], lv[4];
; #pragma unroll
;                         for (int m = 0; m < 4; ++m) { uv[m] = uv[m] * rs[m]; rv[m] = (f32x2){dpp_ror1(uv[m][0]), dpp_ror1(uv[m][1])}; lv[m] = (f32x2){dpp_ror15(uv[m][0]), dpp_ror15(uv[m][1])}; }
; #pragma unroll
;                         for (int m = 0; m < 4; ++m) { const f32x2 pv_ = (m > 0 && f0) ? rv[m > 0 ? m - 1 : 0] : rv[m], nv_ = (m < 3 && f15) ? lv[m < 3 ? m + 1 : 3] : lv[m];
;                             cv[m] = bv + wv0 * pv_ + wv1 * uv[m] + wv2 * nv_; }
;                     }
;                     asm volatile("" : "+v"(cv[0]), "+v"(cv[1]), "+v"(cv[2]), "+v"(cv[3]));
;                     {
;                         f32x2 rg[4], lg[4];
; #pragma unroll
;                         for (int m = 0; m < 4; ++m) { ug[m] = ug[m] * rs[m]; rg[m] = (f32x2){dpp_ror1(ug[m][0]), dpp_ror1(ug[m][1])}; lg[m] = (f32x2){dpp_ror15(ug[m][0]), dpp_ror15(ug[m][1])}; }
; #pragma unroll
;                         for (int m = 0; m < 4; ++m) { const f32x2 pg_ = (m > 0 && f0) ? rg[m > 0 ? m - 1 : 0] : rg[m], ng_ = (m < 3 && f15) ? lg[m < 3 ? m + 1 : 3] : lg[m];
;                             const f32x2 cgt = bg + wg0 * pg_ + wg1 * ug[m] + wg2 * ng_;
;                             const f32x2 e = cgt * (-LOG2E);
;                             const f32x2 d = (f32x2){__builtin_amdgcn_exp2f(e[0]), __builtin_amdgcn_exp2f(e[1])} + 1.f;
	v_cndmask_b32_e64 v46, v76, v62, s[6:7]
	v_pk_fma_f32 v[38:39], v[64:65], v[38:39], v[42:43]
	v_mov_b32_dpp v79, v35 row_ror:1 row_mask:0xf bank_mask:0xf bound_ctrl:1
	v_pk_fma_f32 v[38:39], v[48:49], v[46:47], v[38:39]
	s_nop 0
	v_pk_mul_f32 v[42:43], v[38:39], s[76:77] op_sel_hi:[1,0]
	v_pk_mul_f32 v[38:39], v[54:55], v[38:39]
	v_exp_f32_e32 v42, v42
	v_exp_f32_e32 v43, v43
	s_nop 0
	v_pk_add_f32 v[42:43], v[42:43], 1.0 op_sel_hi:[1,0]
	s_nop 0
	v_rcp_f32_e32 v42, v42
	v_rcp_f32_e32 v43, v43
	s_nop 0
	v_pk_mul_f32 v[38:39], v[38:39], v[42:43]
	s_nop 0
	v_cvt_pk_bf16_f32 v41, v38, v39
	v_cndmask_b32_e64 v39, v79, v75, s[4:5]
	v_cndmask_b32_e64 v38, v78, v74, s[4:5]
	v_pk_fma_f32 v[38:39], v[52:53], v[38:39], v[66:67]
	s_nop 0
	v_pk_fma_f32 v[34:35], v[64:65], v[34:35], v[38:39]
	s_nop 0
	v_pk_fma_f32 v[34:35], v[48:49], v[62:63], v[34:35]
	s_nop 0
	v_pk_mul_f32 v[38:39], v[34:35], s[76:77] op_sel_hi:[1,0]
	v_pk_mul_f32 v[34:35], v[50:51], v[34:35]
	v_exp_f32_e32 v38, v38
	v_exp_f32_e32 v39, v39
	s_nop 0
	v_pk_add_f32 v[38:39], v[38:39], 1.0 op_sel_hi:[1,0]
	s_nop 0
	v_rcp_f32_e32 v38, v38
	v_rcp_f32_e32 v39, v39
	s_nop 0
	v_pk_mul_f32 v[34:35], v[34:35], v[38:39]
	s_nop 0
	v_cvt_pk_bf16_f32 v45, v34, v35
	global_load_dwordx4 v[50:53], v[170:171], off offset:144
	global_load_dwordx4 v[46:49], v[170:171], off offset:176
	global_load_dwordx4 v[58:61], v[170:171], off offset:128
	global_load_dwordx4 v[62:65], v[170:171], off offset:160
	s_waitcnt vmcnt(3)
	v_mov_b32_e32 v54, v52
	v_pk_mul_f32 v[28:29], v[82:83], v[28:29] op_sel_hi:[0,1]
	v_pk_mul_f32 v[24:25], v[80:81], v[24:25] op_sel_hi:[0,1]
	s_waitcnt vmcnt(1)
	v_mov_b32_e32 v34, v58
	s_waitcnt vmcnt(0)
	v_mov_b32_e32 v35, v62
	v_mov_b32_e32 v39, v64
	v_mov_b32_dpp v42, v28 row_ror:1 row_mask:0xf bank_mask:0xf bound_ctrl:1
	v_mov_b32_dpp v43, v29 row_ror:1 row_mask:0xf bank_mask:0xf bound_ctrl:1
	v_mov_b32_dpp v66, v24 row_ror:1 row_mask:0xf bank_mask:0xf bound_ctrl:1
	v_mov_b32_dpp v67, v25 row_ror:1 row_mask:0xf bank_mask:0xf bound_ctrl:1
	v_mov_b32_e32 v64, v61
	v_mov_b32_e32 v38, v60
	v_pk_mul_f32 v[20:21], v[84:85], v[20:21] op_sel_hi:[0,1]
	v_pk_fma_f32 v[60:61], v[34:35], v[42:43], v[64:65]
	v_cndmask_b32_e64 v43, v67, v43, s[4:5]
	v_cndmask_b32_e64 v42, v66, v42, s[4:5]
	v_mov_b32_e32 v62, v59
	v_mov_b32_dpp v70, v20 row_ror:1 row_mask:0xf bank_mask:0xf bound_ctrl:1
	v_mov_b32_dpp v71, v21 row_ror:1 row_mask:0xf bank_mask:0xf bound_ctrl:1
	v_pk_fma_f32 v[42:43], v[34:35], v[42:43], v[64:65]
	v_mov_b32_dpp v68, v24 row_ror:15 row_mask:0xf bank_mask:0xf bound_ctrl:1
	v_mov_b32_dpp v69, v25 row_ror:15 row_mask:0xf bank_mask:0xf bound_ctrl:1
	v_pk_mul_f32 v[16:17], v[86:87], v[16:17] op_sel_hi:[0,1]
	v_pk_fma_f32 v[24:25], v[62:63], v[24:25], v[42:43]
	v_cndmask_b32_e64 v43, v71, v67, s[4:5]
	v_cndmask_b32_e64 v42, v70, v66, s[4:5]
	v_mov_b32_dpp v74, v16 row_ror:1 row_mask:0xf bank_mask:0xf bound_ctrl:1
	v_mov_b32_dpp v75, v17 row_ror:1 row_mask:0xf bank_mask:0xf bound_ctrl:1
	v_pk_fma_f32 v[42:43], v[34:35], v[42:43], v[64:65]
	v_mov_b32_e32 v55, v48
	v_mov_b32_dpp v48, v28 row_ror:15 row_mask:0xf bank_mask:0xf bound_ctrl:1
	v_mov_b32_dpp v52, v29 row_ror:15 row_mask:0xf bank_mask:0xf bound_ctrl:1
	v_mov_b32_dpp v72, v20 row_ror:15 row_mask:0xf bank_mask:0xf bound_ctrl:1
	v_mov_b32_dpp v73, v21 row_ror:15 row_mask:0xf bank_mask:0xf bound_ctrl:1
	v_pk_fma_f32 v[20:21], v[62:63], v[20:21], v[42:43]
	v_cndmask_b32_e64 v43, v75, v71, s[4:5]
	v_cndmask_b32_e64 v42, v74, v70, s[4:5]
	v_cndmask_b32_e64 v59, v52, v69, s[6:7]
	v_cndmask_b32_e64 v58, v48, v68, s[6:7]
	v_pk_fma_f32 v[28:29], v[62:63], v[28:29], v[60:61]
	v_pk_fma_f32 v[34:35], v[34:35], v[42:43], v[64:65]
	v_mov_b32_e32 v56, v50
	v_mov_b32_e32 v57, v46
	v_mov_b32_e32 v46, v51
	v_mov_b32_dpp v50, v16 row_ror:15 row_mask:0xf bank_mask:0xf bound_ctrl:1
	v_mov_b32_dpp v51, v17 row_ror:15 row_mask:0xf bank_mask:0xf bound_ctrl:1
	v_pk_fma_f32 v[28:29], v[38:39], v[58:59], v[28:29]
	v_cndmask_b32_e64 v59, v69, v73, s[6:7]
	v_cndmask_b32_e64 v58, v68, v72, s[6:7]
	v_pk_fma_f32 v[16:17], v[62:63], v[16:17], v[34:35]
	v_pk_mul_f32 v[34:35], v[82:83], v[12:13] op_sel_hi:[0,1]
	v_pk_fma_f32 v[24:25], v[38:39], v[58:59], v[24:25]
	v_cndmask_b32_e64 v59, v73, v51, s[6:7]
	v_cndmask_b32_e64 v58, v72, v50, s[6:7]
	v_mov_b32_dpp v12, v34 row_ror:1 row_mask:0xf bank_mask:0xf bound_ctrl:1
	v_mov_b32_dpp v13, v35 row_ror:1 row_mask:0xf bank_mask:0xf bound_ctrl:1
	v_pk_mul_f32 v[8:9], v[80:81], v[8:9] op_sel_hi:[0,1]
	v_mov_b32_e32 v48, v53
	v_pk_fma_f32 v[20:21], v[38:39], v[58:59], v[20:21]
	v_pk_fma_f32 v[16:17], v[38:39], v[50:51], v[16:17]
	v_mov_b32_dpp v38, v34 row_ror:15 row_mask:0xf bank_mask:0xf bound_ctrl:1
	v_mov_b32_dpp v39, v35 row_ror:15 row_mask:0xf bank_mask:0xf bound_ctrl:1
	v_mov_b32_dpp v59, v8 row_ror:15 row_mask:0xf bank_mask:0xf bound_ctrl:1
	v_mov_b32_dpp v60, v9 row_ror:15 row_mask:0xf bank_mask:0xf bound_ctrl:1
	v_pk_fma_f32 v[42:43], v[56:57], v[12:13], v[48:49]
	v_cndmask_b32_e64 v39, v39, v60, s[6:7]
	v_cndmask_b32_e64 v38, v38, v59, s[6:7]
	v_pk_fma_f32 v[34:35], v[46:47], v[34:35], v[42:43]
	v_mov_b32_dpp v52, v8 row_ror:1 row_mask:0xf bank_mask:0xf bound_ctrl:1
	v_pk_fma_f32 v[34:35], v[54:55], v[38:39], v[34:35]
	v_mov_b32_dpp v58, v9 row_ror:1 row_mask:0xf bank_mask:0xf bound_ctrl:1
	v_pk_mul_f32 v[38:39], v[34:35], s[76:77] op_sel_hi:[1,0]
	v_pk_mul_f32 v[4:5], v[84:85], v[4:5] op_sel_hi:[0,1]
	v_exp_f32_e32 v38, v38
	v_exp_f32_e32 v39, v39
	v_pk_mul_f32 v[28:29], v[28:29], v[34:35]
	v_cndmask_b32_e64 v13, v58, v13, s[4:5]
	v_cndmask_b32_e64 v12, v52, v12, s[4:5]
	v_pk_add_f32 v[38:39], v[38:39], 1.0 op_sel_hi:[1,0]
;     __device__ __forceinline__ void operator()(const f32x4 (&acc)[2][2][4][2], const Unit& u, int wr, int wc, int fr, int fq) const {
;     ...
;                     const f32x4 c0a = ct[cidx], c0b = ct[cidx + 1], c1a = ct[cidx + 2], c1b = ct[cidx + 3];
;                     const f32x2 wv0 = {c0a[0], c1a[0]}, wv1 = {c0a[1], c1a[1]}, wv2 = {c0a[2], c1a[2]}, bv = {c0a[3], c1a[3]};
;                     const f32x2 wg0 = {c0b[0], c1b[0]}, wg1 = {c0b[1], c1b[1]}, wg2 = {c0b[2], c1b[2]}, bg = {c0b[3], c1b[3]};
;                     f32x2 uv[4], ug[4], cv[4];
; #pragma unroll
;                     for (int m = 0; m < 4; ++m) { uv[m] = (f32x2){acc[ai][0][m][n][2 * jp], acc[ai][0][m][n][2 * jp + 1]}; ug[m] = (f32x2){acc[ai][1][m][n][2 * jp], acc[ai][1][m][n][2 * jp + 1]}; }
;                     asm volatile("" : "+v"(uv[0]), "+v"(uv[1]), "+v"(uv[2]), "+v"(uv[3]), "+v"(ug[0]), "+v"(ug[1]), "+v"(ug[2]), "+v"(ug[3]));
;                     {
;                         f32x2 rv[4], lv[4];
; #pragma unroll
;                         for (int m = 0; m < 4; ++m) { uv[m] = uv[m] * rs[m]; rv[m] = (f32x2){dpp_ror1(uv[m][0]), dpp_ror1(uv[m][1])}; lv[m] = (f32x2){dpp_ror15(uv[m][0]), dpp_ror15(uv[m][1])}; }
; #pragma unroll
;                         for (int m = 0; m < 4; ++m) { const f32x2 pv_ = (m > 0 && f0) ? rv[m > 0 ? m - 1 : 0] : rv[m], nv_ = (m < 3 && f15) ? lv[m < 3 ? m + 1 : 3] : lv[m];
;                             cv[m] = bv + wv0 * pv_ + wv1 * uv[m] + wv2 * nv_; }
;                     }
;                     asm volatile("" : "+v"(cv[0]), "+v"(cv[1]), "+v"(cv[2]), "+v"(cv[3]));
;                     {
;                         f32x2 rg[4], lg[4];
; #pragma unroll
;                         for (int m = 0; m < 4; ++m) { ug[m] = ug[m] * rs[m]; rg[m] = (f32x2){dpp_ror1(ug[m][0]), dpp_ror1(ug[m][1])}; lg[m] = (f32x2){dpp_ror15(ug[m][0]), dpp_ror15(ug[m][1])}; }
; #pragma unroll
;                         for (int m = 0; m < 4; ++m) { const f32x2 pg_ = (m > 0 && f0) ? rg[m > 0 ? m - 1 : 0] : rg[m], ng_ = (m < 3 && f15) ? lg[m < 3 ? m + 1 : 3] : lg[m];
;                             const f32x2 cgt = bg + wg0 * pg_ + wg1 * ug[m] + wg2 * ng_;
;                             const f32x2 e = cgt * (-LOG2E);
;                             const f32x2 d = (f32x2){__builtin_amdgcn_exp2f(e[0]), __builtin_amdgcn_exp2f(e[1])} + 1.f;
	v_mov_b32_dpp v63, v4 row_ror:15 row_mask:0xf bank_mask:0xf bound_ctrl:1
	v_rcp_f32_e32 v38, v38
	v_rcp_f32_e32 v39, v39
	v_mov_b32_dpp v64, v5 row_ror:15 row_mask:0xf bank_mask:0xf bound_ctrl:1
	v_pk_fma_f32 v[12:13], v[56:57], v[12:13], v[48:49]
	v_mov_b32_dpp v61, v4 row_ror:1 row_mask:0xf bank_mask:0xf bound_ctrl:1
	v_pk_mul_f32 v[28:29], v[28:29], v[38:39]
	v_pk_fma_f32 v[8:9], v[46:47], v[8:9], v[12:13]
	v_cvt_pk_bf16_f32 v34, v28, v29
	v_cndmask_b32_e64 v29, v60, v64, s[6:7]
	v_cndmask_b32_e64 v28, v59, v63, s[6:7]
	v_pk_fma_f32 v[8:9], v[54:55], v[28:29], v[8:9]
	v_mov_b32_dpp v62, v5 row_ror:1 row_mask:0xf bank_mask:0xf bound_ctrl:1
	v_pk_mul_f32 v[12:13], v[8:9], s[76:77] op_sel_hi:[1,0]
	v_pk_mul_f32 v[8:9], v[24:25], v[8:9]
	v_exp_f32_e32 v12, v12
	v_exp_f32_e32 v13, v13
	v_pk_mul_f32 v[0:1], v[86:87], v[0:1] op_sel_hi:[0,1]
	v_pk_add_f32 v[12:13], v[12:13], 1.0 op_sel_hi:[1,0]
	s_nop 0
	v_rcp_f32_e32 v12, v12
	v_rcp_f32_e32 v13, v13
	v_mov_b32_dpp v50, v0 row_ror:15 row_mask:0xf bank_mask:0xf bound_ctrl:1
	v_mov_b32_dpp v51, v1 row_ror:15 row_mask:0xf bank_mask:0xf bound_ctrl:1
	v_mov_b32_dpp v65, v0 row_ror:1 row_mask:0xf bank_mask:0xf bound_ctrl:1
	v_pk_mul_f32 v[8:9], v[8:9], v[12:13]
	v_cndmask_b32_e64 v13, v64, v51, s[6:7]
	v_cvt_pk_bf16_f32 v38, v8, v9
	v_cndmask_b32_e64 v9, v62, v58, s[4:5]
	v_cndmask_b32_e64 v8, v61, v52, s[4:5]
	v_pk_fma_f32 v[8:9], v[56:57], v[8:9], v[48:49]
	v_cndmask_b32_e64 v12, v63, v50, s[6:7]
	v_pk_fma_f32 v[4:5], v[46:47], v[4:5], v[8:9]
	v_mov_b32_dpp v66, v1 row_ror:1 row_mask:0xf bank_mask:0xf bound_ctrl:1
	v_pk_fma_f32 v[4:5], v[54:55], v[12:13], v[4:5]
	s_nop 0
	v_pk_mul_f32 v[8:9], v[4:5], s[76:77] op_sel_hi:[1,0]
	v_pk_mul_f32 v[4:5], v[20:21], v[4:5]
	v_exp_f32_e32 v8, v8
	v_exp_f32_e32 v9, v9
	s_nop 0
	v_pk_add_f32 v[8:9], v[8:9], 1.0 op_sel_hi:[1,0]
	s_nop 0
	v_rcp_f32_e32 v8, v8
	v_rcp_f32_e32 v9, v9
	s_nop 0
	v_pk_mul_f32 v[4:5], v[4:5], v[8:9]
	s_nop 0
	v_cvt_pk_bf16_f32 v42, v4, v5
	v_cndmask_b32_e64 v5, v66, v62, s[4:5]
	v_cndmask_b32_e64 v4, v65, v61, s[4:5]
	v_pk_fma_f32 v[4:5], v[56:57], v[4:5], v[48:49]
	s_nop 0
	v_pk_fma_f32 v[0:1], v[46:47], v[0:1], v[4:5]
	s_nop 0
	v_pk_fma_f32 v[0:1], v[54:55], v[50:51], v[0:1]
	s_nop 0
	v_pk_mul_f32 v[4:5], v[0:1], s[76:77] op_sel_hi:[1,0]
	v_pk_mul_f32 v[0:1], v[16:17], v[0:1]
	v_exp_f32_e32 v4, v4
	v_exp_f32_e32 v5, v5
	s_nop 0
	v_pk_add_f32 v[4:5], v[4:5], 1.0 op_sel_hi:[1,0]
	s_nop 0
	v_rcp_f32_e32 v4, v4
	v_rcp_f32_e32 v5, v5
	s_nop 0
	v_pk_mul_f32 v[0:1], v[0:1], v[4:5]
	s_nop 0
	v_cvt_pk_bf16_f32 v46, v0, v1
	global_load_dwordx4 v[52:55], v[170:171], off offset:192
	global_load_dwordx4 v[56:59], v[170:171], off offset:224
	global_load_dwordx4 v[60:63], v[170:171], off offset:208
	global_load_dwordx4 v[48:51], v[170:171], off offset:240
	s_waitcnt vmcnt(3)
	v_mov_b32_e32 v70, v54
	v_pk_mul_f32 v[14:15], v[82:83], v[14:15] op_sel_hi:[0,1]
	v_pk_mul_f32 v[10:11], v[80:81], v[10:11] op_sel_hi:[0,1]
	s_waitcnt vmcnt(1)
	v_mov_b32_e32 v72, v60
	v_mov_b32_dpp v20, v14 row_ror:1 row_mask:0xf bank_mask:0xf bound_ctrl:1
	v_mov_b32_dpp v21, v15 row_ror:1 row_mask:0xf bank_mask:0xf bound_ctrl:1
	s_waitcnt vmcnt(0)
;     __device__ __forceinline__ void operator()(const f32x4 (&acc)[2][2][4][2], const Unit& u, int wr, int wc, int fr, int fq) const {
;     ...
;                     const f32x4 c0a = ct[cidx], c0b = ct[cidx + 1], c1a = ct[cidx + 2], c1b = ct[cidx + 3];
;                     const f32x2 wv0 = {c0a[0], c1a[0]}, wv1 = {c0a[1], c1a[1]}, wv2 = {c0a[2], c1a[2]}, bv = {c0a[3], c1a[3]};
;                     const f32x2 wg0 = {c0b[0], c1b[0]}, wg1 = {c0b[1], c1b[1]}, wg2 = {c0b[2], c1b[2]}, bg = {c0b[3], c1b[3]};
;                     f32x2 uv[4], ug[4], cv[4];
; #pragma unroll
;                     for (int m = 0; m < 4; ++m) { uv[m] = (f32x2){acc[ai][0][m][n][2 * jp], acc[ai][0][m][n][2 * jp + 1]}; ug[m] = (f32x2){acc[ai][1][m][n][2 * jp], acc[ai][1][m][n][2 * jp + 1]}; }
;                     asm volatile("" : "+v"(uv[0]), "+v"(uv[1]), "+v"(uv[2]), "+v"(uv[3]), "+v"(ug[0]), "+v"(ug[1]), "+v"(ug[2]), "+v"(ug[3]));
;                     {
;                         f32x2 rv[4], lv[4];
; #pragma unroll
;                         for (int m = 0; m < 4; ++m) { uv[m] = uv[m] * rs[m]; rv[m] = (f32x2){dpp_ror1(uv[m][0]), dpp_ror1(uv[m][1])}; lv[m] = (f32x2){dpp_ror15(uv[m][0]), dpp_ror15(uv[m][1])}; }
; #pragma unroll
;                         for (int m = 0; m < 4; ++m) { const f32x2 pv_ = (m > 0 && f0) ? rv[m > 0 ? m - 1 : 0] : rv[m], nv_ = (m < 3 && f15) ? lv[m < 3 ? m + 1 : 3] : lv[m];
;                             cv[m] = bv + wv0 * pv_ + wv1 * uv[m] + wv2 * nv_; }
;                     }
;                     asm volatile("" : "+v"(cv[0]), "+v"(cv[1]), "+v"(cv[2]), "+v"(cv[3]));
;                     {
;                         f32x2 rg[4], lg[4];
; #pragma unroll
;                         for (int m = 0; m < 4; ++m) { ug[m] = ug[m] * rs[m]; rg[m] = (f32x2){dpp_ror1(ug[m][0]), dpp_ror1(ug[m][1])}; lg[m] = (f32x2){dpp_ror15(ug[m][0]), dpp_ror15(ug[m][1])}; }
; #pragma unroll
;                         for (int m = 0; m < 4; ++m) { const f32x2 pg_ = (m > 0 && f0) ? rg[m > 0 ? m - 1 : 0] : rg[m], ng_ = (m < 3 && f15) ? lg[m < 3 ? m + 1 : 3] : lg[m];
;                             const f32x2 cgt = bg + wg0 * pg_ + wg1 * ug[m] + wg2 * ng_;
;                             const f32x2 e = cgt * (-LOG2E);
;                             const f32x2 d = (f32x2){__builtin_amdgcn_exp2f(e[0]), __builtin_amdgcn_exp2f(e[1])} + 1.f;
	v_mov_b32_e32 v73, v48
	v_mov_b32_e32 v75, v50
	v_mov_b32_e32 v50, v63
	v_pk_mul_f32 v[0:1], v[82:83], v[30:31] op_sel_hi:[0,1]
	v_pk_mul_f32 v[4:5], v[80:81], v[26:27] op_sel_hi:[0,1]
	v_mov_b32_dpp v66, v14 row_ror:15 row_mask:0xf bank_mask:0xf bound_ctrl:1
	v_mov_b32_dpp v67, v15 row_ror:15 row_mask:0xf bank_mask:0xf bound_ctrl:1
	v_mov_b32_dpp v78, v10 row_ror:15 row_mask:0xf bank_mask:0xf bound_ctrl:1
	v_mov_b32_dpp v79, v11 row_ror:15 row_mask:0xf bank_mask:0xf bound_ctrl:1
	v_mov_b32_e32 v71, v58
	v_mov_b32_e32 v48, v61
	v_mov_b32_e32 v58, v55
	v_pk_fma_f32 v[54:55], v[72:73], v[20:21], v[50:51]
	v_mov_b32_dpp v16, v0 row_ror:1 row_mask:0xf bank_mask:0xf bound_ctrl:1
	v_mov_b32_dpp v17, v1 row_ror:1 row_mask:0xf bank_mask:0xf bound_ctrl:1
	v_mov_b32_dpp v28, v4 row_ror:1 row_mask:0xf bank_mask:0xf bound_ctrl:1
	v_mov_b32_dpp v29, v5 row_ror:1 row_mask:0xf bank_mask:0xf bound_ctrl:1
	v_cndmask_b32_e64 v67, v67, v79, s[6:7]
	v_cndmask_b32_e64 v66, v66, v78, s[6:7]
	v_mov_b32_e32 v68, v52
	v_mov_b32_e32 v69, v56
	v_mov_b32_e32 v74, v62
	v_pk_fma_f32 v[14:15], v[48:49], v[14:15], v[54:55]
	v_cndmask_b32_e64 v25, v29, v17, s[4:5]
	v_cndmask_b32_e64 v24, v28, v16, s[4:5]
	v_mov_b32_e32 v56, v53
	v_pk_fma_f32 v[16:17], v[68:69], v[16:17], v[58:59]
	v_pk_fma_f32 v[14:15], v[74:75], v[66:67], v[14:15]
	v_pk_mul_f32 v[8:9], v[84:85], v[22:23] op_sel_hi:[0,1]
	v_mov_b32_dpp v22, v0 row_ror:15 row_mask:0xf bank_mask:0xf bound_ctrl:1
	v_mov_b32_dpp v23, v1 row_ror:15 row_mask:0xf bank_mask:0xf bound_ctrl:1
	v_pk_fma_f32 v[0:1], v[56:57], v[0:1], v[16:17]
	v_pk_mul_f32 v[16:17], v[14:15], s[76:77] op_sel_hi:[1,0]
	v_mov_b32_dpp v76, v10 row_ror:1 row_mask:0xf bank_mask:0xf bound_ctrl:1
	v_mov_b32_dpp v77, v11 row_ror:1 row_mask:0xf bank_mask:0xf bound_ctrl:1
	v_exp_f32_e32 v16, v16
	v_exp_f32_e32 v17, v17
	v_pk_mul_f32 v[12:13], v[86:87], v[18:19] op_sel_hi:[0,1]
	v_pk_mul_f32 v[6:7], v[84:85], v[6:7] op_sel_hi:[0,1]
	v_mov_b32_dpp v26, v4 row_ror:15 row_mask:0xf bank_mask:0xf bound_ctrl:1
	v_mov_b32_dpp v27, v5 row_ror:15 row_mask:0xf bank_mask:0xf bound_ctrl:1
	v_cndmask_b32_e64 v21, v77, v21, s[4:5]
	v_cndmask_b32_e64 v20, v76, v20, s[4:5]
	v_mov_b32_dpp v35, v8 row_ror:1 row_mask:0xf bank_mask:0xf bound_ctrl:1
	v_mov_b32_dpp v39, v9 row_ror:1 row_mask:0xf bank_mask:0xf bound_ctrl:1
	v_mov_b32_dpp v43, v12 row_ror:1 row_mask:0xf bank_mask:0xf bound_ctrl:1
	v_mov_b32_dpp v47, v13 row_ror:1 row_mask:0xf bank_mask:0xf bound_ctrl:1
	v_mov_b32_dpp v83, v6 row_ror:15 row_mask:0xf bank_mask:0xf bound_ctrl:1
	v_mov_b32_dpp v84, v7 row_ror:15 row_mask:0xf bank_mask:0xf bound_ctrl:1
	v_cndmask_b32_e64 v23, v23, v27, s[6:7]
	v_cndmask_b32_e64 v22, v22, v26, s[6:7]
	v_pk_fma_f32 v[20:21], v[72:73], v[20:21], v[50:51]
	v_cndmask_b32_e64 v29, v39, v29, s[4:5]
	v_cndmask_b32_e64 v28, v35, v28, s[4:5]
	v_cndmask_b32_e64 v65, v47, v39, s[4:5]
	v_cndmask_b32_e64 v64, v43, v35, s[4:5]
	v_pk_fma_f32 v[0:1], v[70:71], v[22:23], v[0:1]
	v_cndmask_b32_e64 v23, v79, v84, s[6:7]
	v_cndmask_b32_e64 v22, v78, v83, s[6:7]
	v_pk_fma_f32 v[10:11], v[48:49], v[10:11], v[20:21]
	v_mov_b32_dpp v30, v8 row_ror:15 row_mask:0xf bank_mask:0xf bound_ctrl:1
	v_mov_b32_dpp v31, v9 row_ror:15 row_mask:0xf bank_mask:0xf bound_ctrl:1
	v_mov_b32_dpp v18, v12 row_ror:15 row_mask:0xf bank_mask:0xf bound_ctrl:1
	v_mov_b32_dpp v19, v13 row_ror:15 row_mask:0xf bank_mask:0xf bound_ctrl:1
	v_pk_fma_f32 v[24:25], v[68:69], v[24:25], v[58:59]
	v_pk_fma_f32 v[28:29], v[68:69], v[28:29], v[58:59]
	v_pk_fma_f32 v[52:53], v[68:69], v[64:65], v[58:59]
	v_pk_add_f32 v[16:17], v[16:17], 1.0 op_sel_hi:[1,0]
	v_pk_fma_f32 v[10:11], v[74:75], v[22:23], v[10:11]
	v_cndmask_b32_e64 v27, v27, v31, s[6:7]
	v_cndmask_b32_e64 v26, v26, v30, s[6:7]
	v_cndmask_b32_e64 v31, v31, v19, s[6:7]
	v_cndmask_b32_e64 v30, v30, v18, s[6:7]
	v_pk_fma_f32 v[4:5], v[56:57], v[4:5], v[24:25]
	v_pk_fma_f32 v[8:9], v[56:57], v[8:9], v[28:29]
	v_pk_fma_f32 v[12:13], v[56:57], v[12:13], v[52:53]
	v_rcp_f32_e32 v16, v16
	v_rcp_f32_e32 v17, v17
	v_pk_mul_f32 v[20:21], v[10:11], s[76:77] op_sel_hi:[1,0]
	v_pk_fma_f32 v[4:5], v[70:71], v[26:27], v[4:5]
	v_pk_fma_f32 v[8:9], v[70:71], v[30:31], v[8:9]
	v_pk_fma_f32 v[12:13], v[70:71], v[18:19], v[12:13]
	v_exp_f32_e32 v20, v20
	v_exp_f32_e32 v21, v21
	v_mov_b32_dpp v80, v6 row_ror:1 row_mask:0xf bank_mask:0xf bound_ctrl:1
	v_pk_mul_f32 v[0:1], v[0:1], v[14:15]
	v_mov_b32_dpp v82, v7 row_ror:1 row_mask:0xf bank_mask:0xf bound_ctrl:1
	v_pk_mul_f32 v[0:1], v[0:1], v[16:17]
	v_pk_mul_f32 v[2:3], v[86:87], v[2:3] op_sel_hi:[0,1]
	v_cvt_pk_bf16_f32 v35, v0, v1
	v_pk_add_f32 v[0:1], v[20:21], 1.0 op_sel_hi:[1,0]
	v_cndmask_b32_e64 v15, v82, v77, s[4:5]
	v_rcp_f32_e32 v0, v0
	v_rcp_f32_e32 v1, v1
	v_cndmask_b32_e64 v14, v80, v76, s[4:5]
	v_mov_b32_dpp v85, v2 row_ror:1 row_mask:0xf bank_mask:0xf bound_ctrl:1
	v_mov_b32_dpp v24, v3 row_ror:1 row_mask:0xf bank_mask:0xf bound_ctrl:1
	v_mov_b32_dpp v18, v2 row_ror:15 row_mask:0xf bank_mask:0xf bound_ctrl:1
	v_mov_b32_dpp v19, v3 row_ror:15 row_mask:0xf bank_mask:0xf bound_ctrl:1
	v_pk_fma_f32 v[14:15], v[72:73], v[14:15], v[50:51]
	v_pk_mul_f32 v[4:5], v[4:5], v[10:11]
	v_cndmask_b32_e64 v17, v84, v19, s[6:7]
	v_cndmask_b32_e64 v16, v83, v18, s[6:7]
	v_pk_fma_f32 v[6:7], v[48:49], v[6:7], v[14:15]
	v_pk_mul_f32 v[0:1], v[4:5], v[0:1]
	v_cndmask_b32_e64 v5, v24, v82, s[4:5]
	v_cndmask_b32_e64 v4, v85, v80, s[4:5]
	v_pk_fma_f32 v[6:7], v[74:75], v[16:17], v[6:7]
	v_pk_fma_f32 v[4:5], v[72:73], v[4:5], v[50:51]
	v_pk_mul_f32 v[14:15], v[6:7], s[76:77] op_sel_hi:[1,0]
	v_pk_fma_f32 v[2:3], v[48:49], v[2:3], v[4:5]
	v_exp_f32_e32 v14, v14
	v_exp_f32_e32 v15, v15
	v_pk_fma_f32 v[2:3], v[74:75], v[18:19], v[2:3]
	v_cvt_pk_bf16_f32 v39, v0, v1
	v_pk_mul_f32 v[4:5], v[2:3], s[76:77] op_sel_hi:[1,0]
	v_pk_add_f32 v[0:1], v[14:15], 1.0 op_sel_hi:[1,0]
	v_exp_f32_e32 v4, v4
	v_exp_f32_e32 v5, v5
	v_rcp_f32_e32 v0, v0
	v_rcp_f32_e32 v1, v1
	v_pk_mul_f32 v[6:7], v[8:9], v[6:7]
	v_pk_add_f32 v[4:5], v[4:5], 1.0 op_sel_hi:[1,0]
	v_pk_mul_f32 v[0:1], v[6:7], v[0:1]
	v_rcp_f32_e32 v4, v4
	v_rcp_f32_e32 v5, v5
	v_cvt_pk_bf16_f32 v43, v0, v1
	v_pk_mul_f32 v[0:1], v[12:13], v[2:3]
	s_nop 0
	v_pk_mul_f32 v[0:1], v[0:1], v[4:5]
	s_nop 0
	v_cvt_pk_bf16_f32 v47, v0, v1
	v_cmp_gt_i32_e32 vcc, s51, v81
	s_and_b64 s[14:15], s[8:9], vcc
	s_and_saveexec_b64 s[2:3], s[14:15]
	s_cbranch_execz .LBB0_804
	v_add_u32_e32 v2, s29, v81
	v_mov_b64_e32 v[0:1], s[24:25]
	v_mad_i64_i32 v[0:1], s[14:15], v2, s73, v[0:1]
	v_lshl_add_u64 v[0:1], s[36:37], 1, v[0:1]
	s_lshl_b32 s84, s45, 1
	v_lshl_add_u64 v[0:1], v[0:1], 0, s[84:85]
	v_lshl_add_u64 v[0:1], v[0:1], 0, v[144:145]
	global_store_dwordx4 v[0:1], v[32:35], off

;     __device__ __forceinline__ void operator()(const f32x4 (&acc)[2][2][4][2], const Unit& u, int wr, int wc, int fr, int fq) const {
;     ...
;                     if (PS) ss += (v0[0] * v0[0] + v0[1] * v0[1]) + (v0[2] * v0[2] + v0[3] * v0[3]) + (v1[0] * v1[0] + v1[1] * v1[1]) + (v1[2] * v1[2] + v1[3] * v1[3]); }
;                 if (PS) { ss = bfly_add<16>(ss); ss = bfly_add<32>(ss); if (fq == 0) PS[(size_t)row * 16 + 4 * u.pn + wc] = ss; }
.LBB0_888:
	v_readlane_b32 s28, v254, 53
	v_readlane_b32 s29, v254, 54
	s_lshl_b32 s26, s44, 2
	s_andn2_b64 vcc, exec, s[28:29]
	v_cndmask_b32_e64 v142, 0, 1, s[28:29]
	v_cmp_ne_u32_e64 s[8:9], 1, v142
	s_ashr_i32 s27, s26, 31
	s_cbranch_vccnz .LBB0_892
	v_mul_f32_e32 v125, v125, v125
	v_mul_f32_e32 v117, v117, v117
	v_fmac_f32_e32 v125, v124, v124
	v_mul_f32_e32 v124, v127, v127
	v_fmac_f32_e32 v117, v116, v116
	v_mul_f32_e32 v116, v119, v119
	v_fmac_f32_e32 v124, v126, v126
	v_mul_f32_e32 v121, v121, v121
	v_fmac_f32_e32 v116, v118, v118
	v_mul_f32_e32 v113, v113, v113
	v_add_f32_e32 v124, v125, v124
	v_fmac_f32_e32 v121, v120, v120
	v_add_f32_e32 v116, v117, v116
	v_fmac_f32_e32 v113, v112, v112
	v_add_f32_e32 v120, v121, v124
	v_mul_f32_e32 v121, v123, v123
	v_add_f32_e32 v112, v113, v116
	v_mul_f32_e32 v113, v115, v115
	v_fmac_f32_e32 v121, v122, v122
	v_fmac_f32_e32 v113, v114, v114
	v_add_f32_e32 v120, v121, v120
	v_add_f32_e32 v112, v113, v112
	v_add_f32_e32 v112, v120, v112
	v_mov_b32_e32 v113, v112
	s_nop 1
	v_permlane16_swap_b32_e32 v112, v113
	s_waitcnt lgkmcnt(0)
	v_add_f32_e32 v112, v112, v113
	v_mov_b32_e32 v113, v112
	s_nop 1
	v_permlane32_swap_b32_e32 v112, v113
	s_and_saveexec_b64 s[28:29], s[10:11]
	s_cbranch_execz .LBB0_891
	v_lshlrev_b64 v[114:115], 6, v[140:141]
	v_lshl_add_u64 v[114:115], s[14:15], 0, v[114:115]
	v_lshl_add_u64 v[114:115], s[26:27], 2, v[114:115]
	s_lshl_b32 s84, s39, 2
	v_lshl_add_u64 v[114:115], v[114:115], 0, s[84:85]
	v_add_f32_e32 v112, v112, v113
	global_store_dword v[114:115], v112, off

;     __device__ __forceinline__ void operator()(const f32x4 (&acc)[2][2][4][2], const Unit& u, int wr, int wc, int fr, int fq) const {
;     ...
;                     if (PS) ss += (v0[0] * v0[0] + v0[1] * v0[1]) + (v0[2] * v0[2] + v0[3] * v0[3]) + (v1[0] * v1[0] + v1[1] * v1[1]) + (v1[2] * v1[2] + v1[3] * v1[3]); }
;                 if (PS) { ss = bfly_add<16>(ss); ss = bfly_add<32>(ss); if (fq == 0) PS[(size_t)row * 16 + 4 * u.pn + wc] = ss; }
.LBB0_898:
	s_and_b64 vcc, exec, s[8:9]
	s_cbranch_vccnz .LBB0_902
	v_mul_f32_e32 v109, v109, v109
	v_mul_f32_e32 v101, v101, v101
	v_fmac_f32_e32 v109, v108, v108
	v_mul_f32_e32 v108, v111, v111
	v_fmac_f32_e32 v101, v100, v100
	v_mul_f32_e32 v100, v103, v103
	v_fmac_f32_e32 v108, v110, v110
	v_mul_f32_e32 v105, v105, v105
	v_fmac_f32_e32 v100, v102, v102
	v_mul_f32_e32 v97, v97, v97
	v_add_f32_e32 v108, v109, v108
	v_fmac_f32_e32 v105, v104, v104
	v_add_f32_e32 v100, v101, v100
	v_fmac_f32_e32 v97, v96, v96
	v_add_f32_e32 v104, v105, v108
	v_mul_f32_e32 v105, v107, v107
	v_add_f32_e32 v96, v97, v100
	v_mul_f32_e32 v97, v99, v99
	v_fmac_f32_e32 v105, v106, v106
	v_fmac_f32_e32 v97, v98, v98
	v_add_f32_e32 v104, v105, v104
	v_add_f32_e32 v96, v97, v96
	v_add_f32_e32 v96, v104, v96
	v_mov_b32_e32 v97, v96
	s_nop 1
	v_permlane16_swap_b32_e32 v96, v97
	s_waitcnt lgkmcnt(0)
	v_add_f32_e32 v96, v96, v97
	v_mov_b32_e32 v97, v96
	s_nop 1
	v_permlane32_swap_b32_e32 v96, v97
	s_and_saveexec_b64 s[28:29], s[10:11]
	s_cbranch_execz .LBB0_901
	v_lshlrev_b64 v[98:99], 6, v[112:113]
	v_lshl_add_u64 v[98:99], s[14:15], 0, v[98:99]
	v_lshl_add_u64 v[98:99], s[26:27], 2, v[98:99]
	s_lshl_b32 s84, s39, 2
	v_lshl_add_u64 v[98:99], v[98:99], 0, s[84:85]
	v_add_f32_e32 v96, v96, v97
	global_store_dword v[98:99], v96, off

;     __device__ __forceinline__ void operator()(const f32x4 (&acc)[2][2][4][2], const Unit& u, int wr, int wc, int fr, int fq) const {
;     ...
;                     if (PS) ss += (v0[0] * v0[0] + v0[1] * v0[1]) + (v0[2] * v0[2] + v0[3] * v0[3]) + (v1[0] * v1[0] + v1[1] * v1[1]) + (v1[2] * v1[2] + v1[3] * v1[3]); }
;                 if (PS) { ss = bfly_add<16>(ss); ss = bfly_add<32>(ss); if (fq == 0) PS[(size_t)row * 16 + 4 * u.pn + wc] = ss; }
.LBB0_908:
	s_and_b64 vcc, exec, s[8:9]
	s_cbranch_vccnz .LBB0_912
	v_mul_f32_e32 v93, v93, v93
	v_mul_f32_e32 v85, v85, v85
	v_fmac_f32_e32 v93, v92, v92
	v_mul_f32_e32 v92, v95, v95
	v_fmac_f32_e32 v85, v84, v84
	v_mul_f32_e32 v84, v87, v87
	v_fmac_f32_e32 v92, v94, v94
	v_mul_f32_e32 v89, v89, v89
	v_fmac_f32_e32 v84, v86, v86
	v_mul_f32_e32 v81, v81, v81
	v_add_f32_e32 v92, v93, v92
	v_fmac_f32_e32 v89, v88, v88
	v_add_f32_e32 v84, v85, v84
	v_fmac_f32_e32 v81, v80, v80
	v_add_f32_e32 v88, v89, v92
	v_mul_f32_e32 v89, v91, v91
	v_add_f32_e32 v80, v81, v84
	v_mul_f32_e32 v81, v83, v83
	v_fmac_f32_e32 v89, v90, v90
	v_fmac_f32_e32 v81, v82, v82
	v_add_f32_e32 v88, v89, v88
	v_add_f32_e32 v80, v81, v80
	v_add_f32_e32 v80, v88, v80
	v_mov_b32_e32 v81, v80
	s_nop 1
	v_permlane16_swap_b32_e32 v80, v81
	s_waitcnt lgkmcnt(0)
	v_add_f32_e32 v80, v80, v81
	v_mov_b32_e32 v81, v80
	s_nop 1
	v_permlane32_swap_b32_e32 v80, v81
	s_and_saveexec_b64 s[28:29], s[10:11]
	s_cbranch_execz .LBB0_911
	v_lshlrev_b64 v[82:83], 6, v[96:97]
	v_lshl_add_u64 v[82:83], s[14:15], 0, v[82:83]
	v_lshl_add_u64 v[82:83], s[26:27], 2, v[82:83]
	s_lshl_b32 s84, s39, 2
	v_lshl_add_u64 v[82:83], v[82:83], 0, s[84:85]
	v_add_f32_e32 v80, v80, v81
	global_store_dword v[82:83], v80, off

;     __device__ __forceinline__ void operator()(const f32x4 (&acc)[2][2][4][2], const Unit& u, int wr, int wc, int fr, int fq) const {
;     ...
;                     if (PS) ss += (v0[0] * v0[0] + v0[1] * v0[1]) + (v0[2] * v0[2] + v0[3] * v0[3]) + (v1[0] * v1[0] + v1[1] * v1[1]) + (v1[2] * v1[2] + v1[3] * v1[3]); }
;                 if (PS) { ss = bfly_add<16>(ss); ss = bfly_add<32>(ss); if (fq == 0) PS[(size_t)row * 16 + 4 * u.pn + wc] = ss; }
.LBB0_918:
	s_and_b64 vcc, exec, s[8:9]
	s_cbranch_vccnz .LBB0_922
	v_mul_f32_e32 v77, v77, v77
	v_mul_f32_e32 v69, v69, v69
	v_fmac_f32_e32 v77, v76, v76
	v_mul_f32_e32 v76, v79, v79
	v_fmac_f32_e32 v69, v68, v68
	v_mul_f32_e32 v68, v71, v71
	v_fmac_f32_e32 v76, v78, v78
	v_mul_f32_e32 v73, v73, v73
	v_fmac_f32_e32 v68, v70, v70
	v_mul_f32_e32 v65, v65, v65
	v_add_f32_e32 v76, v77, v76
	v_fmac_f32_e32 v73, v72, v72
	v_add_f32_e32 v68, v69, v68
	v_fmac_f32_e32 v65, v64, v64
	v_add_f32_e32 v72, v73, v76
	v_mul_f32_e32 v73, v75, v75
	v_add_f32_e32 v64, v65, v68
	v_mul_f32_e32 v65, v67, v67
	v_fmac_f32_e32 v73, v74, v74
	v_fmac_f32_e32 v65, v66, v66
	v_add_f32_e32 v72, v73, v72
	v_add_f32_e32 v64, v65, v64
	v_add_f32_e32 v64, v72, v64
	v_mov_b32_e32 v65, v64
	s_nop 1
	v_permlane16_swap_b32_e32 v64, v65
	s_waitcnt lgkmcnt(0)
	v_add_f32_e32 v64, v64, v65
	v_mov_b32_e32 v65, v64
	s_nop 1
	v_permlane32_swap_b32_e32 v64, v65
	s_and_saveexec_b64 s[28:29], s[10:11]
	s_cbranch_execz .LBB0_921
	v_lshlrev_b64 v[66:67], 6, v[80:81]
	v_lshl_add_u64 v[66:67], s[14:15], 0, v[66:67]
	v_lshl_add_u64 v[66:67], s[26:27], 2, v[66:67]
	s_lshl_b32 s84, s39, 2
	v_lshl_add_u64 v[66:67], v[66:67], 0, s[84:85]
	v_add_f32_e32 v64, v64, v65
	global_store_dword v[66:67], v64, off

;     __device__ __forceinline__ void operator()(const f32x4 (&acc)[2][2][4][2], const Unit& u, int wr, int wc, int fr, int fq) const {
;     ...
;                     if (PS) ss += (v0[0] * v0[0] + v0[1] * v0[1]) + (v0[2] * v0[2] + v0[3] * v0[3]) + (v1[0] * v1[0] + v1[1] * v1[1]) + (v1[2] * v1[2] + v1[3] * v1[3]); }
;                 if (PS) { ss = bfly_add<16>(ss); ss = bfly_add<32>(ss); if (fq == 0) PS[(size_t)row * 16 + 4 * u.pn + wc] = ss; }
.LBB0_928:
	s_and_b64 vcc, exec, s[8:9]
	s_cbranch_vccnz .LBB0_932
	v_mul_f32_e32 v61, v61, v61
	v_mul_f32_e32 v53, v53, v53
	v_fmac_f32_e32 v61, v60, v60
	v_mul_f32_e32 v60, v63, v63
	v_fmac_f32_e32 v53, v52, v52
	v_mul_f32_e32 v52, v55, v55
	v_fmac_f32_e32 v60, v62, v62
	v_mul_f32_e32 v57, v57, v57
	v_fmac_f32_e32 v52, v54, v54
	v_mul_f32_e32 v49, v49, v49
	v_add_f32_e32 v60, v61, v60
	v_fmac_f32_e32 v57, v56, v56
	v_add_f32_e32 v52, v53, v52
	v_fmac_f32_e32 v49, v48, v48
	v_add_f32_e32 v56, v57, v60
	v_mul_f32_e32 v57, v59, v59
	v_add_f32_e32 v48, v49, v52
	v_mul_f32_e32 v49, v51, v51
	v_fmac_f32_e32 v57, v58, v58
	v_fmac_f32_e32 v49, v50, v50
	v_add_f32_e32 v56, v57, v56
	v_add_f32_e32 v48, v49, v48
	v_add_f32_e32 v48, v56, v48
	v_mov_b32_e32 v49, v48
	s_nop 1
	v_permlane16_swap_b32_e32 v48, v49
	s_waitcnt lgkmcnt(0)
	v_add_f32_e32 v48, v48, v49
	v_mov_b32_e32 v49, v48
	s_nop 1
	v_permlane32_swap_b32_e32 v48, v49
	s_and_saveexec_b64 s[28:29], s[10:11]
	s_cbranch_execz .LBB0_931
	v_lshlrev_b64 v[50:51], 6, v[64:65]
	v_lshl_add_u64 v[50:51], s[14:15], 0, v[50:51]
	v_lshl_add_u64 v[50:51], s[26:27], 2, v[50:51]
	s_lshl_b32 s84, s39, 2
	v_lshl_add_u64 v[50:51], v[50:51], 0, s[84:85]
	v_add_f32_e32 v48, v48, v49
	global_store_dword v[50:51], v48, off

;     __device__ __forceinline__ void operator()(const f32x4 (&acc)[2][2][4][2], const Unit& u, int wr, int wc, int fr, int fq) const {
;     ...
;                     if (PS) ss += (v0[0] * v0[0] + v0[1] * v0[1]) + (v0[2] * v0[2] + v0[3] * v0[3]) + (v1[0] * v1[0] + v1[1] * v1[1]) + (v1[2] * v1[2] + v1[3] * v1[3]); }
;                 if (PS) { ss = bfly_add<16>(ss); ss = bfly_add<32>(ss); if (fq == 0) PS[(size_t)row * 16 + 4 * u.pn + wc] = ss; }
.LBB0_938:
	s_and_b64 vcc, exec, s[8:9]
	s_cbranch_vccnz .LBB0_942
	v_mul_f32_e32 v45, v45, v45
	v_mul_f32_e32 v37, v37, v37
	v_fmac_f32_e32 v45, v44, v44
	v_mul_f32_e32 v44, v47, v47
	v_fmac_f32_e32 v37, v36, v36
	v_mul_f32_e32 v36, v39, v39
	v_fmac_f32_e32 v44, v46, v46
	v_mul_f32_e32 v41, v41, v41
	v_fmac_f32_e32 v36, v38, v38
	v_mul_f32_e32 v33, v33, v33
	v_add_f32_e32 v44, v45, v44
	v_fmac_f32_e32 v41, v40, v40
	v_add_f32_e32 v36, v37, v36
	v_fmac_f32_e32 v33, v32, v32
	v_add_f32_e32 v40, v41, v44
	v_mul_f32_e32 v41, v43, v43
	v_add_f32_e32 v32, v33, v36
	v_mul_f32_e32 v33, v35, v35
	v_fmac_f32_e32 v41, v42, v42
	v_fmac_f32_e32 v33, v34, v34
	v_add_f32_e32 v40, v41, v40
	v_add_f32_e32 v32, v33, v32
	v_add_f32_e32 v32, v40, v32
	v_mov_b32_e32 v33, v32
	s_nop 1
	v_permlane16_swap_b32_e32 v32, v33
	s_waitcnt lgkmcnt(0)
	v_add_f32_e32 v32, v32, v33
	v_mov_b32_e32 v33, v32
	s_nop 1
	v_permlane32_swap_b32_e32 v32, v33
	s_and_saveexec_b64 s[28:29], s[10:11]
	s_cbranch_execz .LBB0_941
	v_lshlrev_b64 v[34:35], 6, v[48:49]
	v_lshl_add_u64 v[34:35], s[14:15], 0, v[34:35]
	v_lshl_add_u64 v[34:35], s[26:27], 2, v[34:35]
	s_lshl_b32 s84, s39, 2
	v_lshl_add_u64 v[34:35], v[34:35], 0, s[84:85]
	v_add_f32_e32 v32, v32, v33
	global_store_dword v[34:35], v32, off

;     __device__ __forceinline__ void operator()(const f32x4 (&acc)[2][2][4][2], const Unit& u, int wr, int wc, int fr, int fq) const {
;     ...
;                     if (PS) ss += (v0[0] * v0[0] + v0[1] * v0[1]) + (v0[2] * v0[2] + v0[3] * v0[3]) + (v1[0] * v1[0] + v1[1] * v1[1]) + (v1[2] * v1[2] + v1[3] * v1[3]); }
;                 if (PS) { ss = bfly_add<16>(ss); ss = bfly_add<32>(ss); if (fq == 0) PS[(size_t)row * 16 + 4 * u.pn + wc] = ss; }
.LBB0_948:
	s_and_b64 vcc, exec, s[8:9]
	s_cbranch_vccnz .LBB0_952
	v_mul_f32_e32 v29, v29, v29
	v_mul_f32_e32 v21, v21, v21
	v_fmac_f32_e32 v29, v28, v28
	v_mul_f32_e32 v28, v31, v31
	v_fmac_f32_e32 v21, v20, v20
	v_mul_f32_e32 v20, v23, v23
	v_fmac_f32_e32 v28, v30, v30
	v_mul_f32_e32 v25, v25, v25
	v_fmac_f32_e32 v20, v22, v22
	v_mul_f32_e32 v17, v17, v17
	v_add_f32_e32 v28, v29, v28
	v_fmac_f32_e32 v25, v24, v24
	v_add_f32_e32 v20, v21, v20
	v_fmac_f32_e32 v17, v16, v16
	v_add_f32_e32 v24, v25, v28
	v_mul_f32_e32 v25, v27, v27
	v_add_f32_e32 v16, v17, v20
	v_mul_f32_e32 v17, v19, v19
	v_fmac_f32_e32 v25, v26, v26
	v_fmac_f32_e32 v17, v18, v18
	v_add_f32_e32 v24, v25, v24
	v_add_f32_e32 v16, v17, v16
	v_add_f32_e32 v16, v24, v16
	v_mov_b32_e32 v17, v16
	s_nop 1
	v_permlane16_swap_b32_e32 v16, v17
	s_waitcnt lgkmcnt(0)
	v_add_f32_e32 v16, v16, v17
	v_mov_b32_e32 v17, v16
	s_nop 1
	v_permlane32_swap_b32_e32 v16, v17
	s_and_saveexec_b64 s[28:29], s[10:11]
	s_cbranch_execz .LBB0_951
	v_lshlrev_b64 v[18:19], 6, v[32:33]
	v_lshl_add_u64 v[18:19], s[14:15], 0, v[18:19]
	v_lshl_add_u64 v[18:19], s[26:27], 2, v[18:19]
	s_lshl_b32 s84, s39, 2
	v_lshl_add_u64 v[18:19], v[18:19], 0, s[84:85]
	v_add_f32_e32 v16, v16, v17
	global_store_dword v[18:19], v16, off

;     __device__ __forceinline__ void operator()(const f32x4 (&acc)[2][2][4][2], const Unit& u, int wr, int wc, int fr, int fq) const {
;     ...
;                     if (PS) ss += (v0[0] * v0[0] + v0[1] * v0[1]) + (v0[2] * v0[2] + v0[3] * v0[3]) + (v1[0] * v1[0] + v1[1] * v1[1]) + (v1[2] * v1[2] + v1[3] * v1[3]); }
;                 if (PS) { ss = bfly_add<16>(ss); ss = bfly_add<32>(ss); if (fq == 0) PS[(size_t)row * 16 + 4 * u.pn + wc] = ss; }
.LBB0_958:
	s_and_b64 vcc, exec, s[8:9]
	s_cbranch_vccnz .LBB0_962
	v_mul_f32_e32 v13, v13, v13
	v_mul_f32_e32 v5, v5, v5
	v_fmac_f32_e32 v13, v12, v12
	v_mul_f32_e32 v12, v15, v15
	v_fmac_f32_e32 v5, v4, v4
	v_mul_f32_e32 v4, v7, v7
	v_fmac_f32_e32 v12, v14, v14
	v_mul_f32_e32 v9, v9, v9
	v_fmac_f32_e32 v4, v6, v6
	v_mul_f32_e32 v1, v1, v1
	v_add_f32_e32 v12, v13, v12
	v_fmac_f32_e32 v9, v8, v8
	v_add_f32_e32 v4, v5, v4
	v_fmac_f32_e32 v1, v0, v0
	v_add_f32_e32 v8, v9, v12
	v_mul_f32_e32 v9, v11, v11
	v_add_f32_e32 v0, v1, v4
	v_mul_f32_e32 v1, v3, v3
	v_fmac_f32_e32 v9, v10, v10
	v_fmac_f32_e32 v1, v2, v2
	v_add_f32_e32 v8, v9, v8
	v_add_f32_e32 v0, v1, v0
	v_add_f32_e32 v0, v8, v0
	v_mov_b32_e32 v1, v0
	s_nop 1
	v_permlane16_swap_b32_e32 v0, v1
	s_waitcnt lgkmcnt(0)
	v_add_f32_e32 v0, v0, v1
	v_mov_b32_e32 v1, v0
	s_nop 1
	v_permlane32_swap_b32_e32 v0, v1
	s_and_saveexec_b64 s[6:7], s[10:11]
	s_cbranch_execz .LBB0_961
	v_lshlrev_b64 v[2:3], 6, v[16:17]
	v_lshl_add_u64 v[2:3], s[14:15], 0, v[2:3]
	v_lshl_add_u64 v[2:3], s[26:27], 2, v[2:3]
	s_lshl_b32 s84, s39, 2
	v_lshl_add_u64 v[2:3], v[2:3], 0, s[84:85]
	v_add_f32_e32 v0, v0, v1
	global_store_dword v[2:3], v0, off
